# merge4_split35
# speedup vs baseline: 1.0094x; 1.0094x over previous
; #define STAGE(P, BASE, br, kt) do { const char* _gb = (const char*)(BASE) + ((size_t)(br) * K + (size_t)(kt) * BK) * 2; \
;     __builtin_amdgcn_global_load_lds((const unsigned*)(_gb + loff0), (unsigned*)((char*)(P) + tid * 16), 16, 0, 0); \
;     __builtin_amdgcn_global_load_lds((const unsigned*)(_gb + (size_t)K * 128 + loff0), (unsigned*)((char*)(P) + tid * 16 + 8192), 16, 0, 0); } while (0)
; #define LDA(dst, b, h) for (int m = 0; m < 4; ++m) { \
;     dst[m][0] = *reinterpret_cast<const bf16x8*>((char*)SA(b, h) + aoff0 + m * 2048); \
;     dst[m][1] = *reinterpret_cast<const bf16x8*>((char*)SA(b, h) + aoff1 + m * 2048); }
; #define LDB(dst, b, h) for (int n = 0; n < 2; ++n) { \
;     dst[n][0] = *reinterpret_cast<const bf16x8*>((char*)SB(b, h) + boff0 + n * 256); \
;     dst[n][1] = *reinterpret_cast<const bf16x8*>((char*)SB(b, h) + boff1 + n * 256); }
; #define MMA(ai, bj, At, Btf) do { __builtin_amdgcn_s_setprio(1); \
;     for (int m = 0; m < 4; ++m) for (int n = 0; n < 2; ++n) for (int k = 0; k < 2; ++k) \
;       acc[ai][bj][m][n] = __builtin_amdgcn_mfma_f32_16x16x32_bf16(Btf[n][k], At[m][k], acc[ai][bj][m][n], 0, 0, 0); \
;     __builtin_amdgcn_s_setprio(0); } while (0)
; #define WAIT_V(n) asm volatile("s_waitcnt vmcnt(" #n ")" ::: "memory")
; #define WAIT_L(n) asm volatile("s_waitcnt lgkmcnt(" #n ")" ::: "memory")
; #define BAR __builtin_amdgcn_s_barrier()
; #define SCHED __builtin_amdgcn_sched_barrier(0)
; template <int EPI> ...
;     ...
;     LDB(B0, 0, 0); SCHED; LDA(At, 0, 0); STAGE(SA(1, 1), A, brow + HALF, t + 1);
;     WAIT_L(8); BAR; WAIT_L(0); MMA(0, 0, At, B0); BAR; SCHED;
;     LDB(B1, 0, 1); STAGE(SB(0, 0), Bt, bcol, t + 2);
;     BAR; WAIT_L(0); MMA(0, 1, At, B1); BAR;
;     LDA(At, 0, 1); STAGE(SA(0, 0), A, brow, t + 2);
;     BAR; WAIT_L(0); MMA(1, 0, At, B0); BAR; SCHED;
;     STAGE(SB(0, 1), Bt, bcol + HALF, t + 2);
;     WAIT_V(6); BAR; MMA(1, 1, At, B1); BAR;
.LBB0_277:
	ds_read_b128 v[162:165], v153
	ds_read_b128 v[166:169], v153 offset:256
	ds_read_b128 v[170:173], v154
	ds_read_b128 v[174:177], v154 offset:256
	v_lshl_add_u64 v[226:227], s[70:71], 0, v[130:131]
	v_readfirstlane_b32 s72, v151
	v_lshl_add_u64 v[210:211], v[226:227], 0, s[18:19]
	s_mov_b32 m0, s72
	v_readfirstlane_b32 s72, v152
	ds_read_b128 v[178:181], v150
	ds_read_b128 v[182:185], v150 offset:1024
	ds_read_b128 v[186:189], v150 offset:2048
	ds_read_b128 v[190:193], v150 offset:3072
	ds_read_b128 v[194:197], v150 offset:4096
	ds_read_b128 v[198:201], v150 offset:5120
	ds_read_b128 v[202:205], v150 offset:6144
	ds_read_b128 v[206:209], v150 offset:7168
	global_load_lds_dwordx4 v[210:211], off
	v_lshl_add_u64 v[210:211], v[226:227], 0, s[20:21]
	s_mov_b32 m0, s72
	s_nop 0
	global_load_lds_dwordx4 v[210:211], off
	s_waitcnt lgkmcnt(8)
	v_readfirstlane_b32 s72, v149
	v_lshl_add_u64 v[246:247], v[228:229], 0, s[60:61]
	s_mov_b32 m0, s72
	s_nop 0
	global_load_lds_dwordx4 v[246:247], off
	ds_read_b128 v[210:213], v155
	ds_read_b128 v[214:217], v155 offset:256
	ds_read_b128 v[218:221], v156
	ds_read_b128 v[222:225], v156 offset:256
	s_barrier
	s_waitcnt lgkmcnt(0)
	s_setprio 1
	s_waitcnt lgkmcnt(0)
	v_mfma_f32_16x16x32_bf16 v[124:127], v[162:165], v[178:181], v[124:127]
	v_mfma_f32_16x16x32_bf16 v[120:123], v[166:169], v[178:181], v[120:123]
	v_mfma_f32_16x16x32_bf16 v[116:119], v[162:165], v[186:189], v[116:119]
	v_mfma_f32_16x16x32_bf16 v[112:115], v[166:169], v[186:189], v[112:115]
	v_mfma_f32_16x16x32_bf16 v[108:111], v[162:165], v[194:197], v[108:111]
	v_mfma_f32_16x16x32_bf16 v[104:107], v[166:169], v[194:197], v[104:107]
	v_mfma_f32_16x16x32_bf16 v[100:103], v[162:165], v[202:205], v[100:103]
	v_mfma_f32_16x16x32_bf16 v[96:99], v[166:169], v[202:205], v[96:99]
	v_mfma_f32_16x16x32_bf16 v[124:127], v[170:173], v[182:185], v[124:127]
	v_mfma_f32_16x16x32_bf16 v[120:123], v[174:177], v[182:185], v[120:123]
	v_mfma_f32_16x16x32_bf16 v[116:119], v[170:173], v[190:193], v[116:119]
	v_mfma_f32_16x16x32_bf16 v[112:115], v[174:177], v[190:193], v[112:115]
	v_mfma_f32_16x16x32_bf16 v[108:111], v[170:173], v[198:201], v[108:111]
	v_mfma_f32_16x16x32_bf16 v[104:107], v[174:177], v[198:201], v[104:107]
	v_mfma_f32_16x16x32_bf16 v[100:103], v[170:173], v[206:209], v[100:103]
	v_mfma_f32_16x16x32_bf16 v[96:99], v[174:177], v[206:209], v[96:99]
	s_setprio 0
	s_waitcnt lgkmcnt(0)
	s_setprio 1
	s_waitcnt lgkmcnt(0)
	v_mfma_f32_16x16x32_bf16 v[92:95], v[210:213], v[178:181], v[92:95]
	v_mfma_f32_16x16x32_bf16 v[88:91], v[214:217], v[178:181], v[88:91]
	v_mfma_f32_16x16x32_bf16 v[84:87], v[210:213], v[186:189], v[84:87]
	v_mfma_f32_16x16x32_bf16 v[80:83], v[214:217], v[186:189], v[80:83]
	v_mfma_f32_16x16x32_bf16 v[76:79], v[210:213], v[194:197], v[76:79]
	v_mfma_f32_16x16x32_bf16 v[72:75], v[214:217], v[194:197], v[72:75]
	v_mfma_f32_16x16x32_bf16 v[68:71], v[210:213], v[202:205], v[68:71]
	v_mfma_f32_16x16x32_bf16 v[64:67], v[214:217], v[202:205], v[64:67]
	v_mfma_f32_16x16x32_bf16 v[92:95], v[218:221], v[182:185], v[92:95]
	v_mfma_f32_16x16x32_bf16 v[88:91], v[222:225], v[182:185], v[88:91]
	v_mfma_f32_16x16x32_bf16 v[84:87], v[218:221], v[190:193], v[84:87]
	v_mfma_f32_16x16x32_bf16 v[80:83], v[222:225], v[190:193], v[80:83]
	v_mfma_f32_16x16x32_bf16 v[76:79], v[218:221], v[198:201], v[76:79]
	v_mfma_f32_16x16x32_bf16 v[72:75], v[222:225], v[198:201], v[72:75]
	v_mfma_f32_16x16x32_bf16 v[68:71], v[218:221], v[206:209], v[68:71]
	v_mfma_f32_16x16x32_bf16 v[64:67], v[222:225], v[206:209], v[64:67]
	s_setprio 0
	s_barrier
	v_lshl_add_u64 v[228:229], s[68:69], 0, v[130:131]
	v_readfirstlane_b32 s72, v136
	v_lshl_add_u64 v[230:231], v[228:229], 0, s[22:23]
	s_mov_b32 m0, s72
	v_readfirstlane_b32 s72, v137
	global_load_lds_dwordx4 v[230:231], off
	v_lshl_add_u64 v[230:231], v[228:229], 0, s[26:27]
	s_mov_b32 m0, s72
	s_nop 0
	global_load_lds_dwordx4 v[230:231], off
	v_readfirstlane_b32 s72, v138
	v_lshl_add_u64 v[230:231], v[226:227], 0, s[28:29]
	s_mov_b32 m0, s72
	v_readfirstlane_b32 s72, v139
	ds_read_b128 v[178:181], v150 offset:16384
	ds_read_b128 v[182:185], v150 offset:17408
	ds_read_b128 v[186:189], v150 offset:18432
	ds_read_b128 v[190:193], v150 offset:19456
	ds_read_b128 v[194:197], v150 offset:20480
	ds_read_b128 v[198:201], v150 offset:21504
	ds_read_b128 v[202:205], v150 offset:22528
	ds_read_b128 v[206:209], v150 offset:23552
	global_load_lds_dwordx4 v[230:231], off
	v_lshl_add_u64 v[230:231], v[226:227], 0, s[30:31]
	s_mov_b32 m0, s72
	s_nop 0
	global_load_lds_dwordx4 v[230:231], off
	v_readfirstlane_b32 s72, v140
	v_lshl_add_u64 v[246:247], v[228:229], 0, s[36:37]
	s_mov_b32 m0, s72
	v_readfirstlane_b32 s72, v141
	global_load_lds_dwordx4 v[246:247], off
	s_waitcnt vmcnt(5)
	s_barrier
; #define STAGE(P, BASE, br, kt) do { const char* _gb = (const char*)(BASE) + ((size_t)(br) * K + (size_t)(kt) * BK) * 2; \
;     __builtin_amdgcn_global_load_lds((const unsigned*)(_gb + loff0), (unsigned*)((char*)(P) + tid * 16), 16, 0, 0); \
;     __builtin_amdgcn_global_load_lds((const unsigned*)(_gb + (size_t)K * 128 + loff0), (unsigned*)((char*)(P) + tid * 16 + 8192), 16, 0, 0); } while (0)
; #define LDA(dst, b, h) for (int m = 0; m < 4; ++m) { \
;     dst[m][0] = *reinterpret_cast<const bf16x8*>((char*)SA(b, h) + aoff0 + m * 2048); \
;     dst[m][1] = *reinterpret_cast<const bf16x8*>((char*)SA(b, h) + aoff1 + m * 2048); }
; #define LDB(dst, b, h) for (int n = 0; n < 2; ++n) { \
;     dst[n][0] = *reinterpret_cast<const bf16x8*>((char*)SB(b, h) + boff0 + n * 256); \
;     dst[n][1] = *reinterpret_cast<const bf16x8*>((char*)SB(b, h) + boff1 + n * 256); }
; #define MMA(ai, bj, At, Btf) do { __builtin_amdgcn_s_setprio(1); \
;     for (int m = 0; m < 4; ++m) for (int n = 0; n < 2; ++n) for (int k = 0; k < 2; ++k) \
;       acc[ai][bj][m][n] = __builtin_amdgcn_mfma_f32_16x16x32_bf16(Btf[n][k], At[m][k], acc[ai][bj][m][n], 0, 0, 0); \
;     __builtin_amdgcn_s_setprio(0); } while (0)
; #define WAIT_V(n) asm volatile("s_waitcnt vmcnt(" #n ")" ::: "memory")
; #define WAIT_L(n) asm volatile("s_waitcnt lgkmcnt(" #n ")" ::: "memory")
; #define BAR __builtin_amdgcn_s_barrier()
; #define SCHED __builtin_amdgcn_sched_barrier(0)
; template <int EPI> ...
;     ...
;     BAR; WAIT_L(0); MMA(1, 0, At, B0); BAR; SCHED;
;     STAGE(SB(0, 1), Bt, bcol + HALF, t + 2);
;     WAIT_V(6); BAR; MMA(1, 1, At, B1); BAR;
;     LDB(B0, 1, 0); SCHED; LDA(At, 1, 0); STAGE(SA(0, 1), A, brow + HALF, t + 2);
;     WAIT_L(8); BAR; WAIT_L(0); MMA(0, 0, At, B0); BAR; SCHED;
;     LDB(B1, 1, 1); STAGE(SB(1, 0), Bt, bcol, t + 3);
;     BAR; WAIT_L(0); MMA(0, 1, At, B1); BAR;
	s_waitcnt lgkmcnt(0)
	s_setprio 1
	s_waitcnt lgkmcnt(0)
	v_mfma_f32_16x16x32_bf16 v[60:63], v[162:165], v[178:181], v[60:63]
	v_mfma_f32_16x16x32_bf16 v[56:59], v[166:169], v[178:181], v[56:59]
	v_mfma_f32_16x16x32_bf16 v[52:55], v[162:165], v[186:189], v[52:55]
	v_mfma_f32_16x16x32_bf16 v[48:51], v[166:169], v[186:189], v[48:51]
	v_mfma_f32_16x16x32_bf16 v[44:47], v[162:165], v[194:197], v[44:47]
	v_mfma_f32_16x16x32_bf16 v[40:43], v[166:169], v[194:197], v[40:43]
	v_mfma_f32_16x16x32_bf16 v[36:39], v[162:165], v[202:205], v[36:39]
	v_mfma_f32_16x16x32_bf16 v[32:35], v[166:169], v[202:205], v[32:35]
	v_mfma_f32_16x16x32_bf16 v[60:63], v[170:173], v[182:185], v[60:63]
	v_mfma_f32_16x16x32_bf16 v[56:59], v[174:177], v[182:185], v[56:59]
	v_mfma_f32_16x16x32_bf16 v[52:55], v[170:173], v[190:193], v[52:55]
	v_mfma_f32_16x16x32_bf16 v[48:51], v[174:177], v[190:193], v[48:51]
	v_mfma_f32_16x16x32_bf16 v[44:47], v[170:173], v[198:201], v[44:47]
	v_mfma_f32_16x16x32_bf16 v[40:43], v[174:177], v[198:201], v[40:43]
	v_mfma_f32_16x16x32_bf16 v[36:39], v[170:173], v[206:209], v[36:39]
	v_mfma_f32_16x16x32_bf16 v[32:35], v[174:177], v[206:209], v[32:35]
	s_setprio 0
	s_setprio 1
	v_mfma_f32_16x16x32_bf16 v[28:31], v[210:213], v[178:181], v[28:31]
	v_mfma_f32_16x16x32_bf16 v[24:27], v[214:217], v[178:181], v[24:27]
	v_mfma_f32_16x16x32_bf16 v[20:23], v[210:213], v[186:189], v[20:23]
	v_mfma_f32_16x16x32_bf16 v[16:19], v[214:217], v[186:189], v[16:19]
	v_mfma_f32_16x16x32_bf16 v[12:15], v[210:213], v[194:197], v[12:15]
	v_mfma_f32_16x16x32_bf16 v[8:11], v[214:217], v[194:197], v[8:11]
	v_mfma_f32_16x16x32_bf16 v[4:7], v[210:213], v[202:205], v[4:7]
	v_mfma_f32_16x16x32_bf16 v[0:3], v[214:217], v[202:205], v[0:3]
	v_mfma_f32_16x16x32_bf16 v[28:31], v[218:221], v[182:185], v[28:31]
	v_mfma_f32_16x16x32_bf16 v[24:27], v[222:225], v[182:185], v[24:27]
	v_mfma_f32_16x16x32_bf16 v[20:23], v[218:221], v[190:193], v[20:23]
	v_mfma_f32_16x16x32_bf16 v[16:19], v[222:225], v[190:193], v[16:19]
	v_mfma_f32_16x16x32_bf16 v[12:15], v[218:221], v[198:201], v[12:15]
	v_mfma_f32_16x16x32_bf16 v[8:11], v[222:225], v[198:201], v[8:11]
	v_mfma_f32_16x16x32_bf16 v[4:7], v[218:221], v[206:209], v[4:7]
	v_mfma_f32_16x16x32_bf16 v[0:3], v[222:225], v[206:209], v[0:3]
	s_setprio 0
	s_barrier
	ds_read_b128 v[162:165], v157
	ds_read_b128 v[166:169], v157 offset:256
	ds_read_b128 v[170:173], v158
	ds_read_b128 v[174:177], v158 offset:256
	v_readfirstlane_b32 s72, v142
	v_lshl_add_u64 v[210:211], v[226:227], 0, s[46:47]
	s_mov_b32 m0, s72
	v_readfirstlane_b32 s72, v143
	ds_read_b128 v[178:181], v150 offset:32768
	ds_read_b128 v[182:185], v150 offset:33792
	ds_read_b128 v[186:189], v150 offset:34816
	ds_read_b128 v[190:193], v150 offset:35840
	ds_read_b128 v[194:197], v150 offset:36864
	ds_read_b128 v[198:201], v150 offset:37888
	ds_read_b128 v[202:205], v150 offset:38912
	ds_read_b128 v[206:209], v150 offset:39936
	global_load_lds_dwordx4 v[210:211], off
	v_lshl_add_u64 v[210:211], v[226:227], 0, s[48:49]
	s_mov_b32 m0, s72
	s_nop 0
	global_load_lds_dwordx4 v[210:211], off
	s_waitcnt lgkmcnt(8)
	v_readfirstlane_b32 s72, v141
	v_lshl_add_u64 v[246:247], v[228:229], 0, s[38:39]
	s_mov_b32 m0, s72
	s_nop 0
	global_load_lds_dwordx4 v[246:247], off
	ds_read_b128 v[210:213], v159
	ds_read_b128 v[214:217], v159 offset:256
	ds_read_b128 v[218:221], v160
	ds_read_b128 v[222:225], v160 offset:256
	s_barrier
	s_waitcnt lgkmcnt(0)
	s_setprio 1
	s_waitcnt lgkmcnt(0)
	v_mfma_f32_16x16x32_bf16 v[124:127], v[162:165], v[178:181], v[124:127]
	v_mfma_f32_16x16x32_bf16 v[120:123], v[166:169], v[178:181], v[120:123]
	v_mfma_f32_16x16x32_bf16 v[116:119], v[162:165], v[186:189], v[116:119]
	v_mfma_f32_16x16x32_bf16 v[112:115], v[166:169], v[186:189], v[112:115]
	v_mfma_f32_16x16x32_bf16 v[108:111], v[162:165], v[194:197], v[108:111]
	v_mfma_f32_16x16x32_bf16 v[104:107], v[166:169], v[194:197], v[104:107]
	v_mfma_f32_16x16x32_bf16 v[100:103], v[162:165], v[202:205], v[100:103]
	v_mfma_f32_16x16x32_bf16 v[96:99], v[166:169], v[202:205], v[96:99]
	v_mfma_f32_16x16x32_bf16 v[124:127], v[170:173], v[182:185], v[124:127]
	v_mfma_f32_16x16x32_bf16 v[120:123], v[174:177], v[182:185], v[120:123]
	v_mfma_f32_16x16x32_bf16 v[116:119], v[170:173], v[190:193], v[116:119]
	v_mfma_f32_16x16x32_bf16 v[112:115], v[174:177], v[190:193], v[112:115]
	v_mfma_f32_16x16x32_bf16 v[108:111], v[170:173], v[198:201], v[108:111]
	v_mfma_f32_16x16x32_bf16 v[104:107], v[174:177], v[198:201], v[104:107]
	v_mfma_f32_16x16x32_bf16 v[100:103], v[170:173], v[206:209], v[100:103]
	v_mfma_f32_16x16x32_bf16 v[96:99], v[174:177], v[206:209], v[96:99]
	s_setprio 0
	s_waitcnt lgkmcnt(0)
	s_setprio 1
	s_waitcnt lgkmcnt(0)
	v_mfma_f32_16x16x32_bf16 v[92:95], v[210:213], v[178:181], v[92:95]
	v_mfma_f32_16x16x32_bf16 v[88:91], v[214:217], v[178:181], v[88:91]
	v_mfma_f32_16x16x32_bf16 v[84:87], v[210:213], v[186:189], v[84:87]
	v_mfma_f32_16x16x32_bf16 v[80:83], v[214:217], v[186:189], v[80:83]
	v_mfma_f32_16x16x32_bf16 v[76:79], v[210:213], v[194:197], v[76:79]
	v_mfma_f32_16x16x32_bf16 v[72:75], v[214:217], v[194:197], v[72:75]
	v_mfma_f32_16x16x32_bf16 v[68:71], v[210:213], v[202:205], v[68:71]
	v_mfma_f32_16x16x32_bf16 v[64:67], v[214:217], v[202:205], v[64:67]
	v_mfma_f32_16x16x32_bf16 v[92:95], v[218:221], v[182:185], v[92:95]
	v_mfma_f32_16x16x32_bf16 v[88:91], v[222:225], v[182:185], v[88:91]
	v_mfma_f32_16x16x32_bf16 v[84:87], v[218:221], v[190:193], v[84:87]
	v_mfma_f32_16x16x32_bf16 v[80:83], v[222:225], v[190:193], v[80:83]
	v_mfma_f32_16x16x32_bf16 v[76:79], v[218:221], v[198:201], v[76:79]
	v_mfma_f32_16x16x32_bf16 v[72:75], v[222:225], v[198:201], v[72:75]
	v_mfma_f32_16x16x32_bf16 v[68:71], v[218:221], v[206:209], v[68:71]
	v_mfma_f32_16x16x32_bf16 v[64:67], v[222:225], v[206:209], v[64:67]
	s_setprio 0
	s_barrier
; #define STAGE(P, BASE, br, kt) do { const char* _gb = (const char*)(BASE) + ((size_t)(br) * K + (size_t)(kt) * BK) * 2; \
;     __builtin_amdgcn_global_load_lds((const unsigned*)(_gb + loff0), (unsigned*)((char*)(P) + tid * 16), 16, 0, 0); \
;     __builtin_amdgcn_global_load_lds((const unsigned*)(_gb + (size_t)K * 128 + loff0), (unsigned*)((char*)(P) + tid * 16 + 8192), 16, 0, 0); } while (0)
; #define LDA(dst, b, h) for (int m = 0; m < 4; ++m) { \
;     dst[m][0] = *reinterpret_cast<const bf16x8*>((char*)SA(b, h) + aoff0 + m * 2048); \
;     dst[m][1] = *reinterpret_cast<const bf16x8*>((char*)SA(b, h) + aoff1 + m * 2048); }
; #define LDB(dst, b, h) for (int n = 0; n < 2; ++n) { \
;     dst[n][0] = *reinterpret_cast<const bf16x8*>((char*)SB(b, h) + boff0 + n * 256); \
;     dst[n][1] = *reinterpret_cast<const bf16x8*>((char*)SB(b, h) + boff1 + n * 256); }
; #define MMA(ai, bj, At, Btf) do { __builtin_amdgcn_s_setprio(1); \
;     for (int m = 0; m < 4; ++m) for (int n = 0; n < 2; ++n) for (int k = 0; k < 2; ++k) \
;       acc[ai][bj][m][n] = __builtin_amdgcn_mfma_f32_16x16x32_bf16(Btf[n][k], At[m][k], acc[ai][bj][m][n], 0, 0, 0); \
;     __builtin_amdgcn_s_setprio(0); } while (0)
; #define WAIT_V(n) asm volatile("s_waitcnt vmcnt(" #n ")" ::: "memory")
; #define WAIT_L(n) asm volatile("s_waitcnt lgkmcnt(" #n ")" ::: "memory")
; #define BAR __builtin_amdgcn_s_barrier()
; #define SCHED __builtin_amdgcn_sched_barrier(0)
; template <int EPI> ...
;     ...
;     LDA(At, 1, 1); STAGE(SA(1, 0), A, brow, t + 3);
;     BAR; WAIT_L(0); MMA(1, 0, At, B0); BAR; SCHED;
;     STAGE(SB(1, 1), Bt, bcol + HALF, t + 3);
;     WAIT_V(6); BAR; MMA(1, 1, At, B1); BAR;
;   }
;   { LDB(B0, 0, 0); LDA(At, 0, 0); STAGE(SA(1, 1), A, brow + HALF, nt - 1);
;     BAR; WAIT_L(0); MMA(0, 0, At, B0); BAR;
	v_readfirstlane_b32 s72, v144
	v_lshl_add_u64 v[230:231], v[228:229], 0, s[50:51]
	s_mov_b32 m0, s72
	v_readfirstlane_b32 s72, v145
	global_load_lds_dwordx4 v[230:231], off
	v_lshl_add_u64 v[230:231], v[228:229], 0, s[52:53]
	s_mov_b32 m0, s72
	s_nop 0
	global_load_lds_dwordx4 v[230:231], off
	v_readfirstlane_b32 s72, v146
	v_lshl_add_u64 v[230:231], v[226:227], 0, s[54:55]
	s_mov_b32 m0, s72
	v_readfirstlane_b32 s72, v147
	ds_read_b128 v[178:181], v150 offset:49152
	ds_read_b128 v[182:185], v150 offset:50176
	ds_read_b128 v[186:189], v150 offset:51200
	ds_read_b128 v[190:193], v150 offset:52224
	ds_read_b128 v[194:197], v150 offset:53248
	ds_read_b128 v[198:201], v150 offset:54272
	ds_read_b128 v[202:205], v150 offset:55296
	ds_read_b128 v[206:209], v150 offset:56320
	global_load_lds_dwordx4 v[230:231], off
	v_lshl_add_u64 v[226:227], v[226:227], 0, s[56:57]
	s_mov_b32 m0, s72
	s_nop 0
	global_load_lds_dwordx4 v[226:227], off
	v_readfirstlane_b32 s72, v148
	v_lshl_add_u64 v[246:247], v[228:229], 0, s[58:59]
	s_mov_b32 m0, s72
	v_readfirstlane_b32 s72, v149
	global_load_lds_dwordx4 v[246:247], off
	s_waitcnt vmcnt(5)
	s_barrier
	s_waitcnt lgkmcnt(0)
	s_setprio 1
	s_waitcnt lgkmcnt(0)
	v_mfma_f32_16x16x32_bf16 v[60:63], v[162:165], v[178:181], v[60:63]
	v_mfma_f32_16x16x32_bf16 v[56:59], v[166:169], v[178:181], v[56:59]
	v_mfma_f32_16x16x32_bf16 v[52:55], v[162:165], v[186:189], v[52:55]
	v_mfma_f32_16x16x32_bf16 v[48:51], v[166:169], v[186:189], v[48:51]
	v_mfma_f32_16x16x32_bf16 v[44:47], v[162:165], v[194:197], v[44:47]
	v_mfma_f32_16x16x32_bf16 v[40:43], v[166:169], v[194:197], v[40:43]
	v_mfma_f32_16x16x32_bf16 v[36:39], v[162:165], v[202:205], v[36:39]
	v_mfma_f32_16x16x32_bf16 v[32:35], v[166:169], v[202:205], v[32:35]
	v_mfma_f32_16x16x32_bf16 v[60:63], v[170:173], v[182:185], v[60:63]
	v_mfma_f32_16x16x32_bf16 v[56:59], v[174:177], v[182:185], v[56:59]
	v_mfma_f32_16x16x32_bf16 v[52:55], v[170:173], v[190:193], v[52:55]
	v_mfma_f32_16x16x32_bf16 v[48:51], v[174:177], v[190:193], v[48:51]
	v_mfma_f32_16x16x32_bf16 v[44:47], v[170:173], v[198:201], v[44:47]
	v_mfma_f32_16x16x32_bf16 v[40:43], v[174:177], v[198:201], v[40:43]
	v_mfma_f32_16x16x32_bf16 v[36:39], v[170:173], v[206:209], v[36:39]
	v_mfma_f32_16x16x32_bf16 v[32:35], v[174:177], v[206:209], v[32:35]
	s_setprio 0
	s_setprio 1
	v_mfma_f32_16x16x32_bf16 v[28:31], v[210:213], v[178:181], v[28:31]
	v_mfma_f32_16x16x32_bf16 v[24:27], v[214:217], v[178:181], v[24:27]
	v_mfma_f32_16x16x32_bf16 v[20:23], v[210:213], v[186:189], v[20:23]
	v_mfma_f32_16x16x32_bf16 v[16:19], v[214:217], v[186:189], v[16:19]
	v_mfma_f32_16x16x32_bf16 v[12:15], v[210:213], v[194:197], v[12:15]
	v_mfma_f32_16x16x32_bf16 v[8:11], v[214:217], v[194:197], v[8:11]
	v_mfma_f32_16x16x32_bf16 v[4:7], v[210:213], v[202:205], v[4:7]
	v_mfma_f32_16x16x32_bf16 v[0:3], v[214:217], v[202:205], v[0:3]
	v_mfma_f32_16x16x32_bf16 v[28:31], v[218:221], v[182:185], v[28:31]
	v_mfma_f32_16x16x32_bf16 v[24:27], v[222:225], v[182:185], v[24:27]
	v_mfma_f32_16x16x32_bf16 v[20:23], v[218:221], v[190:193], v[20:23]
	v_mfma_f32_16x16x32_bf16 v[16:19], v[222:225], v[190:193], v[16:19]
	v_mfma_f32_16x16x32_bf16 v[12:15], v[218:221], v[198:201], v[12:15]
	v_mfma_f32_16x16x32_bf16 v[8:11], v[222:225], v[198:201], v[8:11]
	v_mfma_f32_16x16x32_bf16 v[4:7], v[218:221], v[206:209], v[4:7]
	v_mfma_f32_16x16x32_bf16 v[0:3], v[222:225], v[206:209], v[0:3]
	s_setprio 0
	s_add_i32 s67, s67, 2
	s_add_u32 s70, s70, 0x100
	s_addc_u32 s71, s71, 0
	s_add_u32 s68, s68, 0x100
	s_addc_u32 s69, s69, 0
	s_cmp_lt_u32 s67, 28
	s_barrier
	s_cbranch_scc1 .LBB0_277
	v_readfirstlane_b32 s72, v149
	v_lshl_add_u64 v[246:247], v[228:229], 0, s[60:61]
	s_mov_b32 m0, s72
	s_nop 0
	global_load_lds_dwordx4 v[246:247], off
	v_readfirstlane_b32 s67, v151
	v_lshl_add_u64 v[210:211], v[132:133], 0, s[62:63]
	s_mov_b32 m0, s67
	v_readfirstlane_b32 s67, v152
	ds_read_b128 v[162:165], v153
	ds_read_b128 v[166:169], v153 offset:256
	ds_read_b128 v[170:173], v154
	ds_read_b128 v[174:177], v154 offset:256
	ds_read_b128 v[178:181], v150
	ds_read_b128 v[182:185], v150 offset:1024
	ds_read_b128 v[186:189], v150 offset:2048
	ds_read_b128 v[190:193], v150 offset:3072
	ds_read_b128 v[194:197], v150 offset:4096
	ds_read_b128 v[198:201], v150 offset:5120
	ds_read_b128 v[202:205], v150 offset:6144
	ds_read_b128 v[206:209], v150 offset:7168
	global_load_lds_dwordx4 v[210:211], off
	v_lshl_add_u64 v[132:133], v[132:133], 0, s[64:65]
	s_mov_b32 m0, s67
	s_nop 0
	global_load_lds_dwordx4 v[132:133], off
	s_barrier
	s_waitcnt lgkmcnt(0)
	s_setprio 1
	s_waitcnt lgkmcnt(0)
	v_mfma_f32_16x16x32_bf16 v[124:127], v[162:165], v[178:181], v[124:127]
	v_mfma_f32_16x16x32_bf16 v[116:119], v[162:165], v[186:189], v[116:119]
	v_mfma_f32_16x16x32_bf16 v[108:111], v[162:165], v[194:197], v[108:111]
	v_mfma_f32_16x16x32_bf16 v[100:103], v[162:165], v[202:205], v[100:103]
	v_mfma_f32_16x16x32_bf16 v[124:127], v[170:173], v[182:185], v[124:127]
	v_mfma_f32_16x16x32_bf16 v[120:123], v[166:169], v[178:181], v[120:123]
	v_mfma_f32_16x16x32_bf16 v[116:119], v[170:173], v[190:193], v[116:119]
	v_mfma_f32_16x16x32_bf16 v[112:115], v[166:169], v[186:189], v[112:115]
	v_mfma_f32_16x16x32_bf16 v[108:111], v[170:173], v[198:201], v[108:111]
	v_mfma_f32_16x16x32_bf16 v[104:107], v[166:169], v[194:197], v[104:107]
	v_mfma_f32_16x16x32_bf16 v[100:103], v[170:173], v[206:209], v[100:103]
	v_mfma_f32_16x16x32_bf16 v[96:99], v[166:169], v[202:205], v[96:99]
	v_mfma_f32_16x16x32_bf16 v[210:213], v[174:177], v[182:185], v[120:123]
	v_mfma_f32_16x16x32_bf16 v[214:217], v[174:177], v[190:193], v[112:115]
	v_mfma_f32_16x16x32_bf16 v[218:221], v[174:177], v[198:201], v[104:107]
	v_mfma_f32_16x16x32_bf16 v[222:225], v[174:177], v[206:209], v[96:99]
	s_setprio 0
	s_barrier
; #define LDA(dst, b, h) for (int m = 0; m < 4; ++m) { \
;     dst[m][0] = *reinterpret_cast<const bf16x8*>((char*)SA(b, h) + aoff0 + m * 2048); \
;     dst[m][1] = *reinterpret_cast<const bf16x8*>((char*)SA(b, h) + aoff1 + m * 2048); }
; #define LDB(dst, b, h) for (int n = 0; n < 2; ++n) { \
;     dst[n][0] = *reinterpret_cast<const bf16x8*>((char*)SB(b, h) + boff0 + n * 256); \
;     dst[n][1] = *reinterpret_cast<const bf16x8*>((char*)SB(b, h) + boff1 + n * 256); }
; #define MMA(ai, bj, At, Btf) do { __builtin_amdgcn_s_setprio(1); \
;     for (int m = 0; m < 4; ++m) for (int n = 0; n < 2; ++n) for (int k = 0; k < 2; ++k) \
;       acc[ai][bj][m][n] = __builtin_amdgcn_mfma_f32_16x16x32_bf16(Btf[n][k], At[m][k], acc[ai][bj][m][n], 0, 0, 0); \
;     __builtin_amdgcn_s_setprio(0); } while (0)
; #define WAIT_V(n) asm volatile("s_waitcnt vmcnt(" #n ")" ::: "memory")
; #define WAIT_L(n) asm volatile("s_waitcnt lgkmcnt(" #n ")" ::: "memory")
; #define BAR __builtin_amdgcn_s_barrier()
; template <int EPI> ...
;     ...
;     BAR; WAIT_L(0); MMA(0, 0, At, B0); BAR;
;     LDB(B1, 0, 1); BAR; WAIT_L(0); MMA(0, 1, At, B1); BAR;
;     LDA(At, 0, 1); WAIT_V(4); BAR; WAIT_L(0); MMA(1, 0, At, B0); MMA(1, 1, At, B1); BAR; }
;   { LDB(B0, 1, 0); LDA(At, 1, 0); WAIT_V(2); BAR; WAIT_L(0); MMA(0, 0, At, B0); BAR;
	s_nop 1
	ds_read_b128 v[96:99], v155
	ds_read_b128 v[104:107], v155 offset:256
	ds_read_b128 v[112:115], v156
	ds_read_b128 v[120:123], v156 offset:256
	s_barrier
	s_waitcnt lgkmcnt(0)
	s_setprio 1
	s_waitcnt lgkmcnt(0)
	v_mfma_f32_16x16x32_bf16 v[92:95], v[96:99], v[178:181], v[92:95]
	v_mfma_f32_16x16x32_bf16 v[84:87], v[96:99], v[186:189], v[84:87]
	v_mfma_f32_16x16x32_bf16 v[76:79], v[96:99], v[194:197], v[76:79]
	v_mfma_f32_16x16x32_bf16 v[68:71], v[96:99], v[202:205], v[68:71]
	v_mfma_f32_16x16x32_bf16 v[92:95], v[112:115], v[182:185], v[92:95]
	v_mfma_f32_16x16x32_bf16 v[88:91], v[104:107], v[178:181], v[88:91]
	v_mfma_f32_16x16x32_bf16 v[84:87], v[112:115], v[190:193], v[84:87]
	v_mfma_f32_16x16x32_bf16 v[80:83], v[104:107], v[186:189], v[80:83]
	v_mfma_f32_16x16x32_bf16 v[76:79], v[112:115], v[198:201], v[76:79]
	v_mfma_f32_16x16x32_bf16 v[72:75], v[104:107], v[194:197], v[72:75]
	v_mfma_f32_16x16x32_bf16 v[68:71], v[112:115], v[206:209], v[68:71]
	v_mfma_f32_16x16x32_bf16 v[64:67], v[104:107], v[202:205], v[64:67]
	v_mfma_f32_16x16x32_bf16 v[178:181], v[120:123], v[182:185], v[88:91]
	v_mfma_f32_16x16x32_bf16 v[182:185], v[120:123], v[190:193], v[80:83]
	v_mfma_f32_16x16x32_bf16 v[186:189], v[120:123], v[198:201], v[72:75]
	v_mfma_f32_16x16x32_bf16 v[190:193], v[120:123], v[206:209], v[64:67]
	s_setprio 0
	s_barrier
	s_nop 1
	ds_read_b128 v[64:67], v150 offset:16384
	ds_read_b128 v[72:75], v150 offset:17408
	ds_read_b128 v[80:83], v150 offset:18432
	ds_read_b128 v[88:91], v150 offset:19456
	ds_read_b128 v[194:197], v150 offset:20480
	ds_read_b128 v[198:201], v150 offset:21504
	ds_read_b128 v[202:205], v150 offset:22528
	ds_read_b128 v[206:209], v150 offset:23552
	s_waitcnt vmcnt(4)
	s_barrier
	s_waitcnt lgkmcnt(0)
	s_setprio 1
	s_waitcnt lgkmcnt(0)
	v_mfma_f32_16x16x32_bf16 v[60:63], v[162:165], v[64:67], v[60:63]
	v_mfma_f32_16x16x32_bf16 v[56:59], v[166:169], v[64:67], v[56:59]
	v_mfma_f32_16x16x32_bf16 v[52:55], v[162:165], v[80:83], v[52:55]
	v_mfma_f32_16x16x32_bf16 v[40:43], v[166:169], v[194:197], v[40:43]
	v_mfma_f32_16x16x32_bf16 v[36:39], v[162:165], v[202:205], v[36:39]
	v_mfma_f32_16x16x32_bf16 v[60:63], v[170:173], v[72:75], v[60:63]
	v_mfma_f32_16x16x32_bf16 v[56:59], v[174:177], v[72:75], v[56:59]
	v_mfma_f32_16x16x32_bf16 v[52:55], v[170:173], v[88:91], v[52:55]
	v_mfma_f32_16x16x32_bf16 v[48:51], v[166:169], v[80:83], v[48:51]
	v_mfma_f32_16x16x32_bf16 v[44:47], v[162:165], v[194:197], v[44:47]
	v_mfma_f32_16x16x32_bf16 v[40:43], v[174:177], v[198:201], v[40:43]
	v_mfma_f32_16x16x32_bf16 v[36:39], v[170:173], v[206:209], v[36:39]
	v_mfma_f32_16x16x32_bf16 v[32:35], v[166:169], v[202:205], v[32:35]
	v_mfma_f32_16x16x32_bf16 v[226:229], v[174:177], v[88:91], v[48:51]
	v_mfma_f32_16x16x32_bf16 v[230:233], v[170:173], v[198:201], v[44:47]
	v_mfma_f32_16x16x32_bf16 v[162:165], v[174:177], v[206:209], v[32:35]
	s_setprio 0
	s_setprio 1
	v_mfma_f32_16x16x32_bf16 v[24:27], v[104:107], v[64:67], v[24:27]
	v_mfma_f32_16x16x32_bf16 v[20:23], v[96:99], v[80:83], v[20:23]
	v_mfma_f32_16x16x32_bf16 v[8:11], v[104:107], v[194:197], v[8:11]
	v_mfma_f32_16x16x32_bf16 v[4:7], v[96:99], v[202:205], v[4:7]
	v_mfma_f32_16x16x32_bf16 v[28:31], v[96:99], v[64:67], v[28:31]
	v_mfma_f32_16x16x32_bf16 v[24:27], v[120:123], v[72:75], v[24:27]
	v_mfma_f32_16x16x32_bf16 v[20:23], v[112:115], v[88:91], v[20:23]
	v_mfma_f32_16x16x32_bf16 v[16:19], v[104:107], v[80:83], v[16:19]
	v_mfma_f32_16x16x32_bf16 v[12:15], v[96:99], v[194:197], v[12:15]
	v_mfma_f32_16x16x32_bf16 v[8:11], v[120:123], v[198:201], v[8:11]
	v_mfma_f32_16x16x32_bf16 v[4:7], v[112:115], v[206:209], v[4:7]
	v_mfma_f32_16x16x32_bf16 v[0:3], v[104:107], v[202:205], v[0:3]
	v_mfma_f32_16x16x32_bf16 v[166:169], v[112:115], v[72:75], v[28:31]
	v_mfma_f32_16x16x32_bf16 v[170:173], v[120:123], v[88:91], v[16:19]
	v_mfma_f32_16x16x32_bf16 v[174:177], v[112:115], v[198:201], v[12:15]
	v_mfma_f32_16x16x32_bf16 v[194:197], v[120:123], v[206:209], v[0:3]
	s_setprio 0
	s_barrier
	s_nop 1
	ds_read_b128 v[0:3], v157
	ds_read_b128 v[198:201], v157 offset:256
	ds_read_b128 v[12:15], v158
	ds_read_b128 v[202:205], v158 offset:256
	ds_read_b128 v[16:19], v150 offset:32768
	ds_read_b128 v[28:31], v150 offset:33792
	ds_read_b128 v[32:35], v150 offset:34816
	ds_read_b128 v[44:47], v150 offset:35840
	ds_read_b128 v[48:51], v150 offset:36864
	ds_read_b128 v[206:209], v150 offset:37888
	ds_read_b128 v[234:237], v150 offset:38912
	ds_read_b128 v[238:241], v150 offset:39936
	s_waitcnt vmcnt(2)
	s_barrier
; #define LDA(dst, b, h) for (int m = 0; m < 4; ++m) { \
;     dst[m][0] = *reinterpret_cast<const bf16x8*>((char*)SA(b, h) + aoff0 + m * 2048); \
;     dst[m][1] = *reinterpret_cast<const bf16x8*>((char*)SA(b, h) + aoff1 + m * 2048); }
; #define LDB(dst, b, h) for (int n = 0; n < 2; ++n) { \
;     dst[n][0] = *reinterpret_cast<const bf16x8*>((char*)SB(b, h) + boff0 + n * 256); \
;     dst[n][1] = *reinterpret_cast<const bf16x8*>((char*)SB(b, h) + boff1 + n * 256); }
; #define MMA(ai, bj, At, Btf) do { __builtin_amdgcn_s_setprio(1); \
;     for (int m = 0; m < 4; ++m) for (int n = 0; n < 2; ++n) for (int k = 0; k < 2; ++k) \
;       acc[ai][bj][m][n] = __builtin_amdgcn_mfma_f32_16x16x32_bf16(Btf[n][k], At[m][k], acc[ai][bj][m][n], 0, 0, 0); \
;     __builtin_amdgcn_s_setprio(0); } while (0)
; #define WAIT_V(n) asm volatile("s_waitcnt vmcnt(" #n ")" ::: "memory")
; #define WAIT_L(n) asm volatile("s_waitcnt lgkmcnt(" #n ")" ::: "memory")
; #define BAR __builtin_amdgcn_s_barrier()
; template <int EPI> ...
;     ...
;   { LDB(B0, 1, 0); LDA(At, 1, 0); WAIT_V(2); BAR; WAIT_L(0); MMA(0, 0, At, B0); BAR;
;     LDB(B1, 1, 1); WAIT_V(0); BAR; WAIT_L(0); MMA(0, 1, At, B1); BAR;
;     LDA(At, 1, 1); BAR; WAIT_L(0); MMA(1, 0, At, B0); MMA(1, 1, At, B1); BAR; }
;   if (wr == 0) BAR;
	s_waitcnt lgkmcnt(0)
	s_setprio 1
	s_waitcnt lgkmcnt(0)
	v_mfma_f32_16x16x32_bf16 v[64:67], v[0:3], v[16:19], v[124:127]
	v_mfma_f32_16x16x32_bf16 v[120:123], v[12:15], v[28:31], v[64:67]
	v_mfma_f32_16x16x32_bf16 v[64:67], v[198:201], v[16:19], v[210:213]
	v_mfma_f32_16x16x32_bf16 v[112:115], v[202:205], v[28:31], v[64:67]
	v_mfma_f32_16x16x32_bf16 v[64:67], v[0:3], v[32:35], v[116:119]
	v_mfma_f32_16x16x32_bf16 v[104:107], v[12:15], v[44:47], v[64:67]
	v_mfma_f32_16x16x32_bf16 v[64:67], v[198:201], v[32:35], v[214:217]
	v_mfma_f32_16x16x32_bf16 v[96:99], v[202:205], v[44:47], v[64:67]
	v_mfma_f32_16x16x32_bf16 v[64:67], v[0:3], v[48:51], v[108:111]
	v_mfma_f32_16x16x32_bf16 v[88:91], v[12:15], v[206:209], v[64:67]
	v_mfma_f32_16x16x32_bf16 v[64:67], v[198:201], v[48:51], v[218:221]
	v_mfma_f32_16x16x32_bf16 v[80:83], v[202:205], v[206:209], v[64:67]
	v_mfma_f32_16x16x32_bf16 v[64:67], v[0:3], v[234:237], v[100:103]
	v_mfma_f32_16x16x32_bf16 v[72:75], v[12:15], v[238:241], v[64:67]
	v_mfma_f32_16x16x32_bf16 v[64:67], v[198:201], v[234:237], v[222:225]
	v_mfma_f32_16x16x32_bf16 v[64:67], v[202:205], v[238:241], v[64:67]
	s_setprio 0
	s_barrier
	ds_read_b128 v[210:213], v159
	ds_read_b128 v[214:217], v159 offset:256
	ds_read_b128 v[218:221], v160
	ds_read_b128 v[222:225], v160 offset:256
	s_waitcnt vmcnt(0)
	s_barrier
	s_waitcnt lgkmcnt(0)
	s_setprio 1
	s_waitcnt lgkmcnt(0)
	v_mfma_f32_16x16x32_bf16 v[92:95], v[210:213], v[16:19], v[92:95]
	v_mfma_f32_16x16x32_bf16 v[16:19], v[214:217], v[16:19], v[178:181]
	v_mfma_f32_16x16x32_bf16 v[116:119], v[222:225], v[28:31], v[16:19]
	v_mfma_f32_16x16x32_bf16 v[16:19], v[210:213], v[32:35], v[84:87]
	v_mfma_f32_16x16x32_bf16 v[108:111], v[218:221], v[44:47], v[16:19]
	v_mfma_f32_16x16x32_bf16 v[16:19], v[214:217], v[32:35], v[182:185]
	v_mfma_f32_16x16x32_bf16 v[100:103], v[222:225], v[44:47], v[16:19]
	v_mfma_f32_16x16x32_bf16 v[16:19], v[210:213], v[48:51], v[76:79]
	v_mfma_f32_16x16x32_bf16 v[124:127], v[218:221], v[28:31], v[92:95]
	v_mfma_f32_16x16x32_bf16 v[92:95], v[218:221], v[206:209], v[16:19]
	v_mfma_f32_16x16x32_bf16 v[16:19], v[214:217], v[48:51], v[186:189]
	v_mfma_f32_16x16x32_bf16 v[84:87], v[222:225], v[206:209], v[16:19]
	v_mfma_f32_16x16x32_bf16 v[16:19], v[210:213], v[234:237], v[68:71]
	v_mfma_f32_16x16x32_bf16 v[76:79], v[218:221], v[238:241], v[16:19]
	v_mfma_f32_16x16x32_bf16 v[16:19], v[214:217], v[234:237], v[190:193]
	v_mfma_f32_16x16x32_bf16 v[68:71], v[222:225], v[238:241], v[16:19]
	s_setprio 0
	s_barrier
	ds_read_b128 v[178:181], v150 offset:49152
	ds_read_b128 v[182:185], v150 offset:50176
	ds_read_b128 v[186:189], v150 offset:51200
	ds_read_b128 v[190:193], v150 offset:52224
	ds_read_b128 v[206:209], v150 offset:53248
	ds_read_b128 v[234:237], v150 offset:54272
	ds_read_b128 v[238:241], v150 offset:55296
	ds_read_b128 v[242:245], v150 offset:56320
	s_barrier
	s_waitcnt lgkmcnt(0)
	s_setprio 1
	s_waitcnt lgkmcnt(0)
	v_mfma_f32_16x16x32_bf16 v[16:19], v[0:3], v[178:181], v[60:63]
	v_mfma_f32_16x16x32_bf16 v[60:63], v[12:15], v[182:185], v[16:19]
	v_mfma_f32_16x16x32_bf16 v[16:19], v[198:201], v[178:181], v[56:59]
	v_mfma_f32_16x16x32_bf16 v[48:51], v[202:205], v[182:185], v[16:19]
	v_mfma_f32_16x16x32_bf16 v[16:19], v[0:3], v[186:189], v[52:55]
	v_mfma_f32_16x16x32_bf16 v[44:47], v[12:15], v[190:193], v[16:19]
	v_mfma_f32_16x16x32_bf16 v[16:19], v[198:201], v[186:189], v[226:229]
	v_mfma_f32_16x16x32_bf16 v[32:35], v[202:205], v[190:193], v[16:19]
	v_mfma_f32_16x16x32_bf16 v[16:19], v[0:3], v[206:209], v[230:233]
	v_mfma_f32_16x16x32_bf16 v[0:3], v[0:3], v[238:241], v[36:39]
	v_mfma_f32_16x16x32_bf16 v[28:31], v[12:15], v[234:237], v[16:19]
	v_mfma_f32_16x16x32_bf16 v[16:19], v[198:201], v[206:209], v[40:43]
	v_mfma_f32_16x16x32_bf16 v[12:15], v[12:15], v[242:245], v[0:3]
	v_mfma_f32_16x16x32_bf16 v[0:3], v[198:201], v[238:241], v[162:165]
	v_mfma_f32_16x16x32_bf16 v[16:19], v[202:205], v[234:237], v[16:19]
	v_mfma_f32_16x16x32_bf16 v[0:3], v[202:205], v[242:245], v[0:3]
	s_setprio 0
	s_setprio 1
	v_mfma_f32_16x16x32_bf16 v[20:23], v[210:213], v[186:189], v[20:23]
	v_mfma_f32_16x16x32_bf16 v[36:39], v[210:213], v[178:181], v[166:169]
	v_mfma_f32_16x16x32_bf16 v[40:43], v[218:221], v[190:193], v[20:23]
	v_mfma_f32_16x16x32_bf16 v[20:23], v[214:217], v[186:189], v[170:173]
	v_mfma_f32_16x16x32_bf16 v[56:59], v[218:221], v[182:185], v[36:39]
	v_mfma_f32_16x16x32_bf16 v[24:27], v[214:217], v[178:181], v[24:27]
	v_mfma_f32_16x16x32_bf16 v[36:39], v[222:225], v[190:193], v[20:23]
	v_mfma_f32_16x16x32_bf16 v[20:23], v[210:213], v[206:209], v[174:177]
	v_mfma_f32_16x16x32_bf16 v[8:11], v[214:217], v[206:209], v[8:11]
	v_mfma_f32_16x16x32_bf16 v[4:7], v[210:213], v[238:241], v[4:7]
	v_mfma_f32_16x16x32_bf16 v[52:55], v[222:225], v[182:185], v[24:27]
	v_mfma_f32_16x16x32_bf16 v[24:27], v[218:221], v[234:237], v[20:23]
	v_mfma_f32_16x16x32_bf16 v[20:23], v[222:225], v[234:237], v[8:11]
	v_mfma_f32_16x16x32_bf16 v[8:11], v[218:221], v[242:245], v[4:7]
	v_mfma_f32_16x16x32_bf16 v[4:7], v[214:217], v[238:241], v[194:197]
	v_mfma_f32_16x16x32_bf16 v[4:7], v[222:225], v[242:245], v[4:7]
	s_setprio 0
	s_barrier
	s_and_saveexec_b64 s[68:69], s[2:3]
	s_cbranch_execz .LBB0_271
	s_barrier
	s_branch .LBB0_271

; #define STAGE(P, BASE, br, kt) do { const char* _gb = (const char*)(BASE) + ((size_t)(br) * K + (size_t)(kt) * BK) * 2; \
;     __builtin_amdgcn_global_load_lds((const unsigned*)(_gb + loff0), (unsigned*)((char*)(P) + tid * 16), 16, 0, 0); \
;     __builtin_amdgcn_global_load_lds((const unsigned*)(_gb + (size_t)K * 128 + loff0), (unsigned*)((char*)(P) + tid * 16 + 8192), 16, 0, 0); } while (0)
; #define LDA(dst, b, h) for (int m = 0; m < 4; ++m) { \
;     dst[m][0] = *reinterpret_cast<const bf16x8*>((char*)SA(b, h) + aoff0 + m * 2048); \
;     dst[m][1] = *reinterpret_cast<const bf16x8*>((char*)SA(b, h) + aoff1 + m * 2048); }
; #define LDB(dst, b, h) for (int n = 0; n < 2; ++n) { \
;     dst[n][0] = *reinterpret_cast<const bf16x8*>((char*)SB(b, h) + boff0 + n * 256); \
;     dst[n][1] = *reinterpret_cast<const bf16x8*>((char*)SB(b, h) + boff1 + n * 256); }
; #define MMA(ai, bj, At, Btf) do { __builtin_amdgcn_s_setprio(1); \
;     for (int m = 0; m < 4; ++m) for (int n = 0; n < 2; ++n) for (int k = 0; k < 2; ++k) \
;       acc[ai][bj][m][n] = __builtin_amdgcn_mfma_f32_16x16x32_bf16(Btf[n][k], At[m][k], acc[ai][bj][m][n], 0, 0, 0); \
;     __builtin_amdgcn_s_setprio(0); } while (0)
; #define WAIT_V(n) asm volatile("s_waitcnt vmcnt(" #n ")" ::: "memory")
; #define WAIT_L(n) asm volatile("s_waitcnt lgkmcnt(" #n ")" ::: "memory")
; #define BAR __builtin_amdgcn_s_barrier()
; #define SCHED __builtin_amdgcn_sched_barrier(0)
; template <int EPI> ...
;     ...
;     LDB(B0, 0, 0); SCHED; LDA(At, 0, 0); STAGE(SA(1, 1), A, brow + HALF, t + 1);
;     WAIT_L(8); BAR; WAIT_L(0); MMA(0, 0, At, B0); BAR; SCHED;
;     LDB(B1, 0, 1); STAGE(SB(0, 0), Bt, bcol, t + 2);
;     BAR; WAIT_L(0); MMA(0, 1, At, B1); BAR;
;     LDA(At, 0, 1); STAGE(SA(0, 0), A, brow, t + 2);
;     BAR; WAIT_L(0); MMA(1, 0, At, B0); BAR; SCHED;
;     STAGE(SB(0, 1), Bt, bcol + HALF, t + 2);
;     WAIT_V(6); BAR; MMA(1, 1, At, B1); BAR;
.LBB0_324:
	ds_read_b128 v[160:163], v152
	ds_read_b128 v[164:167], v152 offset:256
	ds_read_b128 v[168:171], v153
	ds_read_b128 v[172:175], v153 offset:256
	v_lshl_add_u64 v[224:225], s[64:65], 0, v[132:133]
	v_readfirstlane_b32 s77, v150
	v_lshl_add_u64 v[208:209], v[224:225], 0, s[16:17]
	s_mov_b32 m0, s77
	v_readfirstlane_b32 s77, v151
	ds_read_b128 v[176:179], v149
	ds_read_b128 v[180:183], v149 offset:1024
	ds_read_b128 v[184:187], v149 offset:2048
	ds_read_b128 v[188:191], v149 offset:3072
	ds_read_b128 v[192:195], v149 offset:4096
	ds_read_b128 v[196:199], v149 offset:5120
	ds_read_b128 v[200:203], v149 offset:6144
	ds_read_b128 v[204:207], v149 offset:7168
	global_load_lds_dwordx4 v[208:209], off
	v_lshl_add_u64 v[208:209], v[224:225], 0, s[18:19]
	s_mov_b32 m0, s77
	s_nop 0
	global_load_lds_dwordx4 v[208:209], off
	s_waitcnt lgkmcnt(8)
	v_readfirstlane_b32 s77, v148
	v_lshl_add_u64 v[246:247], v[228:229], 0, s[58:59]
	s_mov_b32 m0, s77
	s_nop 0
	global_load_lds_dwordx4 v[246:247], off
	ds_read_b128 v[208:211], v154
	ds_read_b128 v[212:215], v154 offset:256
	ds_read_b128 v[216:219], v155
	ds_read_b128 v[220:223], v155 offset:256
	s_barrier
	s_waitcnt lgkmcnt(0)
	s_setprio 1
	s_waitcnt lgkmcnt(0)
	v_mfma_f32_16x16x32_bf16 v[124:127], v[160:163], v[176:179], v[124:127]
	v_mfma_f32_16x16x32_bf16 v[120:123], v[164:167], v[176:179], v[120:123]
	v_mfma_f32_16x16x32_bf16 v[116:119], v[160:163], v[184:187], v[116:119]
	v_mfma_f32_16x16x32_bf16 v[112:115], v[164:167], v[184:187], v[112:115]
	v_mfma_f32_16x16x32_bf16 v[108:111], v[160:163], v[192:195], v[108:111]
	v_mfma_f32_16x16x32_bf16 v[104:107], v[164:167], v[192:195], v[104:107]
	v_mfma_f32_16x16x32_bf16 v[100:103], v[160:163], v[200:203], v[100:103]
	v_mfma_f32_16x16x32_bf16 v[96:99], v[164:167], v[200:203], v[96:99]
	v_mfma_f32_16x16x32_bf16 v[124:127], v[168:171], v[180:183], v[124:127]
	v_mfma_f32_16x16x32_bf16 v[120:123], v[172:175], v[180:183], v[120:123]
	v_mfma_f32_16x16x32_bf16 v[116:119], v[168:171], v[188:191], v[116:119]
	v_mfma_f32_16x16x32_bf16 v[112:115], v[172:175], v[188:191], v[112:115]
	v_mfma_f32_16x16x32_bf16 v[108:111], v[168:171], v[196:199], v[108:111]
	v_mfma_f32_16x16x32_bf16 v[104:107], v[172:175], v[196:199], v[104:107]
	v_mfma_f32_16x16x32_bf16 v[100:103], v[168:171], v[204:207], v[100:103]
	v_mfma_f32_16x16x32_bf16 v[96:99], v[172:175], v[204:207], v[96:99]
	s_setprio 0
	s_waitcnt lgkmcnt(0)
	s_setprio 1
	s_waitcnt lgkmcnt(0)
	v_mfma_f32_16x16x32_bf16 v[92:95], v[208:211], v[176:179], v[92:95]
	v_mfma_f32_16x16x32_bf16 v[88:91], v[212:215], v[176:179], v[88:91]
	v_mfma_f32_16x16x32_bf16 v[84:87], v[208:211], v[184:187], v[84:87]
	v_mfma_f32_16x16x32_bf16 v[80:83], v[212:215], v[184:187], v[80:83]
	v_mfma_f32_16x16x32_bf16 v[76:79], v[208:211], v[192:195], v[76:79]
	v_mfma_f32_16x16x32_bf16 v[72:75], v[212:215], v[192:195], v[72:75]
	v_mfma_f32_16x16x32_bf16 v[68:71], v[208:211], v[200:203], v[68:71]
	v_mfma_f32_16x16x32_bf16 v[64:67], v[212:215], v[200:203], v[64:67]
	v_mfma_f32_16x16x32_bf16 v[92:95], v[216:219], v[180:183], v[92:95]
	v_mfma_f32_16x16x32_bf16 v[88:91], v[220:223], v[180:183], v[88:91]
	v_mfma_f32_16x16x32_bf16 v[84:87], v[216:219], v[188:191], v[84:87]
	v_mfma_f32_16x16x32_bf16 v[80:83], v[220:223], v[188:191], v[80:83]
	v_mfma_f32_16x16x32_bf16 v[76:79], v[216:219], v[196:199], v[76:79]
	v_mfma_f32_16x16x32_bf16 v[72:75], v[220:223], v[196:199], v[72:75]
	v_mfma_f32_16x16x32_bf16 v[68:71], v[216:219], v[204:207], v[68:71]
	v_mfma_f32_16x16x32_bf16 v[64:67], v[220:223], v[204:207], v[64:67]
	s_setprio 0
	s_barrier
	v_lshl_add_u64 v[226:227], s[66:67], 0, v[132:133]
	v_readfirstlane_b32 s77, v135
	v_lshl_add_u64 v[228:229], v[226:227], 0, s[20:21]
	s_mov_b32 m0, s77
	v_readfirstlane_b32 s77, v136
	global_load_lds_dwordx4 v[228:229], off
	v_lshl_add_u64 v[228:229], v[226:227], 0, s[22:23]
	s_mov_b32 m0, s77
	s_nop 0
	global_load_lds_dwordx4 v[228:229], off
	v_readfirstlane_b32 s77, v137
	v_lshl_add_u64 v[228:229], v[224:225], 0, s[26:27]
	s_mov_b32 m0, s77
	v_readfirstlane_b32 s77, v138
	ds_read_b128 v[176:179], v149 offset:16384
	ds_read_b128 v[180:183], v149 offset:17408
	ds_read_b128 v[184:187], v149 offset:18432
	ds_read_b128 v[188:191], v149 offset:19456
	ds_read_b128 v[192:195], v149 offset:20480
	ds_read_b128 v[196:199], v149 offset:21504
	ds_read_b128 v[200:203], v149 offset:22528
	ds_read_b128 v[204:207], v149 offset:23552
	global_load_lds_dwordx4 v[228:229], off
	v_lshl_add_u64 v[228:229], v[224:225], 0, s[28:29]
	s_mov_b32 m0, s77
	s_nop 0
	global_load_lds_dwordx4 v[228:229], off
	v_lshl_add_u64 v[228:229], s[62:63], 0, v[132:133]
	v_readfirstlane_b32 s77, v139
	v_lshl_add_u64 v[246:247], v[228:229], 0, s[30:31]
	s_mov_b32 m0, s77
	v_readfirstlane_b32 s77, v140
	global_load_lds_dwordx4 v[246:247], off
	s_waitcnt vmcnt(5)
	s_barrier
; #define STAGE(P, BASE, br, kt) do { const char* _gb = (const char*)(BASE) + ((size_t)(br) * K + (size_t)(kt) * BK) * 2; \
;     __builtin_amdgcn_global_load_lds((const unsigned*)(_gb + loff0), (unsigned*)((char*)(P) + tid * 16), 16, 0, 0); \
;     __builtin_amdgcn_global_load_lds((const unsigned*)(_gb + (size_t)K * 128 + loff0), (unsigned*)((char*)(P) + tid * 16 + 8192), 16, 0, 0); } while (0)
; #define LDA(dst, b, h) for (int m = 0; m < 4; ++m) { \
;     dst[m][0] = *reinterpret_cast<const bf16x8*>((char*)SA(b, h) + aoff0 + m * 2048); \
;     dst[m][1] = *reinterpret_cast<const bf16x8*>((char*)SA(b, h) + aoff1 + m * 2048); }
; #define LDB(dst, b, h) for (int n = 0; n < 2; ++n) { \
;     dst[n][0] = *reinterpret_cast<const bf16x8*>((char*)SB(b, h) + boff0 + n * 256); \
;     dst[n][1] = *reinterpret_cast<const bf16x8*>((char*)SB(b, h) + boff1 + n * 256); }
; #define MMA(ai, bj, At, Btf) do { __builtin_amdgcn_s_setprio(1); \
;     for (int m = 0; m < 4; ++m) for (int n = 0; n < 2; ++n) for (int k = 0; k < 2; ++k) \
;       acc[ai][bj][m][n] = __builtin_amdgcn_mfma_f32_16x16x32_bf16(Btf[n][k], At[m][k], acc[ai][bj][m][n], 0, 0, 0); \
;     __builtin_amdgcn_s_setprio(0); } while (0)
; #define WAIT_V(n) asm volatile("s_waitcnt vmcnt(" #n ")" ::: "memory")
; #define WAIT_L(n) asm volatile("s_waitcnt lgkmcnt(" #n ")" ::: "memory")
; #define BAR __builtin_amdgcn_s_barrier()
; #define SCHED __builtin_amdgcn_sched_barrier(0)
; template <int EPI> ...
;     ...
;     BAR; WAIT_L(0); MMA(1, 0, At, B0); BAR; SCHED;
;     STAGE(SB(0, 1), Bt, bcol + HALF, t + 2);
;     WAIT_V(6); BAR; MMA(1, 1, At, B1); BAR;
;     LDB(B0, 1, 0); SCHED; LDA(At, 1, 0); STAGE(SA(0, 1), A, brow + HALF, t + 2);
;     WAIT_L(8); BAR; WAIT_L(0); MMA(0, 0, At, B0); BAR; SCHED;
;     LDB(B1, 1, 1); STAGE(SB(1, 0), Bt, bcol, t + 3);
;     BAR; WAIT_L(0); MMA(0, 1, At, B1); BAR;
	s_waitcnt lgkmcnt(0)
	s_setprio 1
	s_waitcnt lgkmcnt(0)
	v_mfma_f32_16x16x32_bf16 v[60:63], v[160:163], v[176:179], v[60:63]
	v_mfma_f32_16x16x32_bf16 v[56:59], v[164:167], v[176:179], v[56:59]
	v_mfma_f32_16x16x32_bf16 v[52:55], v[160:163], v[184:187], v[52:55]
	v_mfma_f32_16x16x32_bf16 v[48:51], v[164:167], v[184:187], v[48:51]
	v_mfma_f32_16x16x32_bf16 v[44:47], v[160:163], v[192:195], v[44:47]
	v_mfma_f32_16x16x32_bf16 v[40:43], v[164:167], v[192:195], v[40:43]
	v_mfma_f32_16x16x32_bf16 v[36:39], v[160:163], v[200:203], v[36:39]
	v_mfma_f32_16x16x32_bf16 v[32:35], v[164:167], v[200:203], v[32:35]
	v_mfma_f32_16x16x32_bf16 v[60:63], v[168:171], v[180:183], v[60:63]
	v_mfma_f32_16x16x32_bf16 v[56:59], v[172:175], v[180:183], v[56:59]
	v_mfma_f32_16x16x32_bf16 v[52:55], v[168:171], v[188:191], v[52:55]
	v_mfma_f32_16x16x32_bf16 v[48:51], v[172:175], v[188:191], v[48:51]
	v_mfma_f32_16x16x32_bf16 v[44:47], v[168:171], v[196:199], v[44:47]
	v_mfma_f32_16x16x32_bf16 v[40:43], v[172:175], v[196:199], v[40:43]
	v_mfma_f32_16x16x32_bf16 v[36:39], v[168:171], v[204:207], v[36:39]
	v_mfma_f32_16x16x32_bf16 v[32:35], v[172:175], v[204:207], v[32:35]
	s_setprio 0
	s_setprio 1
	v_mfma_f32_16x16x32_bf16 v[28:31], v[208:211], v[176:179], v[28:31]
	v_mfma_f32_16x16x32_bf16 v[24:27], v[212:215], v[176:179], v[24:27]
	v_mfma_f32_16x16x32_bf16 v[20:23], v[208:211], v[184:187], v[20:23]
	v_mfma_f32_16x16x32_bf16 v[16:19], v[212:215], v[184:187], v[16:19]
	v_mfma_f32_16x16x32_bf16 v[12:15], v[208:211], v[192:195], v[12:15]
	v_mfma_f32_16x16x32_bf16 v[8:11], v[212:215], v[192:195], v[8:11]
	v_mfma_f32_16x16x32_bf16 v[4:7], v[208:211], v[200:203], v[4:7]
	v_mfma_f32_16x16x32_bf16 v[0:3], v[212:215], v[200:203], v[0:3]
	v_mfma_f32_16x16x32_bf16 v[28:31], v[216:219], v[180:183], v[28:31]
	v_mfma_f32_16x16x32_bf16 v[24:27], v[220:223], v[180:183], v[24:27]
	v_mfma_f32_16x16x32_bf16 v[20:23], v[216:219], v[188:191], v[20:23]
	v_mfma_f32_16x16x32_bf16 v[16:19], v[220:223], v[188:191], v[16:19]
	v_mfma_f32_16x16x32_bf16 v[12:15], v[216:219], v[196:199], v[12:15]
	v_mfma_f32_16x16x32_bf16 v[8:11], v[220:223], v[196:199], v[8:11]
	v_mfma_f32_16x16x32_bf16 v[4:7], v[216:219], v[204:207], v[4:7]
	v_mfma_f32_16x16x32_bf16 v[0:3], v[220:223], v[204:207], v[0:3]
	s_setprio 0
	s_barrier
	ds_read_b128 v[160:163], v156
	ds_read_b128 v[164:167], v156 offset:256
	ds_read_b128 v[168:171], v157
	ds_read_b128 v[172:175], v157 offset:256
	v_readfirstlane_b32 s77, v141
	v_lshl_add_u64 v[208:209], v[224:225], 0, s[38:39]
	s_mov_b32 m0, s77
	v_readfirstlane_b32 s77, v142
	ds_read_b128 v[176:179], v149 offset:32768
	ds_read_b128 v[180:183], v149 offset:33792
	ds_read_b128 v[184:187], v149 offset:34816
	ds_read_b128 v[188:191], v149 offset:35840
	ds_read_b128 v[192:195], v149 offset:36864
	ds_read_b128 v[196:199], v149 offset:37888
	ds_read_b128 v[200:203], v149 offset:38912
	ds_read_b128 v[204:207], v149 offset:39936
	global_load_lds_dwordx4 v[208:209], off
	v_lshl_add_u64 v[208:209], v[224:225], 0, s[46:47]
	s_mov_b32 m0, s77
	s_nop 0
	global_load_lds_dwordx4 v[208:209], off
	s_waitcnt lgkmcnt(8)
	v_readfirstlane_b32 s77, v140
	v_lshl_add_u64 v[246:247], v[228:229], 0, s[36:37]
	s_mov_b32 m0, s77
	s_nop 0
	global_load_lds_dwordx4 v[246:247], off
	ds_read_b128 v[208:211], v158
	ds_read_b128 v[212:215], v158 offset:256
	ds_read_b128 v[216:219], v159
	ds_read_b128 v[220:223], v159 offset:256
	s_barrier
	s_waitcnt lgkmcnt(0)
	s_setprio 1
	s_waitcnt lgkmcnt(0)
	v_mfma_f32_16x16x32_bf16 v[124:127], v[160:163], v[176:179], v[124:127]
	v_mfma_f32_16x16x32_bf16 v[120:123], v[164:167], v[176:179], v[120:123]
	v_mfma_f32_16x16x32_bf16 v[116:119], v[160:163], v[184:187], v[116:119]
	v_mfma_f32_16x16x32_bf16 v[112:115], v[164:167], v[184:187], v[112:115]
	v_mfma_f32_16x16x32_bf16 v[108:111], v[160:163], v[192:195], v[108:111]
	v_mfma_f32_16x16x32_bf16 v[104:107], v[164:167], v[192:195], v[104:107]
	v_mfma_f32_16x16x32_bf16 v[100:103], v[160:163], v[200:203], v[100:103]
	v_mfma_f32_16x16x32_bf16 v[96:99], v[164:167], v[200:203], v[96:99]
	v_mfma_f32_16x16x32_bf16 v[124:127], v[168:171], v[180:183], v[124:127]
	v_mfma_f32_16x16x32_bf16 v[120:123], v[172:175], v[180:183], v[120:123]
	v_mfma_f32_16x16x32_bf16 v[116:119], v[168:171], v[188:191], v[116:119]
	v_mfma_f32_16x16x32_bf16 v[112:115], v[172:175], v[188:191], v[112:115]
	v_mfma_f32_16x16x32_bf16 v[108:111], v[168:171], v[196:199], v[108:111]
	v_mfma_f32_16x16x32_bf16 v[104:107], v[172:175], v[196:199], v[104:107]
	v_mfma_f32_16x16x32_bf16 v[100:103], v[168:171], v[204:207], v[100:103]
	v_mfma_f32_16x16x32_bf16 v[96:99], v[172:175], v[204:207], v[96:99]
	s_setprio 0
	s_waitcnt lgkmcnt(0)
	s_setprio 1
	s_waitcnt lgkmcnt(0)
	v_mfma_f32_16x16x32_bf16 v[92:95], v[208:211], v[176:179], v[92:95]
	v_mfma_f32_16x16x32_bf16 v[88:91], v[212:215], v[176:179], v[88:91]
	v_mfma_f32_16x16x32_bf16 v[84:87], v[208:211], v[184:187], v[84:87]
	v_mfma_f32_16x16x32_bf16 v[80:83], v[212:215], v[184:187], v[80:83]
	v_mfma_f32_16x16x32_bf16 v[76:79], v[208:211], v[192:195], v[76:79]
	v_mfma_f32_16x16x32_bf16 v[72:75], v[212:215], v[192:195], v[72:75]
	v_mfma_f32_16x16x32_bf16 v[68:71], v[208:211], v[200:203], v[68:71]
	v_mfma_f32_16x16x32_bf16 v[64:67], v[212:215], v[200:203], v[64:67]
	v_mfma_f32_16x16x32_bf16 v[92:95], v[216:219], v[180:183], v[92:95]
	v_mfma_f32_16x16x32_bf16 v[88:91], v[220:223], v[180:183], v[88:91]
	v_mfma_f32_16x16x32_bf16 v[84:87], v[216:219], v[188:191], v[84:87]
	v_mfma_f32_16x16x32_bf16 v[80:83], v[220:223], v[188:191], v[80:83]
	v_mfma_f32_16x16x32_bf16 v[76:79], v[216:219], v[196:199], v[76:79]
	v_mfma_f32_16x16x32_bf16 v[72:75], v[220:223], v[196:199], v[72:75]
	v_mfma_f32_16x16x32_bf16 v[68:71], v[216:219], v[204:207], v[68:71]
	v_mfma_f32_16x16x32_bf16 v[64:67], v[220:223], v[204:207], v[64:67]
	s_setprio 0
	s_barrier
; #define STAGE(P, BASE, br, kt) do { const char* _gb = (const char*)(BASE) + ((size_t)(br) * K + (size_t)(kt) * BK) * 2; \
;     __builtin_amdgcn_global_load_lds((const unsigned*)(_gb + loff0), (unsigned*)((char*)(P) + tid * 16), 16, 0, 0); \
;     __builtin_amdgcn_global_load_lds((const unsigned*)(_gb + (size_t)K * 128 + loff0), (unsigned*)((char*)(P) + tid * 16 + 8192), 16, 0, 0); } while (0)
; #define LDA(dst, b, h) for (int m = 0; m < 4; ++m) { \
;     dst[m][0] = *reinterpret_cast<const bf16x8*>((char*)SA(b, h) + aoff0 + m * 2048); \
;     dst[m][1] = *reinterpret_cast<const bf16x8*>((char*)SA(b, h) + aoff1 + m * 2048); }
; #define LDB(dst, b, h) for (int n = 0; n < 2; ++n) { \
;     dst[n][0] = *reinterpret_cast<const bf16x8*>((char*)SB(b, h) + boff0 + n * 256); \
;     dst[n][1] = *reinterpret_cast<const bf16x8*>((char*)SB(b, h) + boff1 + n * 256); }
; #define MMA(ai, bj, At, Btf) do { __builtin_amdgcn_s_setprio(1); \
;     for (int m = 0; m < 4; ++m) for (int n = 0; n < 2; ++n) for (int k = 0; k < 2; ++k) \
;       acc[ai][bj][m][n] = __builtin_amdgcn_mfma_f32_16x16x32_bf16(Btf[n][k], At[m][k], acc[ai][bj][m][n], 0, 0, 0); \
;     __builtin_amdgcn_s_setprio(0); } while (0)
; #define WAIT_V(n) asm volatile("s_waitcnt vmcnt(" #n ")" ::: "memory")
; #define WAIT_L(n) asm volatile("s_waitcnt lgkmcnt(" #n ")" ::: "memory")
; #define BAR __builtin_amdgcn_s_barrier()
; #define SCHED __builtin_amdgcn_sched_barrier(0)
; template <int EPI> ...
;     ...
;     LDA(At, 1, 1); STAGE(SA(1, 0), A, brow, t + 3);
;     BAR; WAIT_L(0); MMA(1, 0, At, B0); BAR; SCHED;
;     STAGE(SB(1, 1), Bt, bcol + HALF, t + 3);
;     WAIT_V(6); BAR; MMA(1, 1, At, B1); BAR;
;   }
;   { LDB(B0, 0, 0); LDA(At, 0, 0); STAGE(SA(1, 1), A, brow + HALF, nt - 1);
;     BAR; WAIT_L(0); MMA(0, 0, At, B0); BAR;
	v_readfirstlane_b32 s77, v143
	v_lshl_add_u64 v[230:231], v[226:227], 0, s[48:49]
	s_mov_b32 m0, s77
	v_readfirstlane_b32 s77, v144
	global_load_lds_dwordx4 v[230:231], off
	v_lshl_add_u64 v[226:227], v[226:227], 0, s[50:51]
	s_mov_b32 m0, s77
	s_nop 0
	global_load_lds_dwordx4 v[226:227], off
	v_readfirstlane_b32 s77, v145
	v_lshl_add_u64 v[226:227], v[224:225], 0, s[52:53]
	s_mov_b32 m0, s77
	v_readfirstlane_b32 s77, v146
	ds_read_b128 v[176:179], v149 offset:49152
	ds_read_b128 v[180:183], v149 offset:50176
	ds_read_b128 v[184:187], v149 offset:51200
	ds_read_b128 v[188:191], v149 offset:52224
	ds_read_b128 v[192:195], v149 offset:53248
	ds_read_b128 v[196:199], v149 offset:54272
	ds_read_b128 v[200:203], v149 offset:55296
	ds_read_b128 v[204:207], v149 offset:56320
	global_load_lds_dwordx4 v[226:227], off
	v_lshl_add_u64 v[224:225], v[224:225], 0, s[54:55]
	s_mov_b32 m0, s77
	s_nop 0
	global_load_lds_dwordx4 v[224:225], off
	v_readfirstlane_b32 s77, v147
	v_lshl_add_u64 v[246:247], v[228:229], 0, s[56:57]
	s_mov_b32 m0, s77
	v_readfirstlane_b32 s77, v148
	global_load_lds_dwordx4 v[246:247], off
	s_waitcnt vmcnt(5)
	s_barrier
	s_waitcnt lgkmcnt(0)
	s_setprio 1
	s_waitcnt lgkmcnt(0)
	v_mfma_f32_16x16x32_bf16 v[60:63], v[160:163], v[176:179], v[60:63]
	v_mfma_f32_16x16x32_bf16 v[56:59], v[164:167], v[176:179], v[56:59]
	v_mfma_f32_16x16x32_bf16 v[52:55], v[160:163], v[184:187], v[52:55]
	v_mfma_f32_16x16x32_bf16 v[48:51], v[164:167], v[184:187], v[48:51]
	v_mfma_f32_16x16x32_bf16 v[44:47], v[160:163], v[192:195], v[44:47]
	v_mfma_f32_16x16x32_bf16 v[40:43], v[164:167], v[192:195], v[40:43]
	v_mfma_f32_16x16x32_bf16 v[36:39], v[160:163], v[200:203], v[36:39]
	v_mfma_f32_16x16x32_bf16 v[32:35], v[164:167], v[200:203], v[32:35]
	v_mfma_f32_16x16x32_bf16 v[60:63], v[168:171], v[180:183], v[60:63]
	v_mfma_f32_16x16x32_bf16 v[56:59], v[172:175], v[180:183], v[56:59]
	v_mfma_f32_16x16x32_bf16 v[52:55], v[168:171], v[188:191], v[52:55]
	v_mfma_f32_16x16x32_bf16 v[48:51], v[172:175], v[188:191], v[48:51]
	v_mfma_f32_16x16x32_bf16 v[44:47], v[168:171], v[196:199], v[44:47]
	v_mfma_f32_16x16x32_bf16 v[40:43], v[172:175], v[196:199], v[40:43]
	v_mfma_f32_16x16x32_bf16 v[36:39], v[168:171], v[204:207], v[36:39]
	v_mfma_f32_16x16x32_bf16 v[32:35], v[172:175], v[204:207], v[32:35]
	s_setprio 0
	s_setprio 1
	v_mfma_f32_16x16x32_bf16 v[28:31], v[208:211], v[176:179], v[28:31]
	v_mfma_f32_16x16x32_bf16 v[24:27], v[212:215], v[176:179], v[24:27]
	v_mfma_f32_16x16x32_bf16 v[20:23], v[208:211], v[184:187], v[20:23]
	v_mfma_f32_16x16x32_bf16 v[16:19], v[212:215], v[184:187], v[16:19]
	v_mfma_f32_16x16x32_bf16 v[12:15], v[208:211], v[192:195], v[12:15]
	v_mfma_f32_16x16x32_bf16 v[8:11], v[212:215], v[192:195], v[8:11]
	v_mfma_f32_16x16x32_bf16 v[4:7], v[208:211], v[200:203], v[4:7]
	v_mfma_f32_16x16x32_bf16 v[0:3], v[212:215], v[200:203], v[0:3]
	v_mfma_f32_16x16x32_bf16 v[28:31], v[216:219], v[180:183], v[28:31]
	v_mfma_f32_16x16x32_bf16 v[24:27], v[220:223], v[180:183], v[24:27]
	v_mfma_f32_16x16x32_bf16 v[20:23], v[216:219], v[188:191], v[20:23]
	v_mfma_f32_16x16x32_bf16 v[16:19], v[220:223], v[188:191], v[16:19]
	v_mfma_f32_16x16x32_bf16 v[12:15], v[216:219], v[196:199], v[12:15]
	v_mfma_f32_16x16x32_bf16 v[8:11], v[220:223], v[196:199], v[8:11]
	v_mfma_f32_16x16x32_bf16 v[4:7], v[216:219], v[204:207], v[4:7]
	v_mfma_f32_16x16x32_bf16 v[0:3], v[220:223], v[204:207], v[0:3]
	s_setprio 0
	s_add_i32 s76, s76, 2
	s_add_u32 s62, s62, 0x100
	s_addc_u32 s63, s63, 0
	s_add_u32 s64, s64, 0x100
	s_addc_u32 s65, s65, 0
	s_add_u32 s66, s66, 0x100
	s_addc_u32 s67, s67, 0
	s_cmpk_lt_u32 s76, 0x54
	s_barrier
	s_cbranch_scc1 .LBB0_324
	v_readfirstlane_b32 s77, v148
	v_lshl_add_u64 v[246:247], v[228:229], 0, s[58:59]
	s_mov_b32 m0, s77
	s_nop 0
	global_load_lds_dwordx4 v[246:247], off
	s_add_u32 s62, s70, s75
	s_addc_u32 s63, s71, s74
	v_lshl_add_u64 v[208:209], s[62:63], 0, v[128:129]
	v_readfirstlane_b32 s62, v150
	s_mov_b32 m0, s62
	v_readfirstlane_b32 s62, v151
	ds_read_b128 v[160:163], v152
	ds_read_b128 v[164:167], v152 offset:256
	ds_read_b128 v[168:171], v153
	ds_read_b128 v[172:175], v153 offset:256
	ds_read_b128 v[176:179], v149
	ds_read_b128 v[180:183], v149 offset:1024
	ds_read_b128 v[184:187], v149 offset:2048
	ds_read_b128 v[188:191], v149 offset:3072
	ds_read_b128 v[192:195], v149 offset:4096
	ds_read_b128 v[196:199], v149 offset:5120
	ds_read_b128 v[200:203], v149 offset:6144
	ds_read_b128 v[204:207], v149 offset:7168
	global_load_lds_dwordx4 v[208:209], off
	v_lshl_add_u64 v[208:209], v[208:209], 0, s[8:9]
	s_mov_b32 m0, s62
	s_nop 0
	global_load_lds_dwordx4 v[208:209], off
	s_barrier
	s_waitcnt lgkmcnt(0)
	s_setprio 1
	s_waitcnt lgkmcnt(0)
	v_mfma_f32_16x16x32_bf16 v[124:127], v[160:163], v[176:179], v[124:127]
	v_mfma_f32_16x16x32_bf16 v[116:119], v[160:163], v[184:187], v[116:119]
	v_mfma_f32_16x16x32_bf16 v[108:111], v[160:163], v[192:195], v[108:111]
	v_mfma_f32_16x16x32_bf16 v[100:103], v[160:163], v[200:203], v[100:103]
	v_mfma_f32_16x16x32_bf16 v[96:99], v[164:167], v[200:203], v[96:99]
	v_mfma_f32_16x16x32_bf16 v[124:127], v[168:171], v[180:183], v[124:127]
	v_mfma_f32_16x16x32_bf16 v[120:123], v[164:167], v[176:179], v[120:123]
	v_mfma_f32_16x16x32_bf16 v[116:119], v[168:171], v[188:191], v[116:119]
	v_mfma_f32_16x16x32_bf16 v[112:115], v[164:167], v[184:187], v[112:115]
	v_mfma_f32_16x16x32_bf16 v[108:111], v[168:171], v[196:199], v[108:111]
	v_mfma_f32_16x16x32_bf16 v[104:107], v[164:167], v[192:195], v[104:107]
	v_mfma_f32_16x16x32_bf16 v[100:103], v[168:171], v[204:207], v[100:103]
	v_mfma_f32_16x16x32_bf16 v[96:99], v[172:175], v[204:207], v[96:99]
	v_mfma_f32_16x16x32_bf16 v[208:211], v[172:175], v[180:183], v[120:123]
	v_mfma_f32_16x16x32_bf16 v[212:215], v[172:175], v[188:191], v[112:115]
	v_mfma_f32_16x16x32_bf16 v[216:219], v[172:175], v[196:199], v[104:107]
	s_setprio 0
	s_barrier
; #define LDA(dst, b, h) for (int m = 0; m < 4; ++m) { \
;     dst[m][0] = *reinterpret_cast<const bf16x8*>((char*)SA(b, h) + aoff0 + m * 2048); \
;     dst[m][1] = *reinterpret_cast<const bf16x8*>((char*)SA(b, h) + aoff1 + m * 2048); }
; #define LDB(dst, b, h) for (int n = 0; n < 2; ++n) { \
;     dst[n][0] = *reinterpret_cast<const bf16x8*>((char*)SB(b, h) + boff0 + n * 256); \
;     dst[n][1] = *reinterpret_cast<const bf16x8*>((char*)SB(b, h) + boff1 + n * 256); }
; #define MMA(ai, bj, At, Btf) do { __builtin_amdgcn_s_setprio(1); \
;     for (int m = 0; m < 4; ++m) for (int n = 0; n < 2; ++n) for (int k = 0; k < 2; ++k) \
;       acc[ai][bj][m][n] = __builtin_amdgcn_mfma_f32_16x16x32_bf16(Btf[n][k], At[m][k], acc[ai][bj][m][n], 0, 0, 0); \
;     __builtin_amdgcn_s_setprio(0); } while (0)
; #define WAIT_V(n) asm volatile("s_waitcnt vmcnt(" #n ")" ::: "memory")
; #define WAIT_L(n) asm volatile("s_waitcnt lgkmcnt(" #n ")" ::: "memory")
; #define BAR __builtin_amdgcn_s_barrier()
; template <int EPI> ...
;     ...
;     BAR; WAIT_L(0); MMA(0, 0, At, B0); BAR;
;     LDB(B1, 0, 1); BAR; WAIT_L(0); MMA(0, 1, At, B1); BAR;
;     LDA(At, 0, 1); WAIT_V(4); BAR; WAIT_L(0); MMA(1, 0, At, B0); MMA(1, 1, At, B1); BAR; }
;   { LDB(B0, 1, 0); LDA(At, 1, 0); WAIT_V(2); BAR; WAIT_L(0); MMA(0, 0, At, B0); BAR;
	s_nop 0
	ds_read_b128 v[104:107], v154
	ds_read_b128 v[112:115], v154 offset:256
	ds_read_b128 v[120:123], v155
	ds_read_b128 v[220:223], v155 offset:256
	s_barrier
	s_waitcnt lgkmcnt(0)
	s_setprio 1
	s_waitcnt lgkmcnt(0)
	v_mfma_f32_16x16x32_bf16 v[84:87], v[104:107], v[184:187], v[84:87]
	v_mfma_f32_16x16x32_bf16 v[76:79], v[104:107], v[192:195], v[76:79]
	v_mfma_f32_16x16x32_bf16 v[72:75], v[112:115], v[192:195], v[72:75]
	v_mfma_f32_16x16x32_bf16 v[92:95], v[104:107], v[176:179], v[92:95]
	v_mfma_f32_16x16x32_bf16 v[88:91], v[112:115], v[176:179], v[88:91]
	v_mfma_f32_16x16x32_bf16 v[84:87], v[120:123], v[188:191], v[84:87]
	v_mfma_f32_16x16x32_bf16 v[80:83], v[112:115], v[184:187], v[80:83]
	v_mfma_f32_16x16x32_bf16 v[76:79], v[120:123], v[196:199], v[76:79]
	v_mfma_f32_16x16x32_bf16 v[72:75], v[220:223], v[196:199], v[72:75]
	v_mfma_f32_16x16x32_bf16 v[68:71], v[104:107], v[200:203], v[68:71]
	v_mfma_f32_16x16x32_bf16 v[64:67], v[112:115], v[200:203], v[64:67]
	v_mfma_f32_16x16x32_bf16 v[224:227], v[120:123], v[180:183], v[92:95]
	v_mfma_f32_16x16x32_bf16 v[176:179], v[220:223], v[180:183], v[88:91]
	v_mfma_f32_16x16x32_bf16 v[180:183], v[220:223], v[188:191], v[80:83]
	v_mfma_f32_16x16x32_bf16 v[184:187], v[120:123], v[204:207], v[68:71]
	v_mfma_f32_16x16x32_bf16 v[188:191], v[220:223], v[204:207], v[64:67]
	s_setprio 0
	s_barrier
	s_nop 0
	ds_read_b128 v[64:67], v149 offset:16384
	ds_read_b128 v[68:71], v149 offset:17408
	ds_read_b128 v[80:83], v149 offset:18432
	ds_read_b128 v[88:91], v149 offset:19456
	ds_read_b128 v[92:95], v149 offset:20480
	ds_read_b128 v[192:195], v149 offset:21504
	ds_read_b128 v[196:199], v149 offset:22528
	ds_read_b128 v[200:203], v149 offset:23552
	s_waitcnt vmcnt(4)
	s_barrier
	s_waitcnt lgkmcnt(0)
	s_setprio 1
	s_waitcnt lgkmcnt(0)
	v_mfma_f32_16x16x32_bf16 v[52:55], v[160:163], v[80:83], v[52:55]
	v_mfma_f32_16x16x32_bf16 v[44:47], v[160:163], v[92:95], v[44:47]
	v_mfma_f32_16x16x32_bf16 v[36:39], v[160:163], v[196:199], v[36:39]
	v_mfma_f32_16x16x32_bf16 v[60:63], v[160:163], v[64:67], v[60:63]
	v_mfma_f32_16x16x32_bf16 v[56:59], v[164:167], v[64:67], v[56:59]
	v_mfma_f32_16x16x32_bf16 v[52:55], v[168:171], v[88:91], v[52:55]
	v_mfma_f32_16x16x32_bf16 v[48:51], v[164:167], v[80:83], v[48:51]
	v_mfma_f32_16x16x32_bf16 v[44:47], v[168:171], v[192:195], v[44:47]
	v_mfma_f32_16x16x32_bf16 v[40:43], v[164:167], v[92:95], v[40:43]
	v_mfma_f32_16x16x32_bf16 v[36:39], v[168:171], v[200:203], v[36:39]
	v_mfma_f32_16x16x32_bf16 v[32:35], v[164:167], v[196:199], v[32:35]
	v_mfma_f32_16x16x32_bf16 v[204:207], v[168:171], v[68:71], v[60:63]
	v_mfma_f32_16x16x32_bf16 v[228:231], v[172:175], v[68:71], v[56:59]
	v_mfma_f32_16x16x32_bf16 v[232:235], v[172:175], v[88:91], v[48:51]
	v_mfma_f32_16x16x32_bf16 v[236:239], v[172:175], v[192:195], v[40:43]
	v_mfma_f32_16x16x32_bf16 v[160:163], v[172:175], v[200:203], v[32:35]
	s_setprio 0
	s_setprio 1
	v_mfma_f32_16x16x32_bf16 v[28:31], v[104:107], v[64:67], v[28:31]
	v_mfma_f32_16x16x32_bf16 v[20:23], v[104:107], v[80:83], v[20:23]
	v_mfma_f32_16x16x32_bf16 v[12:15], v[104:107], v[92:95], v[12:15]
	v_mfma_f32_16x16x32_bf16 v[4:7], v[104:107], v[196:199], v[4:7]
	v_mfma_f32_16x16x32_bf16 v[28:31], v[120:123], v[68:71], v[28:31]
	v_mfma_f32_16x16x32_bf16 v[24:27], v[112:115], v[64:67], v[24:27]
	v_mfma_f32_16x16x32_bf16 v[20:23], v[120:123], v[88:91], v[20:23]
	v_mfma_f32_16x16x32_bf16 v[16:19], v[112:115], v[80:83], v[16:19]
	v_mfma_f32_16x16x32_bf16 v[12:15], v[120:123], v[192:195], v[12:15]
	v_mfma_f32_16x16x32_bf16 v[8:11], v[112:115], v[92:95], v[8:11]
	v_mfma_f32_16x16x32_bf16 v[4:7], v[120:123], v[200:203], v[4:7]
	v_mfma_f32_16x16x32_bf16 v[0:3], v[112:115], v[196:199], v[0:3]
	v_mfma_f32_16x16x32_bf16 v[164:167], v[220:223], v[68:71], v[24:27]
	v_mfma_f32_16x16x32_bf16 v[168:171], v[220:223], v[88:91], v[16:19]
	v_mfma_f32_16x16x32_bf16 v[172:175], v[220:223], v[192:195], v[8:11]
	v_mfma_f32_16x16x32_bf16 v[192:195], v[220:223], v[200:203], v[0:3]
	s_setprio 0
	s_barrier
	s_nop 1
	ds_read_b128 v[0:3], v156
	ds_read_b128 v[8:11], v156 offset:256
	ds_read_b128 v[16:19], v157
	ds_read_b128 v[24:27], v157 offset:256
	ds_read_b128 v[32:35], v149 offset:32768
	ds_read_b128 v[40:43], v149 offset:33792
	ds_read_b128 v[48:51], v149 offset:34816
	ds_read_b128 v[56:59], v149 offset:35840
	ds_read_b128 v[60:63], v149 offset:36864
	ds_read_b128 v[68:71], v149 offset:37888
	ds_read_b128 v[196:199], v149 offset:38912
	ds_read_b128 v[200:203], v149 offset:39936
	s_waitcnt vmcnt(2)
	s_barrier
; #define LDA(dst, b, h) for (int m = 0; m < 4; ++m) { \
;     dst[m][0] = *reinterpret_cast<const bf16x8*>((char*)SA(b, h) + aoff0 + m * 2048); \
;     dst[m][1] = *reinterpret_cast<const bf16x8*>((char*)SA(b, h) + aoff1 + m * 2048); }
; #define LDB(dst, b, h) for (int n = 0; n < 2; ++n) { \
;     dst[n][0] = *reinterpret_cast<const bf16x8*>((char*)SB(b, h) + boff0 + n * 256); \
;     dst[n][1] = *reinterpret_cast<const bf16x8*>((char*)SB(b, h) + boff1 + n * 256); }
; #define MMA(ai, bj, At, Btf) do { __builtin_amdgcn_s_setprio(1); \
;     for (int m = 0; m < 4; ++m) for (int n = 0; n < 2; ++n) for (int k = 0; k < 2; ++k) \
;       acc[ai][bj][m][n] = __builtin_amdgcn_mfma_f32_16x16x32_bf16(Btf[n][k], At[m][k], acc[ai][bj][m][n], 0, 0, 0); \
;     __builtin_amdgcn_s_setprio(0); } while (0)
; #define WAIT_V(n) asm volatile("s_waitcnt vmcnt(" #n ")" ::: "memory")
; #define WAIT_L(n) asm volatile("s_waitcnt lgkmcnt(" #n ")" ::: "memory")
; #define BAR __builtin_amdgcn_s_barrier()
; template <int EPI> ...
;     ...
;   { LDB(B0, 1, 0); LDA(At, 1, 0); WAIT_V(2); BAR; WAIT_L(0); MMA(0, 0, At, B0); BAR;
;     LDB(B1, 1, 1); WAIT_V(0); BAR; WAIT_L(0); MMA(0, 1, At, B1); BAR;
;     LDA(At, 1, 1); BAR; WAIT_L(0); MMA(1, 0, At, B0); MMA(1, 1, At, B1); BAR; }
;   if (wr == 0) BAR;
	s_waitcnt lgkmcnt(0)
	s_setprio 1
	s_waitcnt lgkmcnt(0)
	v_mfma_f32_16x16x32_bf16 v[64:67], v[0:3], v[32:35], v[124:127]
	v_mfma_f32_16x16x32_bf16 v[120:123], v[16:19], v[40:43], v[64:67]
	v_mfma_f32_16x16x32_bf16 v[64:67], v[8:11], v[32:35], v[208:211]
	v_mfma_f32_16x16x32_bf16 v[124:127], v[24:27], v[40:43], v[64:67]
	v_mfma_f32_16x16x32_bf16 v[64:67], v[0:3], v[48:51], v[116:119]
	v_mfma_f32_16x16x32_bf16 v[112:115], v[16:19], v[56:59], v[64:67]
	v_mfma_f32_16x16x32_bf16 v[64:67], v[8:11], v[48:51], v[212:215]
	v_mfma_f32_16x16x32_bf16 v[116:119], v[24:27], v[56:59], v[64:67]
	v_mfma_f32_16x16x32_bf16 v[64:67], v[0:3], v[60:63], v[108:111]
	v_mfma_f32_16x16x32_bf16 v[104:107], v[16:19], v[68:71], v[64:67]
	v_mfma_f32_16x16x32_bf16 v[64:67], v[8:11], v[60:63], v[216:219]
	v_mfma_f32_16x16x32_bf16 v[108:111], v[24:27], v[68:71], v[64:67]
	v_mfma_f32_16x16x32_bf16 v[64:67], v[0:3], v[196:199], v[100:103]
	v_mfma_f32_16x16x32_bf16 v[88:91], v[16:19], v[200:203], v[64:67]
	v_mfma_f32_16x16x32_bf16 v[64:67], v[8:11], v[196:199], v[96:99]
	v_mfma_f32_16x16x32_bf16 v[92:95], v[24:27], v[200:203], v[64:67]
	s_setprio 0
	s_barrier
	ds_read_b128 v[208:211], v158
	ds_read_b128 v[212:215], v158 offset:256
	ds_read_b128 v[216:219], v159
	ds_read_b128 v[220:223], v159 offset:256
	s_waitcnt vmcnt(0)
	s_barrier
	s_waitcnt lgkmcnt(0)
	s_setprio 1
	s_waitcnt lgkmcnt(0)
	v_mfma_f32_16x16x32_bf16 v[64:67], v[208:211], v[32:35], v[224:227]
	v_mfma_f32_16x16x32_bf16 v[32:35], v[212:215], v[32:35], v[176:179]
	v_mfma_f32_16x16x32_bf16 v[100:103], v[220:223], v[40:43], v[32:35]
	v_mfma_f32_16x16x32_bf16 v[32:35], v[208:211], v[48:51], v[84:87]
	v_mfma_f32_16x16x32_bf16 v[80:83], v[216:219], v[56:59], v[32:35]
	v_mfma_f32_16x16x32_bf16 v[32:35], v[212:215], v[48:51], v[180:183]
	v_mfma_f32_16x16x32_bf16 v[84:87], v[220:223], v[56:59], v[32:35]
	v_mfma_f32_16x16x32_bf16 v[32:35], v[208:211], v[60:63], v[76:79]
	v_mfma_f32_16x16x32_bf16 v[96:99], v[216:219], v[40:43], v[64:67]
	v_mfma_f32_16x16x32_bf16 v[64:67], v[216:219], v[68:71], v[32:35]
	v_mfma_f32_16x16x32_bf16 v[32:35], v[212:215], v[60:63], v[72:75]
	v_mfma_f32_16x16x32_bf16 v[68:71], v[220:223], v[68:71], v[32:35]
	v_mfma_f32_16x16x32_bf16 v[32:35], v[208:211], v[196:199], v[184:187]
	v_mfma_f32_16x16x32_bf16 v[56:59], v[216:219], v[200:203], v[32:35]
	v_mfma_f32_16x16x32_bf16 v[32:35], v[212:215], v[196:199], v[188:191]
	v_mfma_f32_16x16x32_bf16 v[60:63], v[220:223], v[200:203], v[32:35]
	s_setprio 0
	s_barrier
	ds_read_b128 v[176:179], v149 offset:49152
	ds_read_b128 v[180:183], v149 offset:50176
	ds_read_b128 v[184:187], v149 offset:51200
	ds_read_b128 v[188:191], v149 offset:52224
	ds_read_b128 v[196:199], v149 offset:53248
	ds_read_b128 v[200:203], v149 offset:54272
	ds_read_b128 v[224:227], v149 offset:55296
	ds_read_b128 v[240:243], v149 offset:56320
	s_barrier
	s_waitcnt lgkmcnt(0)
	s_setprio 1
	s_waitcnt lgkmcnt(0)
	v_mfma_f32_16x16x32_bf16 v[32:35], v[0:3], v[176:179], v[204:207]
	v_mfma_f32_16x16x32_bf16 v[72:75], v[16:19], v[180:183], v[32:35]
	v_mfma_f32_16x16x32_bf16 v[32:35], v[8:11], v[176:179], v[228:231]
	v_mfma_f32_16x16x32_bf16 v[76:79], v[24:27], v[180:183], v[32:35]
	v_mfma_f32_16x16x32_bf16 v[32:35], v[0:3], v[184:187], v[52:55]
	v_mfma_f32_16x16x32_bf16 v[48:51], v[16:19], v[188:191], v[32:35]
	v_mfma_f32_16x16x32_bf16 v[32:35], v[8:11], v[184:187], v[232:235]
	v_mfma_f32_16x16x32_bf16 v[52:55], v[24:27], v[188:191], v[32:35]
	v_mfma_f32_16x16x32_bf16 v[32:35], v[0:3], v[196:199], v[44:47]
	v_mfma_f32_16x16x32_bf16 v[40:43], v[16:19], v[200:203], v[32:35]
	v_mfma_f32_16x16x32_bf16 v[32:35], v[8:11], v[196:199], v[236:239]
	v_mfma_f32_16x16x32_bf16 v[0:3], v[0:3], v[224:227], v[36:39]
	v_mfma_f32_16x16x32_bf16 v[44:47], v[24:27], v[200:203], v[32:35]
	v_mfma_f32_16x16x32_bf16 v[32:35], v[16:19], v[240:243], v[0:3]
	v_mfma_f32_16x16x32_bf16 v[0:3], v[8:11], v[224:227], v[160:163]
	v_mfma_f32_16x16x32_bf16 v[36:39], v[24:27], v[240:243], v[0:3]
	s_setprio 0
	s_setprio 1
	v_mfma_f32_16x16x32_bf16 v[0:3], v[208:211], v[176:179], v[28:31]
	v_mfma_f32_16x16x32_bf16 v[24:27], v[216:219], v[180:183], v[0:3]
	v_mfma_f32_16x16x32_bf16 v[0:3], v[212:215], v[176:179], v[164:167]
	v_mfma_f32_16x16x32_bf16 v[28:31], v[220:223], v[180:183], v[0:3]
	v_mfma_f32_16x16x32_bf16 v[0:3], v[208:211], v[184:187], v[20:23]
	v_mfma_f32_16x16x32_bf16 v[16:19], v[216:219], v[188:191], v[0:3]
	v_mfma_f32_16x16x32_bf16 v[0:3], v[212:215], v[184:187], v[168:171]
	v_mfma_f32_16x16x32_bf16 v[20:23], v[220:223], v[188:191], v[0:3]
	v_mfma_f32_16x16x32_bf16 v[0:3], v[208:211], v[196:199], v[12:15]
	v_mfma_f32_16x16x32_bf16 v[8:11], v[216:219], v[200:203], v[0:3]
	v_mfma_f32_16x16x32_bf16 v[0:3], v[212:215], v[196:199], v[172:175]
	v_mfma_f32_16x16x32_bf16 v[12:15], v[220:223], v[200:203], v[0:3]
	v_mfma_f32_16x16x32_bf16 v[0:3], v[208:211], v[224:227], v[4:7]
	v_mfma_f32_16x16x32_bf16 v[4:7], v[212:215], v[224:227], v[192:195]
	v_mfma_f32_16x16x32_bf16 v[0:3], v[216:219], v[240:243], v[0:3]
	v_mfma_f32_16x16x32_bf16 v[4:7], v[220:223], v[240:243], v[4:7]
	s_setprio 0
	s_barrier
	s_and_saveexec_b64 s[62:63], s[2:3]
	s_cbranch_execz .LBB0_318
	s_barrier
	s_branch .LBB0_318

; #define STAGE(P, BASE, br, kt) do { const char* _gb = (const char*)(BASE) + ((size_t)(br) * K + (size_t)(kt) * BK) * 2; \
;     __builtin_amdgcn_global_load_lds((const unsigned*)(_gb + loff0), (unsigned*)((char*)(P) + tid * 16), 16, 0, 0); \
;     __builtin_amdgcn_global_load_lds((const unsigned*)(_gb + (size_t)K * 128 + loff0), (unsigned*)((char*)(P) + tid * 16 + 8192), 16, 0, 0); } while (0)
; #define LDA(dst, b, h) for (int m = 0; m < 4; ++m) { \
;     dst[m][0] = *reinterpret_cast<const bf16x8*>((char*)SA(b, h) + aoff0 + m * 2048); \
;     dst[m][1] = *reinterpret_cast<const bf16x8*>((char*)SA(b, h) + aoff1 + m * 2048); }
; #define LDB(dst, b, h) for (int n = 0; n < 2; ++n) { \
;     dst[n][0] = *reinterpret_cast<const bf16x8*>((char*)SB(b, h) + boff0 + n * 256); \
;     dst[n][1] = *reinterpret_cast<const bf16x8*>((char*)SB(b, h) + boff1 + n * 256); }
; #define MMA(ai, bj, At, Btf) do { __builtin_amdgcn_s_setprio(1); \
;     for (int m = 0; m < 4; ++m) for (int n = 0; n < 2; ++n) for (int k = 0; k < 2; ++k) \
;       acc[ai][bj][m][n] = __builtin_amdgcn_mfma_f32_16x16x32_bf16(Btf[n][k], At[m][k], acc[ai][bj][m][n], 0, 0, 0); \
;     __builtin_amdgcn_s_setprio(0); } while (0)
; #define WAIT_V(n) asm volatile("s_waitcnt vmcnt(" #n ")" ::: "memory")
; #define WAIT_L(n) asm volatile("s_waitcnt lgkmcnt(" #n ")" ::: "memory")
; #define BAR __builtin_amdgcn_s_barrier()
; template <int EPI> ...
;     ...
;   for (int t = 0; t < nt - 2; t += 2) {
;     LDB(B0, 0, 0); SCHED; LDA(At, 0, 0); STAGE(SA(1, 1), A, brow + HALF, t + 1);
;     WAIT_L(8); BAR; WAIT_L(0); MMA(0, 0, At, B0); BAR; SCHED;
;     LDB(B1, 0, 1); STAGE(SB(0, 0), Bt, bcol, t + 2);
;     BAR; WAIT_L(0); MMA(0, 1, At, B1); BAR;
;     LDA(At, 0, 1); STAGE(SA(0, 0), A, brow, t + 2);
;     BAR; WAIT_L(0); MMA(1, 0, At, B0); BAR; SCHED;
;     STAGE(SB(0, 1), Bt, bcol + HALF, t + 2);
;     WAIT_V(6); BAR; MMA(1, 1, At, B1); BAR;
;     LDB(B0, 1, 0); SCHED; LDA(At, 1, 0); STAGE(SA(0, 1), A, brow + HALF, t + 2);
;     WAIT_L(8); BAR; WAIT_L(0); MMA(0, 0, At, B0); BAR; SCHED;
;     LDB(B1, 1, 1); STAGE(SB(1, 0), Bt, bcol, t + 3);
;     BAR; WAIT_L(0); MMA(0, 1, At, B1); BAR;
;     LDA(At, 1, 1); STAGE(SA(1, 0), A, brow, t + 3);
;     BAR; WAIT_L(0); MMA(1, 0, At, B0); BAR; SCHED;
;     STAGE(SB(1, 1), Bt, bcol + HALF, t + 3);
;     WAIT_V(6); BAR; MMA(1, 1, At, B1); BAR;
;   }
.LBB0_411:
	ds_read_b128 v[160:163], v152
	ds_read_b128 v[164:167], v152 offset:256
	ds_read_b128 v[168:171], v153
	ds_read_b128 v[172:175], v153 offset:256
	v_lshl_add_u64 v[224:225], s[68:69], 0, v[132:133]
	v_readfirstlane_b32 s70, v150
	v_lshl_add_u64 v[208:209], v[224:225], 0, s[16:17]
	s_mov_b32 m0, s70
	v_readfirstlane_b32 s70, v151
	ds_read_b128 v[176:179], v149
	ds_read_b128 v[180:183], v149 offset:1024
	ds_read_b128 v[184:187], v149 offset:2048
	ds_read_b128 v[188:191], v149 offset:3072
	ds_read_b128 v[192:195], v149 offset:4096
	ds_read_b128 v[196:199], v149 offset:5120
	ds_read_b128 v[200:203], v149 offset:6144
	ds_read_b128 v[204:207], v149 offset:7168
	global_load_lds_dwordx4 v[208:209], off
	v_lshl_add_u64 v[208:209], v[224:225], 0, s[18:19]
	s_mov_b32 m0, s70
	s_nop 0
	global_load_lds_dwordx4 v[208:209], off
	s_waitcnt lgkmcnt(8)
	v_readfirstlane_b32 s70, v148
	v_lshl_add_u64 v[246:247], v[226:227], 0, s[58:59]
	s_mov_b32 m0, s70
	s_nop 0
	global_load_lds_dwordx4 v[246:247], off
	ds_read_b128 v[208:211], v154
	ds_read_b128 v[212:215], v154 offset:256
	ds_read_b128 v[216:219], v155
	ds_read_b128 v[220:223], v155 offset:256
	s_barrier
	s_waitcnt lgkmcnt(0)
	s_setprio 1
	s_waitcnt lgkmcnt(0)
	v_mfma_f32_16x16x32_bf16 v[124:127], v[160:163], v[176:179], v[124:127]
	v_mfma_f32_16x16x32_bf16 v[120:123], v[164:167], v[176:179], v[120:123]
	v_mfma_f32_16x16x32_bf16 v[116:119], v[160:163], v[184:187], v[116:119]
	v_mfma_f32_16x16x32_bf16 v[112:115], v[164:167], v[184:187], v[112:115]
	v_mfma_f32_16x16x32_bf16 v[108:111], v[160:163], v[192:195], v[108:111]
	v_mfma_f32_16x16x32_bf16 v[104:107], v[164:167], v[192:195], v[104:107]
	v_mfma_f32_16x16x32_bf16 v[100:103], v[160:163], v[200:203], v[100:103]
	v_mfma_f32_16x16x32_bf16 v[96:99], v[164:167], v[200:203], v[96:99]
	v_mfma_f32_16x16x32_bf16 v[124:127], v[168:171], v[180:183], v[124:127]
	v_mfma_f32_16x16x32_bf16 v[120:123], v[172:175], v[180:183], v[120:123]
	v_mfma_f32_16x16x32_bf16 v[116:119], v[168:171], v[188:191], v[116:119]
	v_mfma_f32_16x16x32_bf16 v[112:115], v[172:175], v[188:191], v[112:115]
	v_mfma_f32_16x16x32_bf16 v[108:111], v[168:171], v[196:199], v[108:111]
	v_mfma_f32_16x16x32_bf16 v[104:107], v[172:175], v[196:199], v[104:107]
	v_mfma_f32_16x16x32_bf16 v[100:103], v[168:171], v[204:207], v[100:103]
	v_mfma_f32_16x16x32_bf16 v[96:99], v[172:175], v[204:207], v[96:99]
	s_setprio 0
	s_waitcnt lgkmcnt(0)
	s_setprio 1
	s_waitcnt lgkmcnt(0)
	v_mfma_f32_16x16x32_bf16 v[92:95], v[208:211], v[176:179], v[92:95]
	v_mfma_f32_16x16x32_bf16 v[88:91], v[212:215], v[176:179], v[88:91]
	v_mfma_f32_16x16x32_bf16 v[84:87], v[208:211], v[184:187], v[84:87]
	v_mfma_f32_16x16x32_bf16 v[80:83], v[212:215], v[184:187], v[80:83]
	v_mfma_f32_16x16x32_bf16 v[76:79], v[208:211], v[192:195], v[76:79]
	v_mfma_f32_16x16x32_bf16 v[72:75], v[212:215], v[192:195], v[72:75]
	v_mfma_f32_16x16x32_bf16 v[68:71], v[208:211], v[200:203], v[68:71]
	v_mfma_f32_16x16x32_bf16 v[64:67], v[212:215], v[200:203], v[64:67]
	v_mfma_f32_16x16x32_bf16 v[92:95], v[216:219], v[180:183], v[92:95]
	v_mfma_f32_16x16x32_bf16 v[88:91], v[220:223], v[180:183], v[88:91]
	v_mfma_f32_16x16x32_bf16 v[84:87], v[216:219], v[188:191], v[84:87]
	v_mfma_f32_16x16x32_bf16 v[80:83], v[220:223], v[188:191], v[80:83]
	v_mfma_f32_16x16x32_bf16 v[76:79], v[216:219], v[196:199], v[76:79]
	v_mfma_f32_16x16x32_bf16 v[72:75], v[220:223], v[196:199], v[72:75]
	v_mfma_f32_16x16x32_bf16 v[68:71], v[216:219], v[204:207], v[68:71]
	v_mfma_f32_16x16x32_bf16 v[64:67], v[220:223], v[204:207], v[64:67]
	s_setprio 0
	s_barrier
	v_lshl_add_u64 v[226:227], s[66:67], 0, v[132:133]
	v_readfirstlane_b32 s70, v135
	v_lshl_add_u64 v[228:229], v[226:227], 0, s[20:21]
	s_mov_b32 m0, s70
	v_readfirstlane_b32 s70, v136
	global_load_lds_dwordx4 v[228:229], off
	v_lshl_add_u64 v[228:229], v[226:227], 0, s[22:23]
	s_mov_b32 m0, s70
	s_nop 0
	global_load_lds_dwordx4 v[228:229], off
	v_readfirstlane_b32 s70, v137
	v_lshl_add_u64 v[228:229], v[224:225], 0, s[26:27]
	s_mov_b32 m0, s70
	v_readfirstlane_b32 s70, v138
	ds_read_b128 v[176:179], v149 offset:16384
	ds_read_b128 v[180:183], v149 offset:17408
	ds_read_b128 v[184:187], v149 offset:18432
	ds_read_b128 v[188:191], v149 offset:19456
	ds_read_b128 v[192:195], v149 offset:20480
	ds_read_b128 v[196:199], v149 offset:21504
	ds_read_b128 v[200:203], v149 offset:22528
	ds_read_b128 v[204:207], v149 offset:23552
	global_load_lds_dwordx4 v[228:229], off
	v_lshl_add_u64 v[228:229], v[224:225], 0, s[28:29]
	s_mov_b32 m0, s70
	s_nop 0
	global_load_lds_dwordx4 v[228:229], off
	v_readfirstlane_b32 s70, v139
	v_lshl_add_u64 v[246:247], v[226:227], 0, s[30:31]
	s_mov_b32 m0, s70
	v_readfirstlane_b32 s70, v140
	global_load_lds_dwordx4 v[246:247], off
	s_waitcnt vmcnt(5)
	s_barrier
; #define STAGE(P, BASE, br, kt) do { const char* _gb = (const char*)(BASE) + ((size_t)(br) * K + (size_t)(kt) * BK) * 2; \
;     __builtin_amdgcn_global_load_lds((const unsigned*)(_gb + loff0), (unsigned*)((char*)(P) + tid * 16), 16, 0, 0); \
;     __builtin_amdgcn_global_load_lds((const unsigned*)(_gb + (size_t)K * 128 + loff0), (unsigned*)((char*)(P) + tid * 16 + 8192), 16, 0, 0); } while (0)
; #define LDA(dst, b, h) for (int m = 0; m < 4; ++m) { \
;     dst[m][0] = *reinterpret_cast<const bf16x8*>((char*)SA(b, h) + aoff0 + m * 2048); \
;     dst[m][1] = *reinterpret_cast<const bf16x8*>((char*)SA(b, h) + aoff1 + m * 2048); }
; #define LDB(dst, b, h) for (int n = 0; n < 2; ++n) { \
;     dst[n][0] = *reinterpret_cast<const bf16x8*>((char*)SB(b, h) + boff0 + n * 256); \
;     dst[n][1] = *reinterpret_cast<const bf16x8*>((char*)SB(b, h) + boff1 + n * 256); }
; #define MMA(ai, bj, At, Btf) do { __builtin_amdgcn_s_setprio(1); \
;     for (int m = 0; m < 4; ++m) for (int n = 0; n < 2; ++n) for (int k = 0; k < 2; ++k) \
;       acc[ai][bj][m][n] = __builtin_amdgcn_mfma_f32_16x16x32_bf16(Btf[n][k], At[m][k], acc[ai][bj][m][n], 0, 0, 0); \
;     __builtin_amdgcn_s_setprio(0); } while (0)
; #define WAIT_V(n) asm volatile("s_waitcnt vmcnt(" #n ")" ::: "memory")
; #define WAIT_L(n) asm volatile("s_waitcnt lgkmcnt(" #n ")" ::: "memory")
; #define BAR __builtin_amdgcn_s_barrier()
; template <int EPI> ...
;     ...
;   for (int t = 0; t < nt - 2; t += 2) {
;     LDB(B0, 0, 0); SCHED; LDA(At, 0, 0); STAGE(SA(1, 1), A, brow + HALF, t + 1);
;     WAIT_L(8); BAR; WAIT_L(0); MMA(0, 0, At, B0); BAR; SCHED;
;     LDB(B1, 0, 1); STAGE(SB(0, 0), Bt, bcol, t + 2);
;     BAR; WAIT_L(0); MMA(0, 1, At, B1); BAR;
;     LDA(At, 0, 1); STAGE(SA(0, 0), A, brow, t + 2);
;     BAR; WAIT_L(0); MMA(1, 0, At, B0); BAR; SCHED;
;     STAGE(SB(0, 1), Bt, bcol + HALF, t + 2);
;     WAIT_V(6); BAR; MMA(1, 1, At, B1); BAR;
;     LDB(B0, 1, 0); SCHED; LDA(At, 1, 0); STAGE(SA(0, 1), A, brow + HALF, t + 2);
;     WAIT_L(8); BAR; WAIT_L(0); MMA(0, 0, At, B0); BAR; SCHED;
;     LDB(B1, 1, 1); STAGE(SB(1, 0), Bt, bcol, t + 3);
;     BAR; WAIT_L(0); MMA(0, 1, At, B1); BAR;
;     LDA(At, 1, 1); STAGE(SA(1, 0), A, brow, t + 3);
;     BAR; WAIT_L(0); MMA(1, 0, At, B0); BAR; SCHED;
;     STAGE(SB(1, 1), Bt, bcol + HALF, t + 3);
;     WAIT_V(6); BAR; MMA(1, 1, At, B1); BAR;
;   }
	s_waitcnt lgkmcnt(0)
	s_setprio 1
	s_waitcnt lgkmcnt(0)
	v_mfma_f32_16x16x32_bf16 v[60:63], v[160:163], v[176:179], v[60:63]
	v_mfma_f32_16x16x32_bf16 v[56:59], v[164:167], v[176:179], v[56:59]
	v_mfma_f32_16x16x32_bf16 v[52:55], v[160:163], v[184:187], v[52:55]
	v_mfma_f32_16x16x32_bf16 v[48:51], v[164:167], v[184:187], v[48:51]
	v_mfma_f32_16x16x32_bf16 v[44:47], v[160:163], v[192:195], v[44:47]
	v_mfma_f32_16x16x32_bf16 v[40:43], v[164:167], v[192:195], v[40:43]
	v_mfma_f32_16x16x32_bf16 v[36:39], v[160:163], v[200:203], v[36:39]
	v_mfma_f32_16x16x32_bf16 v[32:35], v[164:167], v[200:203], v[32:35]
	v_mfma_f32_16x16x32_bf16 v[60:63], v[168:171], v[180:183], v[60:63]
	v_mfma_f32_16x16x32_bf16 v[56:59], v[172:175], v[180:183], v[56:59]
	v_mfma_f32_16x16x32_bf16 v[52:55], v[168:171], v[188:191], v[52:55]
	v_mfma_f32_16x16x32_bf16 v[48:51], v[172:175], v[188:191], v[48:51]
	v_mfma_f32_16x16x32_bf16 v[44:47], v[168:171], v[196:199], v[44:47]
	v_mfma_f32_16x16x32_bf16 v[40:43], v[172:175], v[196:199], v[40:43]
	v_mfma_f32_16x16x32_bf16 v[36:39], v[168:171], v[204:207], v[36:39]
	v_mfma_f32_16x16x32_bf16 v[32:35], v[172:175], v[204:207], v[32:35]
	s_setprio 0
	s_setprio 1
	v_mfma_f32_16x16x32_bf16 v[28:31], v[208:211], v[176:179], v[28:31]
	v_mfma_f32_16x16x32_bf16 v[24:27], v[212:215], v[176:179], v[24:27]
	v_mfma_f32_16x16x32_bf16 v[20:23], v[208:211], v[184:187], v[20:23]
	v_mfma_f32_16x16x32_bf16 v[16:19], v[212:215], v[184:187], v[16:19]
	v_mfma_f32_16x16x32_bf16 v[12:15], v[208:211], v[192:195], v[12:15]
	v_mfma_f32_16x16x32_bf16 v[8:11], v[212:215], v[192:195], v[8:11]
	v_mfma_f32_16x16x32_bf16 v[4:7], v[208:211], v[200:203], v[4:7]
	v_mfma_f32_16x16x32_bf16 v[0:3], v[212:215], v[200:203], v[0:3]
	v_mfma_f32_16x16x32_bf16 v[28:31], v[216:219], v[180:183], v[28:31]
	v_mfma_f32_16x16x32_bf16 v[24:27], v[220:223], v[180:183], v[24:27]
	v_mfma_f32_16x16x32_bf16 v[20:23], v[216:219], v[188:191], v[20:23]
	v_mfma_f32_16x16x32_bf16 v[16:19], v[220:223], v[188:191], v[16:19]
	v_mfma_f32_16x16x32_bf16 v[12:15], v[216:219], v[196:199], v[12:15]
	v_mfma_f32_16x16x32_bf16 v[8:11], v[220:223], v[196:199], v[8:11]
	v_mfma_f32_16x16x32_bf16 v[4:7], v[216:219], v[204:207], v[4:7]
	v_mfma_f32_16x16x32_bf16 v[0:3], v[220:223], v[204:207], v[0:3]
	s_setprio 0
	s_barrier
	ds_read_b128 v[160:163], v156
	ds_read_b128 v[164:167], v156 offset:256
	ds_read_b128 v[168:171], v157
	ds_read_b128 v[172:175], v157 offset:256
	v_readfirstlane_b32 s70, v141
	v_lshl_add_u64 v[208:209], v[224:225], 0, s[38:39]
	s_mov_b32 m0, s70
	v_readfirstlane_b32 s70, v142
	ds_read_b128 v[176:179], v149 offset:32768
	ds_read_b128 v[180:183], v149 offset:33792
	ds_read_b128 v[184:187], v149 offset:34816
	ds_read_b128 v[188:191], v149 offset:35840
	ds_read_b128 v[192:195], v149 offset:36864
	ds_read_b128 v[196:199], v149 offset:37888
	ds_read_b128 v[200:203], v149 offset:38912
	ds_read_b128 v[204:207], v149 offset:39936
	global_load_lds_dwordx4 v[208:209], off
	v_lshl_add_u64 v[208:209], v[224:225], 0, s[46:47]
	s_mov_b32 m0, s70
	s_nop 0
	global_load_lds_dwordx4 v[208:209], off
	s_waitcnt lgkmcnt(8)
	v_readfirstlane_b32 s70, v140
	v_lshl_add_u64 v[246:247], v[226:227], 0, s[36:37]
	s_mov_b32 m0, s70
	s_nop 0
	global_load_lds_dwordx4 v[246:247], off
	ds_read_b128 v[208:211], v158
	ds_read_b128 v[212:215], v158 offset:256
	ds_read_b128 v[216:219], v159
	ds_read_b128 v[220:223], v159 offset:256
	s_barrier
	s_waitcnt lgkmcnt(0)
	s_setprio 1
	s_waitcnt lgkmcnt(0)
	v_mfma_f32_16x16x32_bf16 v[124:127], v[160:163], v[176:179], v[124:127]
	v_mfma_f32_16x16x32_bf16 v[120:123], v[164:167], v[176:179], v[120:123]
	v_mfma_f32_16x16x32_bf16 v[116:119], v[160:163], v[184:187], v[116:119]
	v_mfma_f32_16x16x32_bf16 v[112:115], v[164:167], v[184:187], v[112:115]
	v_mfma_f32_16x16x32_bf16 v[108:111], v[160:163], v[192:195], v[108:111]
	v_mfma_f32_16x16x32_bf16 v[104:107], v[164:167], v[192:195], v[104:107]
	v_mfma_f32_16x16x32_bf16 v[100:103], v[160:163], v[200:203], v[100:103]
	v_mfma_f32_16x16x32_bf16 v[96:99], v[164:167], v[200:203], v[96:99]
	v_mfma_f32_16x16x32_bf16 v[124:127], v[168:171], v[180:183], v[124:127]
	v_mfma_f32_16x16x32_bf16 v[120:123], v[172:175], v[180:183], v[120:123]
	v_mfma_f32_16x16x32_bf16 v[116:119], v[168:171], v[188:191], v[116:119]
	v_mfma_f32_16x16x32_bf16 v[112:115], v[172:175], v[188:191], v[112:115]
	v_mfma_f32_16x16x32_bf16 v[108:111], v[168:171], v[196:199], v[108:111]
	v_mfma_f32_16x16x32_bf16 v[104:107], v[172:175], v[196:199], v[104:107]
	v_mfma_f32_16x16x32_bf16 v[100:103], v[168:171], v[204:207], v[100:103]
	v_mfma_f32_16x16x32_bf16 v[96:99], v[172:175], v[204:207], v[96:99]
	s_setprio 0
	s_waitcnt lgkmcnt(0)
	s_setprio 1
	s_waitcnt lgkmcnt(0)
	v_mfma_f32_16x16x32_bf16 v[92:95], v[208:211], v[176:179], v[92:95]
	v_mfma_f32_16x16x32_bf16 v[88:91], v[212:215], v[176:179], v[88:91]
	v_mfma_f32_16x16x32_bf16 v[84:87], v[208:211], v[184:187], v[84:87]
	v_mfma_f32_16x16x32_bf16 v[80:83], v[212:215], v[184:187], v[80:83]
	v_mfma_f32_16x16x32_bf16 v[76:79], v[208:211], v[192:195], v[76:79]
	v_mfma_f32_16x16x32_bf16 v[72:75], v[212:215], v[192:195], v[72:75]
	v_mfma_f32_16x16x32_bf16 v[68:71], v[208:211], v[200:203], v[68:71]
	v_mfma_f32_16x16x32_bf16 v[64:67], v[212:215], v[200:203], v[64:67]
	v_mfma_f32_16x16x32_bf16 v[92:95], v[216:219], v[180:183], v[92:95]
	v_mfma_f32_16x16x32_bf16 v[88:91], v[220:223], v[180:183], v[88:91]
	v_mfma_f32_16x16x32_bf16 v[84:87], v[216:219], v[188:191], v[84:87]
	v_mfma_f32_16x16x32_bf16 v[80:83], v[220:223], v[188:191], v[80:83]
	v_mfma_f32_16x16x32_bf16 v[76:79], v[216:219], v[196:199], v[76:79]
	v_mfma_f32_16x16x32_bf16 v[72:75], v[220:223], v[196:199], v[72:75]
	v_mfma_f32_16x16x32_bf16 v[68:71], v[216:219], v[204:207], v[68:71]
	v_mfma_f32_16x16x32_bf16 v[64:67], v[220:223], v[204:207], v[64:67]
	s_setprio 0
	s_barrier
; #define STAGE(P, BASE, br, kt) do { const char* _gb = (const char*)(BASE) + ((size_t)(br) * K + (size_t)(kt) * BK) * 2; \
;     __builtin_amdgcn_global_load_lds((const unsigned*)(_gb + loff0), (unsigned*)((char*)(P) + tid * 16), 16, 0, 0); \
;     __builtin_amdgcn_global_load_lds((const unsigned*)(_gb + (size_t)K * 128 + loff0), (unsigned*)((char*)(P) + tid * 16 + 8192), 16, 0, 0); } while (0)
; #define LDA(dst, b, h) for (int m = 0; m < 4; ++m) { \
;     dst[m][0] = *reinterpret_cast<const bf16x8*>((char*)SA(b, h) + aoff0 + m * 2048); \
;     dst[m][1] = *reinterpret_cast<const bf16x8*>((char*)SA(b, h) + aoff1 + m * 2048); }
; #define LDB(dst, b, h) for (int n = 0; n < 2; ++n) { \
;     dst[n][0] = *reinterpret_cast<const bf16x8*>((char*)SB(b, h) + boff0 + n * 256); \
;     dst[n][1] = *reinterpret_cast<const bf16x8*>((char*)SB(b, h) + boff1 + n * 256); }
; #define MMA(ai, bj, At, Btf) do { __builtin_amdgcn_s_setprio(1); \
;     for (int m = 0; m < 4; ++m) for (int n = 0; n < 2; ++n) for (int k = 0; k < 2; ++k) \
;       acc[ai][bj][m][n] = __builtin_amdgcn_mfma_f32_16x16x32_bf16(Btf[n][k], At[m][k], acc[ai][bj][m][n], 0, 0, 0); \
;     __builtin_amdgcn_s_setprio(0); } while (0)
; #define WAIT_V(n) asm volatile("s_waitcnt vmcnt(" #n ")" ::: "memory")
; template <int EPI> ...
;     ...
;   for (int t = 0; t < nt - 2; t += 2) {
;     LDB(B0, 0, 0); SCHED; LDA(At, 0, 0); STAGE(SA(1, 1), A, brow + HALF, t + 1);
;     WAIT_L(8); BAR; WAIT_L(0); MMA(0, 0, At, B0); BAR; SCHED;
;     LDB(B1, 0, 1); STAGE(SB(0, 0), Bt, bcol, t + 2);
;     BAR; WAIT_L(0); MMA(0, 1, At, B1); BAR;
;     LDA(At, 0, 1); STAGE(SA(0, 0), A, brow, t + 2);
;     BAR; WAIT_L(0); MMA(1, 0, At, B0); BAR; SCHED;
;     STAGE(SB(0, 1), Bt, bcol + HALF, t + 2);
;     WAIT_V(6); BAR; MMA(1, 1, At, B1); BAR;
;     LDB(B0, 1, 0); SCHED; LDA(At, 1, 0); STAGE(SA(0, 1), A, brow + HALF, t + 2);
;     WAIT_L(8); BAR; WAIT_L(0); MMA(0, 0, At, B0); BAR; SCHED;
;     LDB(B1, 1, 1); STAGE(SB(1, 0), Bt, bcol, t + 3);
;     BAR; WAIT_L(0); MMA(0, 1, At, B1); BAR;
;     LDA(At, 1, 1); STAGE(SA(1, 0), A, brow, t + 3);
;     BAR; WAIT_L(0); MMA(1, 0, At, B0); BAR; SCHED;
;     STAGE(SB(1, 1), Bt, bcol + HALF, t + 3);
;     WAIT_V(6); BAR; MMA(1, 1, At, B1); BAR;
;   }
;   { LDB(B0, 0, 0); LDA(At, 0, 0); STAGE(SA(1, 1), A, brow + HALF, nt - 1);
;     BAR; WAIT_L(0); MMA(0, 0, At, B0); BAR;
	v_readfirstlane_b32 s70, v143
	v_lshl_add_u64 v[228:229], v[226:227], 0, s[48:49]
	s_mov_b32 m0, s70
	v_readfirstlane_b32 s70, v144
	global_load_lds_dwordx4 v[228:229], off
	v_lshl_add_u64 v[228:229], v[226:227], 0, s[50:51]
	s_mov_b32 m0, s70
	s_nop 0
	global_load_lds_dwordx4 v[228:229], off
	v_readfirstlane_b32 s70, v145
	v_lshl_add_u64 v[228:229], v[224:225], 0, s[52:53]
	s_mov_b32 m0, s70
	v_readfirstlane_b32 s70, v146
	ds_read_b128 v[176:179], v149 offset:49152
	ds_read_b128 v[180:183], v149 offset:50176
	ds_read_b128 v[184:187], v149 offset:51200
	ds_read_b128 v[188:191], v149 offset:52224
	ds_read_b128 v[192:195], v149 offset:53248
	ds_read_b128 v[196:199], v149 offset:54272
	ds_read_b128 v[200:203], v149 offset:55296
	ds_read_b128 v[204:207], v149 offset:56320
	global_load_lds_dwordx4 v[228:229], off
	v_lshl_add_u64 v[224:225], v[224:225], 0, s[54:55]
	s_mov_b32 m0, s70
	s_nop 0
	global_load_lds_dwordx4 v[224:225], off
	v_readfirstlane_b32 s70, v147
	v_lshl_add_u64 v[246:247], v[226:227], 0, s[56:57]
	s_mov_b32 m0, s70
	v_readfirstlane_b32 s70, v148
	global_load_lds_dwordx4 v[246:247], off
	s_waitcnt vmcnt(5)
	s_barrier
	s_waitcnt lgkmcnt(0)
	s_setprio 1
	s_waitcnt lgkmcnt(0)
	v_mfma_f32_16x16x32_bf16 v[60:63], v[160:163], v[176:179], v[60:63]
	v_mfma_f32_16x16x32_bf16 v[56:59], v[164:167], v[176:179], v[56:59]
	v_mfma_f32_16x16x32_bf16 v[52:55], v[160:163], v[184:187], v[52:55]
	v_mfma_f32_16x16x32_bf16 v[48:51], v[164:167], v[184:187], v[48:51]
	v_mfma_f32_16x16x32_bf16 v[44:47], v[160:163], v[192:195], v[44:47]
	v_mfma_f32_16x16x32_bf16 v[40:43], v[164:167], v[192:195], v[40:43]
	v_mfma_f32_16x16x32_bf16 v[36:39], v[160:163], v[200:203], v[36:39]
	v_mfma_f32_16x16x32_bf16 v[32:35], v[164:167], v[200:203], v[32:35]
	v_mfma_f32_16x16x32_bf16 v[60:63], v[168:171], v[180:183], v[60:63]
	v_mfma_f32_16x16x32_bf16 v[56:59], v[172:175], v[180:183], v[56:59]
	v_mfma_f32_16x16x32_bf16 v[52:55], v[168:171], v[188:191], v[52:55]
	v_mfma_f32_16x16x32_bf16 v[48:51], v[172:175], v[188:191], v[48:51]
	v_mfma_f32_16x16x32_bf16 v[44:47], v[168:171], v[196:199], v[44:47]
	v_mfma_f32_16x16x32_bf16 v[40:43], v[172:175], v[196:199], v[40:43]
	v_mfma_f32_16x16x32_bf16 v[36:39], v[168:171], v[204:207], v[36:39]
	v_mfma_f32_16x16x32_bf16 v[32:35], v[172:175], v[204:207], v[32:35]
	s_setprio 0
	s_setprio 1
	v_mfma_f32_16x16x32_bf16 v[28:31], v[208:211], v[176:179], v[28:31]
	v_mfma_f32_16x16x32_bf16 v[24:27], v[212:215], v[176:179], v[24:27]
	v_mfma_f32_16x16x32_bf16 v[20:23], v[208:211], v[184:187], v[20:23]
	v_mfma_f32_16x16x32_bf16 v[16:19], v[212:215], v[184:187], v[16:19]
	v_mfma_f32_16x16x32_bf16 v[12:15], v[208:211], v[192:195], v[12:15]
	v_mfma_f32_16x16x32_bf16 v[8:11], v[212:215], v[192:195], v[8:11]
	v_mfma_f32_16x16x32_bf16 v[4:7], v[208:211], v[200:203], v[4:7]
	v_mfma_f32_16x16x32_bf16 v[0:3], v[212:215], v[200:203], v[0:3]
	v_mfma_f32_16x16x32_bf16 v[28:31], v[216:219], v[180:183], v[28:31]
	v_mfma_f32_16x16x32_bf16 v[24:27], v[220:223], v[180:183], v[24:27]
	v_mfma_f32_16x16x32_bf16 v[20:23], v[216:219], v[188:191], v[20:23]
	v_mfma_f32_16x16x32_bf16 v[16:19], v[220:223], v[188:191], v[16:19]
	v_mfma_f32_16x16x32_bf16 v[12:15], v[216:219], v[196:199], v[12:15]
	v_mfma_f32_16x16x32_bf16 v[8:11], v[220:223], v[196:199], v[8:11]
	v_mfma_f32_16x16x32_bf16 v[4:7], v[216:219], v[204:207], v[4:7]
	v_mfma_f32_16x16x32_bf16 v[0:3], v[220:223], v[204:207], v[0:3]
	s_setprio 0
	s_add_i32 s61, s61, 2
	s_add_u32 s66, s66, 0x100
	s_addc_u32 s67, s67, 0
	s_add_u32 s68, s68, 0x100
	s_addc_u32 s69, s69, 0
	s_cmp_lt_u32 s61, 28
	s_barrier
	s_cbranch_scc1 .LBB0_411
	v_readfirstlane_b32 s70, v148
	v_lshl_add_u64 v[246:247], v[226:227], 0, s[58:59]
	s_mov_b32 m0, s70
	s_nop 0
	global_load_lds_dwordx4 v[246:247], off
	s_add_u32 s64, s74, s64
	s_addc_u32 s65, s75, s65
	v_readfirstlane_b32 s61, v150
	v_lshl_add_u64 v[208:209], s[64:65], 0, v[128:129]
	s_mov_b32 m0, s61
	v_readfirstlane_b32 s61, v151
	ds_read_b128 v[160:163], v152
	ds_read_b128 v[164:167], v152 offset:256
	ds_read_b128 v[168:171], v153
	ds_read_b128 v[172:175], v153 offset:256
	ds_read_b128 v[176:179], v149
	ds_read_b128 v[180:183], v149 offset:1024
	ds_read_b128 v[184:187], v149 offset:2048
	ds_read_b128 v[188:191], v149 offset:3072
	ds_read_b128 v[192:195], v149 offset:4096
	ds_read_b128 v[196:199], v149 offset:5120
	ds_read_b128 v[200:203], v149 offset:6144
	ds_read_b128 v[204:207], v149 offset:7168
	global_load_lds_dwordx4 v[208:209], off
	v_lshl_add_u64 v[208:209], v[208:209], 0, s[8:9]
	s_mov_b32 m0, s61
	s_nop 0
	global_load_lds_dwordx4 v[208:209], off
	s_barrier
	s_waitcnt lgkmcnt(0)
	s_setprio 1
	s_waitcnt lgkmcnt(0)
	v_mfma_f32_16x16x32_bf16 v[124:127], v[160:163], v[176:179], v[124:127]
	v_mfma_f32_16x16x32_bf16 v[116:119], v[160:163], v[184:187], v[116:119]
	v_mfma_f32_16x16x32_bf16 v[108:111], v[160:163], v[192:195], v[108:111]
	v_mfma_f32_16x16x32_bf16 v[100:103], v[160:163], v[200:203], v[100:103]
	v_mfma_f32_16x16x32_bf16 v[96:99], v[164:167], v[200:203], v[96:99]
	v_mfma_f32_16x16x32_bf16 v[124:127], v[168:171], v[180:183], v[124:127]
	v_mfma_f32_16x16x32_bf16 v[120:123], v[164:167], v[176:179], v[120:123]
	v_mfma_f32_16x16x32_bf16 v[116:119], v[168:171], v[188:191], v[116:119]
	v_mfma_f32_16x16x32_bf16 v[112:115], v[164:167], v[184:187], v[112:115]
	v_mfma_f32_16x16x32_bf16 v[108:111], v[168:171], v[196:199], v[108:111]
	v_mfma_f32_16x16x32_bf16 v[104:107], v[164:167], v[192:195], v[104:107]
	v_mfma_f32_16x16x32_bf16 v[100:103], v[168:171], v[204:207], v[100:103]
	v_mfma_f32_16x16x32_bf16 v[96:99], v[172:175], v[204:207], v[96:99]
	v_mfma_f32_16x16x32_bf16 v[208:211], v[172:175], v[180:183], v[120:123]
	v_mfma_f32_16x16x32_bf16 v[212:215], v[172:175], v[188:191], v[112:115]
	v_mfma_f32_16x16x32_bf16 v[216:219], v[172:175], v[196:199], v[104:107]
	s_setprio 0
	s_barrier
; #define LDA(dst, b, h) for (int m = 0; m < 4; ++m) { \
;     dst[m][0] = *reinterpret_cast<const bf16x8*>((char*)SA(b, h) + aoff0 + m * 2048); \
;     dst[m][1] = *reinterpret_cast<const bf16x8*>((char*)SA(b, h) + aoff1 + m * 2048); }
; #define LDB(dst, b, h) for (int n = 0; n < 2; ++n) { \
;     dst[n][0] = *reinterpret_cast<const bf16x8*>((char*)SB(b, h) + boff0 + n * 256); \
;     dst[n][1] = *reinterpret_cast<const bf16x8*>((char*)SB(b, h) + boff1 + n * 256); }
; #define MMA(ai, bj, At, Btf) do { __builtin_amdgcn_s_setprio(1); \
;     for (int m = 0; m < 4; ++m) for (int n = 0; n < 2; ++n) for (int k = 0; k < 2; ++k) \
;       acc[ai][bj][m][n] = __builtin_amdgcn_mfma_f32_16x16x32_bf16(Btf[n][k], At[m][k], acc[ai][bj][m][n], 0, 0, 0); \
;     __builtin_amdgcn_s_setprio(0); } while (0)
; #define WAIT_V(n) asm volatile("s_waitcnt vmcnt(" #n ")" ::: "memory")
; #define WAIT_L(n) asm volatile("s_waitcnt lgkmcnt(" #n ")" ::: "memory")
; #define BAR __builtin_amdgcn_s_barrier()
; template <int EPI> ...
;     ...
;     LDB(B1, 0, 1); BAR; WAIT_L(0); MMA(0, 1, At, B1); BAR;
;     LDA(At, 0, 1); WAIT_V(4); BAR; WAIT_L(0); MMA(1, 0, At, B0); MMA(1, 1, At, B1); BAR; }
;   { LDB(B0, 1, 0); LDA(At, 1, 0); WAIT_V(2); BAR; WAIT_L(0); MMA(0, 0, At, B0); BAR;
	s_nop 0
	ds_read_b128 v[104:107], v154
	ds_read_b128 v[112:115], v154 offset:256
	ds_read_b128 v[120:123], v155
	ds_read_b128 v[220:223], v155 offset:256
	s_barrier
	s_waitcnt lgkmcnt(0)
	s_setprio 1
	s_waitcnt lgkmcnt(0)
	v_mfma_f32_16x16x32_bf16 v[92:95], v[104:107], v[176:179], v[92:95]
	v_mfma_f32_16x16x32_bf16 v[88:91], v[112:115], v[176:179], v[88:91]
	v_mfma_f32_16x16x32_bf16 v[76:79], v[104:107], v[192:195], v[76:79]
	v_mfma_f32_16x16x32_bf16 v[72:75], v[112:115], v[192:195], v[72:75]
	v_mfma_f32_16x16x32_bf16 v[92:95], v[120:123], v[180:183], v[92:95]
	v_mfma_f32_16x16x32_bf16 v[88:91], v[220:223], v[180:183], v[88:91]
	v_mfma_f32_16x16x32_bf16 v[84:87], v[104:107], v[184:187], v[84:87]
	v_mfma_f32_16x16x32_bf16 v[80:83], v[112:115], v[184:187], v[80:83]
	v_mfma_f32_16x16x32_bf16 v[76:79], v[120:123], v[196:199], v[76:79]
	v_mfma_f32_16x16x32_bf16 v[72:75], v[220:223], v[196:199], v[72:75]
	v_mfma_f32_16x16x32_bf16 v[68:71], v[104:107], v[200:203], v[68:71]
	v_mfma_f32_16x16x32_bf16 v[64:67], v[112:115], v[200:203], v[64:67]
	v_mfma_f32_16x16x32_bf16 v[176:179], v[120:123], v[188:191], v[84:87]
	v_mfma_f32_16x16x32_bf16 v[180:183], v[220:223], v[188:191], v[80:83]
	v_mfma_f32_16x16x32_bf16 v[184:187], v[120:123], v[204:207], v[68:71]
	v_mfma_f32_16x16x32_bf16 v[188:191], v[220:223], v[204:207], v[64:67]
	s_setprio 0
	s_barrier
	s_nop 1
	ds_read_b128 v[64:67], v149 offset:16384
	ds_read_b128 v[68:71], v149 offset:17408
	ds_read_b128 v[80:83], v149 offset:18432
	ds_read_b128 v[84:87], v149 offset:19456
	ds_read_b128 v[192:195], v149 offset:20480
	ds_read_b128 v[196:199], v149 offset:21504
	ds_read_b128 v[200:203], v149 offset:22528
	ds_read_b128 v[204:207], v149 offset:23552
	s_waitcnt vmcnt(4)
	s_barrier
	s_waitcnt lgkmcnt(0)
	s_setprio 1
	s_waitcnt lgkmcnt(0)
	v_mfma_f32_16x16x32_bf16 v[60:63], v[160:163], v[64:67], v[60:63]
	v_mfma_f32_16x16x32_bf16 v[56:59], v[164:167], v[64:67], v[56:59]
	v_mfma_f32_16x16x32_bf16 v[44:47], v[160:163], v[192:195], v[44:47]
	v_mfma_f32_16x16x32_bf16 v[36:39], v[160:163], v[200:203], v[36:39]
	v_mfma_f32_16x16x32_bf16 v[60:63], v[168:171], v[68:71], v[60:63]
	v_mfma_f32_16x16x32_bf16 v[56:59], v[172:175], v[68:71], v[56:59]
	v_mfma_f32_16x16x32_bf16 v[52:55], v[160:163], v[80:83], v[52:55]
	v_mfma_f32_16x16x32_bf16 v[48:51], v[164:167], v[80:83], v[48:51]
	v_mfma_f32_16x16x32_bf16 v[44:47], v[168:171], v[196:199], v[44:47]
	v_mfma_f32_16x16x32_bf16 v[40:43], v[164:167], v[192:195], v[40:43]
	v_mfma_f32_16x16x32_bf16 v[36:39], v[168:171], v[204:207], v[36:39]
	v_mfma_f32_16x16x32_bf16 v[32:35], v[164:167], v[200:203], v[32:35]
	v_mfma_f32_16x16x32_bf16 v[224:227], v[168:171], v[84:87], v[52:55]
	v_mfma_f32_16x16x32_bf16 v[228:231], v[172:175], v[84:87], v[48:51]
	v_mfma_f32_16x16x32_bf16 v[232:235], v[172:175], v[196:199], v[40:43]
	v_mfma_f32_16x16x32_bf16 v[160:163], v[172:175], v[204:207], v[32:35]
	s_setprio 0
	s_setprio 1
	v_mfma_f32_16x16x32_bf16 v[28:31], v[104:107], v[64:67], v[28:31]
	v_mfma_f32_16x16x32_bf16 v[20:23], v[104:107], v[80:83], v[20:23]
	v_mfma_f32_16x16x32_bf16 v[12:15], v[104:107], v[192:195], v[12:15]
	v_mfma_f32_16x16x32_bf16 v[4:7], v[104:107], v[200:203], v[4:7]
	v_mfma_f32_16x16x32_bf16 v[28:31], v[120:123], v[68:71], v[28:31]
	v_mfma_f32_16x16x32_bf16 v[24:27], v[112:115], v[64:67], v[24:27]
	v_mfma_f32_16x16x32_bf16 v[20:23], v[120:123], v[84:87], v[20:23]
	v_mfma_f32_16x16x32_bf16 v[16:19], v[112:115], v[80:83], v[16:19]
	v_mfma_f32_16x16x32_bf16 v[12:15], v[120:123], v[196:199], v[12:15]
	v_mfma_f32_16x16x32_bf16 v[8:11], v[112:115], v[192:195], v[8:11]
	v_mfma_f32_16x16x32_bf16 v[4:7], v[120:123], v[204:207], v[4:7]
	v_mfma_f32_16x16x32_bf16 v[0:3], v[112:115], v[200:203], v[0:3]
	v_mfma_f32_16x16x32_bf16 v[164:167], v[220:223], v[68:71], v[24:27]
	v_mfma_f32_16x16x32_bf16 v[168:171], v[220:223], v[84:87], v[16:19]
	v_mfma_f32_16x16x32_bf16 v[172:175], v[220:223], v[196:199], v[8:11]
	v_mfma_f32_16x16x32_bf16 v[192:195], v[220:223], v[204:207], v[0:3]
	s_setprio 0
	s_barrier
	s_nop 1
	ds_read_b128 v[0:3], v156
	ds_read_b128 v[8:11], v156 offset:256
	ds_read_b128 v[16:19], v157
	ds_read_b128 v[24:27], v157 offset:256
	ds_read_b128 v[32:35], v149 offset:32768
	ds_read_b128 v[40:43], v149 offset:33792
	ds_read_b128 v[48:51], v149 offset:34816
	ds_read_b128 v[52:55], v149 offset:35840
	ds_read_b128 v[68:71], v149 offset:36864
	ds_read_b128 v[196:199], v149 offset:37888
	ds_read_b128 v[200:203], v149 offset:38912
	ds_read_b128 v[204:207], v149 offset:39936
	s_waitcnt vmcnt(2)
	s_barrier
; #define LDA(dst, b, h) for (int m = 0; m < 4; ++m) { \
;     dst[m][0] = *reinterpret_cast<const bf16x8*>((char*)SA(b, h) + aoff0 + m * 2048); \
;     dst[m][1] = *reinterpret_cast<const bf16x8*>((char*)SA(b, h) + aoff1 + m * 2048); }
; #define LDB(dst, b, h) for (int n = 0; n < 2; ++n) { \
;     dst[n][0] = *reinterpret_cast<const bf16x8*>((char*)SB(b, h) + boff0 + n * 256); \
;     dst[n][1] = *reinterpret_cast<const bf16x8*>((char*)SB(b, h) + boff1 + n * 256); }
; #define MMA(ai, bj, At, Btf) do { __builtin_amdgcn_s_setprio(1); \
;     for (int m = 0; m < 4; ++m) for (int n = 0; n < 2; ++n) for (int k = 0; k < 2; ++k) \
;       acc[ai][bj][m][n] = __builtin_amdgcn_mfma_f32_16x16x32_bf16(Btf[n][k], At[m][k], acc[ai][bj][m][n], 0, 0, 0); \
;     __builtin_amdgcn_s_setprio(0); } while (0)
; #define WAIT_V(n) asm volatile("s_waitcnt vmcnt(" #n ")" ::: "memory")
; #define WAIT_L(n) asm volatile("s_waitcnt lgkmcnt(" #n ")" ::: "memory")
; #define BAR __builtin_amdgcn_s_barrier()
; template <int EPI> ...
;     ...
;   { LDB(B0, 1, 0); LDA(At, 1, 0); WAIT_V(2); BAR; WAIT_L(0); MMA(0, 0, At, B0); BAR;
;     LDB(B1, 1, 1); WAIT_V(0); BAR; WAIT_L(0); MMA(0, 1, At, B1); BAR;
;     LDA(At, 1, 1); BAR; WAIT_L(0); MMA(1, 0, At, B0); MMA(1, 1, At, B1); BAR; }
;   if (wr == 0) BAR;
	s_waitcnt lgkmcnt(0)
	s_setprio 1
	s_waitcnt lgkmcnt(0)
	v_mfma_f32_16x16x32_bf16 v[64:67], v[0:3], v[32:35], v[124:127]
	v_mfma_f32_16x16x32_bf16 v[120:123], v[16:19], v[40:43], v[64:67]
	v_mfma_f32_16x16x32_bf16 v[64:67], v[8:11], v[32:35], v[208:211]
	v_mfma_f32_16x16x32_bf16 v[124:127], v[24:27], v[40:43], v[64:67]
	v_mfma_f32_16x16x32_bf16 v[64:67], v[0:3], v[48:51], v[116:119]
	v_mfma_f32_16x16x32_bf16 v[112:115], v[16:19], v[52:55], v[64:67]
	v_mfma_f32_16x16x32_bf16 v[64:67], v[8:11], v[48:51], v[212:215]
	v_mfma_f32_16x16x32_bf16 v[116:119], v[24:27], v[52:55], v[64:67]
	v_mfma_f32_16x16x32_bf16 v[64:67], v[0:3], v[68:71], v[108:111]
	v_mfma_f32_16x16x32_bf16 v[104:107], v[16:19], v[196:199], v[64:67]
	v_mfma_f32_16x16x32_bf16 v[64:67], v[8:11], v[68:71], v[216:219]
	v_mfma_f32_16x16x32_bf16 v[108:111], v[24:27], v[196:199], v[64:67]
	v_mfma_f32_16x16x32_bf16 v[64:67], v[0:3], v[200:203], v[100:103]
	v_mfma_f32_16x16x32_bf16 v[80:83], v[16:19], v[204:207], v[64:67]
	v_mfma_f32_16x16x32_bf16 v[64:67], v[8:11], v[200:203], v[96:99]
	v_mfma_f32_16x16x32_bf16 v[84:87], v[24:27], v[204:207], v[64:67]
	s_setprio 0
	s_barrier
	ds_read_b128 v[208:211], v158
	ds_read_b128 v[212:215], v158 offset:256
	ds_read_b128 v[216:219], v159
	ds_read_b128 v[220:223], v159 offset:256
	s_waitcnt vmcnt(0)
	s_barrier
	s_waitcnt lgkmcnt(0)
	s_setprio 1
	s_waitcnt lgkmcnt(0)
	v_mfma_f32_16x16x32_bf16 v[64:67], v[208:211], v[32:35], v[92:95]
	v_mfma_f32_16x16x32_bf16 v[32:35], v[212:215], v[32:35], v[88:91]
	v_mfma_f32_16x16x32_bf16 v[100:103], v[220:223], v[40:43], v[32:35]
	v_mfma_f32_16x16x32_bf16 v[32:35], v[208:211], v[48:51], v[176:179]
	v_mfma_f32_16x16x32_bf16 v[88:91], v[216:219], v[52:55], v[32:35]
	v_mfma_f32_16x16x32_bf16 v[32:35], v[212:215], v[48:51], v[180:183]
	v_mfma_f32_16x16x32_bf16 v[92:95], v[220:223], v[52:55], v[32:35]
	v_mfma_f32_16x16x32_bf16 v[32:35], v[208:211], v[68:71], v[76:79]
	v_mfma_f32_16x16x32_bf16 v[96:99], v[216:219], v[40:43], v[64:67]
	v_mfma_f32_16x16x32_bf16 v[64:67], v[216:219], v[196:199], v[32:35]
	v_mfma_f32_16x16x32_bf16 v[32:35], v[212:215], v[68:71], v[72:75]
	v_mfma_f32_16x16x32_bf16 v[68:71], v[220:223], v[196:199], v[32:35]
	v_mfma_f32_16x16x32_bf16 v[32:35], v[208:211], v[200:203], v[184:187]
	v_mfma_f32_16x16x32_bf16 v[48:51], v[216:219], v[204:207], v[32:35]
	v_mfma_f32_16x16x32_bf16 v[32:35], v[212:215], v[200:203], v[188:191]
	v_mfma_f32_16x16x32_bf16 v[52:55], v[220:223], v[204:207], v[32:35]
	s_setprio 0
	s_barrier
	ds_read_b128 v[176:179], v149 offset:49152
	ds_read_b128 v[180:183], v149 offset:50176
	ds_read_b128 v[184:187], v149 offset:51200
	ds_read_b128 v[188:191], v149 offset:52224
	ds_read_b128 v[196:199], v149 offset:53248
	ds_read_b128 v[200:203], v149 offset:54272
	ds_read_b128 v[204:207], v149 offset:55296
	ds_read_b128 v[236:239], v149 offset:56320
	s_barrier
	s_waitcnt lgkmcnt(0)
	s_setprio 1
	s_waitcnt lgkmcnt(0)
	v_mfma_f32_16x16x32_bf16 v[32:35], v[0:3], v[176:179], v[60:63]
	v_mfma_f32_16x16x32_bf16 v[72:75], v[16:19], v[180:183], v[32:35]
	v_mfma_f32_16x16x32_bf16 v[32:35], v[8:11], v[176:179], v[56:59]
	v_mfma_f32_16x16x32_bf16 v[76:79], v[24:27], v[180:183], v[32:35]
	v_mfma_f32_16x16x32_bf16 v[32:35], v[0:3], v[184:187], v[224:227]
	v_mfma_f32_16x16x32_bf16 v[56:59], v[16:19], v[188:191], v[32:35]
	v_mfma_f32_16x16x32_bf16 v[32:35], v[8:11], v[184:187], v[228:231]
	v_mfma_f32_16x16x32_bf16 v[60:63], v[24:27], v[188:191], v[32:35]
	v_mfma_f32_16x16x32_bf16 v[32:35], v[0:3], v[196:199], v[44:47]
	v_mfma_f32_16x16x32_bf16 v[40:43], v[16:19], v[200:203], v[32:35]
	v_mfma_f32_16x16x32_bf16 v[32:35], v[8:11], v[196:199], v[232:235]
	v_mfma_f32_16x16x32_bf16 v[0:3], v[0:3], v[204:207], v[36:39]
	v_mfma_f32_16x16x32_bf16 v[44:47], v[24:27], v[200:203], v[32:35]
	v_mfma_f32_16x16x32_bf16 v[32:35], v[16:19], v[236:239], v[0:3]
	v_mfma_f32_16x16x32_bf16 v[0:3], v[8:11], v[204:207], v[160:163]
	v_mfma_f32_16x16x32_bf16 v[36:39], v[24:27], v[236:239], v[0:3]
	s_setprio 0
	s_setprio 1
	v_mfma_f32_16x16x32_bf16 v[0:3], v[208:211], v[176:179], v[28:31]
	v_mfma_f32_16x16x32_bf16 v[24:27], v[216:219], v[180:183], v[0:3]
	v_mfma_f32_16x16x32_bf16 v[0:3], v[212:215], v[176:179], v[164:167]
	v_mfma_f32_16x16x32_bf16 v[28:31], v[220:223], v[180:183], v[0:3]
	v_mfma_f32_16x16x32_bf16 v[0:3], v[208:211], v[184:187], v[20:23]
	v_mfma_f32_16x16x32_bf16 v[16:19], v[216:219], v[188:191], v[0:3]
	v_mfma_f32_16x16x32_bf16 v[0:3], v[212:215], v[184:187], v[168:171]
	v_mfma_f32_16x16x32_bf16 v[20:23], v[220:223], v[188:191], v[0:3]
	v_mfma_f32_16x16x32_bf16 v[0:3], v[208:211], v[196:199], v[12:15]
	v_mfma_f32_16x16x32_bf16 v[8:11], v[216:219], v[200:203], v[0:3]
	v_mfma_f32_16x16x32_bf16 v[0:3], v[212:215], v[196:199], v[172:175]
	v_mfma_f32_16x16x32_bf16 v[12:15], v[220:223], v[200:203], v[0:3]
	v_mfma_f32_16x16x32_bf16 v[0:3], v[208:211], v[204:207], v[4:7]
	v_mfma_f32_16x16x32_bf16 v[4:7], v[212:215], v[204:207], v[192:195]
	v_mfma_f32_16x16x32_bf16 v[0:3], v[216:219], v[236:239], v[0:3]
	v_mfma_f32_16x16x32_bf16 v[4:7], v[220:223], v[236:239], v[4:7]
	s_setprio 0
	s_barrier
	s_and_saveexec_b64 s[64:65], s[2:3]
	s_cbranch_execz .LBB0_405
	s_barrier
	s_branch .LBB0_405

; #define STAGE(P, BASE, br, kt) do { const char* _gb = (const char*)(BASE) + ((size_t)(br) * K + (size_t)(kt) * BK) * 2; \
;     __builtin_amdgcn_global_load_lds((const unsigned*)(_gb + loff0), (unsigned*)((char*)(P) + tid * 16), 16, 0, 0); \
;     __builtin_amdgcn_global_load_lds((const unsigned*)(_gb + (size_t)K * 128 + loff0), (unsigned*)((char*)(P) + tid * 16 + 8192), 16, 0, 0); } while (0)
; #define LDA(dst, b, h) for (int m = 0; m < 4; ++m) { \
;     dst[m][0] = *reinterpret_cast<const bf16x8*>((char*)SA(b, h) + aoff0 + m * 2048); \
;     dst[m][1] = *reinterpret_cast<const bf16x8*>((char*)SA(b, h) + aoff1 + m * 2048); }
; #define LDB(dst, b, h) for (int n = 0; n < 2; ++n) { \
;     dst[n][0] = *reinterpret_cast<const bf16x8*>((char*)SB(b, h) + boff0 + n * 256); \
;     dst[n][1] = *reinterpret_cast<const bf16x8*>((char*)SB(b, h) + boff1 + n * 256); }
; #define MMA(ai, bj, At, Btf) do { __builtin_amdgcn_s_setprio(1); \
;     for (int m = 0; m < 4; ++m) for (int n = 0; n < 2; ++n) for (int k = 0; k < 2; ++k) \
;       acc[ai][bj][m][n] = __builtin_amdgcn_mfma_f32_16x16x32_bf16(Btf[n][k], At[m][k], acc[ai][bj][m][n], 0, 0, 0); \
;     __builtin_amdgcn_s_setprio(0); } while (0)
; #define WAIT_V(n) asm volatile("s_waitcnt vmcnt(" #n ")" ::: "memory")
; #define WAIT_L(n) asm volatile("s_waitcnt lgkmcnt(" #n ")" ::: "memory")
; #define BAR __builtin_amdgcn_s_barrier()
; template <int EPI> ...
;     ...
;   for (int t = 0; t < nt - 2; t += 2) {
;     LDB(B0, 0, 0); SCHED; LDA(At, 0, 0); STAGE(SA(1, 1), A, brow + HALF, t + 1);
;     WAIT_L(8); BAR; WAIT_L(0); MMA(0, 0, At, B0); BAR; SCHED;
;     LDB(B1, 0, 1); STAGE(SB(0, 0), Bt, bcol, t + 2);
;     BAR; WAIT_L(0); MMA(0, 1, At, B1); BAR;
;     LDA(At, 0, 1); STAGE(SA(0, 0), A, brow, t + 2);
;     BAR; WAIT_L(0); MMA(1, 0, At, B0); BAR; SCHED;
;     STAGE(SB(0, 1), Bt, bcol + HALF, t + 2);
;     WAIT_V(6); BAR; MMA(1, 1, At, B1); BAR;
;     LDB(B0, 1, 0); SCHED; LDA(At, 1, 0); STAGE(SA(0, 1), A, brow + HALF, t + 2);
;     WAIT_L(8); BAR; WAIT_L(0); MMA(0, 0, At, B0); BAR; SCHED;
;     LDB(B1, 1, 1); STAGE(SB(1, 0), Bt, bcol, t + 3);
;     BAR; WAIT_L(0); MMA(0, 1, At, B1); BAR;
;     LDA(At, 1, 1); STAGE(SA(1, 0), A, brow, t + 3);
;     BAR; WAIT_L(0); MMA(1, 0, At, B0); BAR; SCHED;
;     STAGE(SB(1, 1), Bt, bcol + HALF, t + 3);
;     WAIT_V(6); BAR; MMA(1, 1, At, B1); BAR;
;   }
.LBB0_1018:
	ds_read_b128 v[160:163], v152
	ds_read_b128 v[164:167], v152 offset:256
	ds_read_b128 v[168:171], v153
	ds_read_b128 v[172:175], v153 offset:256
	v_lshl_add_u64 v[224:225], s[66:67], 0, v[132:133]
	v_readfirstlane_b32 s68, v150
	v_lshl_add_u64 v[208:209], v[224:225], 0, s[16:17]
	s_mov_b32 m0, s68
	v_readfirstlane_b32 s68, v151
	ds_read_b128 v[176:179], v149
	ds_read_b128 v[180:183], v149 offset:1024
	ds_read_b128 v[184:187], v149 offset:2048
	ds_read_b128 v[188:191], v149 offset:3072
	ds_read_b128 v[192:195], v149 offset:4096
	ds_read_b128 v[196:199], v149 offset:5120
	ds_read_b128 v[200:203], v149 offset:6144
	ds_read_b128 v[204:207], v149 offset:7168
	global_load_lds_dwordx4 v[208:209], off
	v_lshl_add_u64 v[208:209], v[224:225], 0, s[18:19]
	s_mov_b32 m0, s68
	s_nop 0
	global_load_lds_dwordx4 v[208:209], off
	s_waitcnt lgkmcnt(8)
	v_readfirstlane_b32 s68, v148
	v_lshl_add_u64 v[246:247], v[226:227], 0, s[56:57]
	s_mov_b32 m0, s68
	s_nop 0
	global_load_lds_dwordx4 v[246:247], off
	ds_read_b128 v[208:211], v154
	ds_read_b128 v[212:215], v154 offset:256
	ds_read_b128 v[216:219], v155
	ds_read_b128 v[220:223], v155 offset:256
	s_barrier
	s_waitcnt lgkmcnt(0)
	s_setprio 1
	s_waitcnt lgkmcnt(0)
	v_mfma_f32_16x16x32_bf16 v[124:127], v[160:163], v[176:179], v[124:127]
	v_mfma_f32_16x16x32_bf16 v[120:123], v[164:167], v[176:179], v[120:123]
	v_mfma_f32_16x16x32_bf16 v[116:119], v[160:163], v[184:187], v[116:119]
	v_mfma_f32_16x16x32_bf16 v[112:115], v[164:167], v[184:187], v[112:115]
	v_mfma_f32_16x16x32_bf16 v[108:111], v[160:163], v[192:195], v[108:111]
	v_mfma_f32_16x16x32_bf16 v[104:107], v[164:167], v[192:195], v[104:107]
	v_mfma_f32_16x16x32_bf16 v[100:103], v[160:163], v[200:203], v[100:103]
	v_mfma_f32_16x16x32_bf16 v[96:99], v[164:167], v[200:203], v[96:99]
	v_mfma_f32_16x16x32_bf16 v[124:127], v[168:171], v[180:183], v[124:127]
	v_mfma_f32_16x16x32_bf16 v[120:123], v[172:175], v[180:183], v[120:123]
	v_mfma_f32_16x16x32_bf16 v[116:119], v[168:171], v[188:191], v[116:119]
	v_mfma_f32_16x16x32_bf16 v[112:115], v[172:175], v[188:191], v[112:115]
	v_mfma_f32_16x16x32_bf16 v[108:111], v[168:171], v[196:199], v[108:111]
	v_mfma_f32_16x16x32_bf16 v[104:107], v[172:175], v[196:199], v[104:107]
	v_mfma_f32_16x16x32_bf16 v[100:103], v[168:171], v[204:207], v[100:103]
	v_mfma_f32_16x16x32_bf16 v[96:99], v[172:175], v[204:207], v[96:99]
	s_setprio 0
	s_waitcnt lgkmcnt(0)
	s_setprio 1
	s_waitcnt lgkmcnt(0)
	v_mfma_f32_16x16x32_bf16 v[92:95], v[208:211], v[176:179], v[92:95]
	v_mfma_f32_16x16x32_bf16 v[88:91], v[212:215], v[176:179], v[88:91]
	v_mfma_f32_16x16x32_bf16 v[84:87], v[208:211], v[184:187], v[84:87]
	v_mfma_f32_16x16x32_bf16 v[80:83], v[212:215], v[184:187], v[80:83]
	v_mfma_f32_16x16x32_bf16 v[76:79], v[208:211], v[192:195], v[76:79]
	v_mfma_f32_16x16x32_bf16 v[72:75], v[212:215], v[192:195], v[72:75]
	v_mfma_f32_16x16x32_bf16 v[68:71], v[208:211], v[200:203], v[68:71]
	v_mfma_f32_16x16x32_bf16 v[64:67], v[212:215], v[200:203], v[64:67]
	v_mfma_f32_16x16x32_bf16 v[92:95], v[216:219], v[180:183], v[92:95]
	v_mfma_f32_16x16x32_bf16 v[88:91], v[220:223], v[180:183], v[88:91]
	v_mfma_f32_16x16x32_bf16 v[84:87], v[216:219], v[188:191], v[84:87]
	v_mfma_f32_16x16x32_bf16 v[80:83], v[220:223], v[188:191], v[80:83]
	v_mfma_f32_16x16x32_bf16 v[76:79], v[216:219], v[196:199], v[76:79]
	v_mfma_f32_16x16x32_bf16 v[72:75], v[220:223], v[196:199], v[72:75]
	v_mfma_f32_16x16x32_bf16 v[68:71], v[216:219], v[204:207], v[68:71]
	v_mfma_f32_16x16x32_bf16 v[64:67], v[220:223], v[204:207], v[64:67]
	s_setprio 0
	s_barrier
	v_lshl_add_u64 v[226:227], s[64:65], 0, v[132:133]
	v_readfirstlane_b32 s68, v135
	v_lshl_add_u64 v[228:229], v[226:227], 0, s[20:21]
	s_mov_b32 m0, s68
	v_readfirstlane_b32 s68, v136
	global_load_lds_dwordx4 v[228:229], off
	v_lshl_add_u64 v[228:229], v[226:227], 0, s[22:23]
	s_mov_b32 m0, s68
	s_nop 0
	global_load_lds_dwordx4 v[228:229], off
	v_readfirstlane_b32 s68, v137
	v_lshl_add_u64 v[228:229], v[224:225], 0, s[24:25]
	s_mov_b32 m0, s68
	v_readfirstlane_b32 s68, v138
	ds_read_b128 v[176:179], v149 offset:16384
	ds_read_b128 v[180:183], v149 offset:17408
	ds_read_b128 v[184:187], v149 offset:18432
	ds_read_b128 v[188:191], v149 offset:19456
	ds_read_b128 v[192:195], v149 offset:20480
	ds_read_b128 v[196:199], v149 offset:21504
	ds_read_b128 v[200:203], v149 offset:22528
	ds_read_b128 v[204:207], v149 offset:23552
	global_load_lds_dwordx4 v[228:229], off
	v_lshl_add_u64 v[228:229], v[224:225], 0, s[26:27]
	s_mov_b32 m0, s68
	s_nop 0
	global_load_lds_dwordx4 v[228:229], off
	v_readfirstlane_b32 s68, v139
	v_lshl_add_u64 v[246:247], v[226:227], 0, s[28:29]
	s_mov_b32 m0, s68
	v_readfirstlane_b32 s68, v140
	global_load_lds_dwordx4 v[246:247], off
	s_waitcnt vmcnt(5)
	s_barrier
; #define STAGE(P, BASE, br, kt) do { const char* _gb = (const char*)(BASE) + ((size_t)(br) * K + (size_t)(kt) * BK) * 2; \
;     __builtin_amdgcn_global_load_lds((const unsigned*)(_gb + loff0), (unsigned*)((char*)(P) + tid * 16), 16, 0, 0); \
;     __builtin_amdgcn_global_load_lds((const unsigned*)(_gb + (size_t)K * 128 + loff0), (unsigned*)((char*)(P) + tid * 16 + 8192), 16, 0, 0); } while (0)
; #define LDA(dst, b, h) for (int m = 0; m < 4; ++m) { \
;     dst[m][0] = *reinterpret_cast<const bf16x8*>((char*)SA(b, h) + aoff0 + m * 2048); \
;     dst[m][1] = *reinterpret_cast<const bf16x8*>((char*)SA(b, h) + aoff1 + m * 2048); }
; #define LDB(dst, b, h) for (int n = 0; n < 2; ++n) { \
;     dst[n][0] = *reinterpret_cast<const bf16x8*>((char*)SB(b, h) + boff0 + n * 256); \
;     dst[n][1] = *reinterpret_cast<const bf16x8*>((char*)SB(b, h) + boff1 + n * 256); }
; #define MMA(ai, bj, At, Btf) do { __builtin_amdgcn_s_setprio(1); \
;     for (int m = 0; m < 4; ++m) for (int n = 0; n < 2; ++n) for (int k = 0; k < 2; ++k) \
;       acc[ai][bj][m][n] = __builtin_amdgcn_mfma_f32_16x16x32_bf16(Btf[n][k], At[m][k], acc[ai][bj][m][n], 0, 0, 0); \
;     __builtin_amdgcn_s_setprio(0); } while (0)
; #define WAIT_V(n) asm volatile("s_waitcnt vmcnt(" #n ")" ::: "memory")
; #define WAIT_L(n) asm volatile("s_waitcnt lgkmcnt(" #n ")" ::: "memory")
; #define BAR __builtin_amdgcn_s_barrier()
; template <int EPI> ...
;     ...
;   for (int t = 0; t < nt - 2; t += 2) {
;     LDB(B0, 0, 0); SCHED; LDA(At, 0, 0); STAGE(SA(1, 1), A, brow + HALF, t + 1);
;     WAIT_L(8); BAR; WAIT_L(0); MMA(0, 0, At, B0); BAR; SCHED;
;     LDB(B1, 0, 1); STAGE(SB(0, 0), Bt, bcol, t + 2);
;     BAR; WAIT_L(0); MMA(0, 1, At, B1); BAR;
;     LDA(At, 0, 1); STAGE(SA(0, 0), A, brow, t + 2);
;     BAR; WAIT_L(0); MMA(1, 0, At, B0); BAR; SCHED;
;     STAGE(SB(0, 1), Bt, bcol + HALF, t + 2);
;     WAIT_V(6); BAR; MMA(1, 1, At, B1); BAR;
;     LDB(B0, 1, 0); SCHED; LDA(At, 1, 0); STAGE(SA(0, 1), A, brow + HALF, t + 2);
;     WAIT_L(8); BAR; WAIT_L(0); MMA(0, 0, At, B0); BAR; SCHED;
;     LDB(B1, 1, 1); STAGE(SB(1, 0), Bt, bcol, t + 3);
;     BAR; WAIT_L(0); MMA(0, 1, At, B1); BAR;
;     LDA(At, 1, 1); STAGE(SA(1, 0), A, brow, t + 3);
;     BAR; WAIT_L(0); MMA(1, 0, At, B0); BAR; SCHED;
;     STAGE(SB(1, 1), Bt, bcol + HALF, t + 3);
;     WAIT_V(6); BAR; MMA(1, 1, At, B1); BAR;
;   }
	s_waitcnt lgkmcnt(0)
	s_setprio 1
	s_waitcnt lgkmcnt(0)
	v_mfma_f32_16x16x32_bf16 v[60:63], v[160:163], v[176:179], v[60:63]
	v_mfma_f32_16x16x32_bf16 v[56:59], v[164:167], v[176:179], v[56:59]
	v_mfma_f32_16x16x32_bf16 v[52:55], v[160:163], v[184:187], v[52:55]
	v_mfma_f32_16x16x32_bf16 v[48:51], v[164:167], v[184:187], v[48:51]
	v_mfma_f32_16x16x32_bf16 v[44:47], v[160:163], v[192:195], v[44:47]
	v_mfma_f32_16x16x32_bf16 v[40:43], v[164:167], v[192:195], v[40:43]
	v_mfma_f32_16x16x32_bf16 v[36:39], v[160:163], v[200:203], v[36:39]
	v_mfma_f32_16x16x32_bf16 v[32:35], v[164:167], v[200:203], v[32:35]
	v_mfma_f32_16x16x32_bf16 v[60:63], v[168:171], v[180:183], v[60:63]
	v_mfma_f32_16x16x32_bf16 v[56:59], v[172:175], v[180:183], v[56:59]
	v_mfma_f32_16x16x32_bf16 v[52:55], v[168:171], v[188:191], v[52:55]
	v_mfma_f32_16x16x32_bf16 v[48:51], v[172:175], v[188:191], v[48:51]
	v_mfma_f32_16x16x32_bf16 v[44:47], v[168:171], v[196:199], v[44:47]
	v_mfma_f32_16x16x32_bf16 v[40:43], v[172:175], v[196:199], v[40:43]
	v_mfma_f32_16x16x32_bf16 v[36:39], v[168:171], v[204:207], v[36:39]
	v_mfma_f32_16x16x32_bf16 v[32:35], v[172:175], v[204:207], v[32:35]
	s_setprio 0
	s_setprio 1
	v_mfma_f32_16x16x32_bf16 v[28:31], v[208:211], v[176:179], v[28:31]
	v_mfma_f32_16x16x32_bf16 v[24:27], v[212:215], v[176:179], v[24:27]
	v_mfma_f32_16x16x32_bf16 v[20:23], v[208:211], v[184:187], v[20:23]
	v_mfma_f32_16x16x32_bf16 v[16:19], v[212:215], v[184:187], v[16:19]
	v_mfma_f32_16x16x32_bf16 v[12:15], v[208:211], v[192:195], v[12:15]
	v_mfma_f32_16x16x32_bf16 v[8:11], v[212:215], v[192:195], v[8:11]
	v_mfma_f32_16x16x32_bf16 v[4:7], v[208:211], v[200:203], v[4:7]
	v_mfma_f32_16x16x32_bf16 v[0:3], v[212:215], v[200:203], v[0:3]
	v_mfma_f32_16x16x32_bf16 v[28:31], v[216:219], v[180:183], v[28:31]
	v_mfma_f32_16x16x32_bf16 v[24:27], v[220:223], v[180:183], v[24:27]
	v_mfma_f32_16x16x32_bf16 v[20:23], v[216:219], v[188:191], v[20:23]
	v_mfma_f32_16x16x32_bf16 v[16:19], v[220:223], v[188:191], v[16:19]
	v_mfma_f32_16x16x32_bf16 v[12:15], v[216:219], v[196:199], v[12:15]
	v_mfma_f32_16x16x32_bf16 v[8:11], v[220:223], v[196:199], v[8:11]
	v_mfma_f32_16x16x32_bf16 v[4:7], v[216:219], v[204:207], v[4:7]
	v_mfma_f32_16x16x32_bf16 v[0:3], v[220:223], v[204:207], v[0:3]
	s_setprio 0
	s_barrier
	ds_read_b128 v[160:163], v156
	ds_read_b128 v[164:167], v156 offset:256
	ds_read_b128 v[168:171], v157
	ds_read_b128 v[172:175], v157 offset:256
	v_readfirstlane_b32 s68, v141
	v_lshl_add_u64 v[208:209], v[224:225], 0, s[36:37]
	s_mov_b32 m0, s68
	v_readfirstlane_b32 s68, v142
	ds_read_b128 v[176:179], v149 offset:32768
	ds_read_b128 v[180:183], v149 offset:33792
	ds_read_b128 v[184:187], v149 offset:34816
	ds_read_b128 v[188:191], v149 offset:35840
	ds_read_b128 v[192:195], v149 offset:36864
	ds_read_b128 v[196:199], v149 offset:37888
	ds_read_b128 v[200:203], v149 offset:38912
	ds_read_b128 v[204:207], v149 offset:39936
	global_load_lds_dwordx4 v[208:209], off
	v_lshl_add_u64 v[208:209], v[224:225], 0, s[38:39]
	s_mov_b32 m0, s68
	s_nop 0
	global_load_lds_dwordx4 v[208:209], off
	s_waitcnt lgkmcnt(8)
	v_readfirstlane_b32 s68, v140
	v_lshl_add_u64 v[246:247], v[226:227], 0, s[30:31]
	s_mov_b32 m0, s68
	s_nop 0
	global_load_lds_dwordx4 v[246:247], off
	ds_read_b128 v[208:211], v158
	ds_read_b128 v[212:215], v158 offset:256
	ds_read_b128 v[216:219], v159
	ds_read_b128 v[220:223], v159 offset:256
	s_barrier
	s_waitcnt lgkmcnt(0)
	s_setprio 1
	s_waitcnt lgkmcnt(0)
	v_mfma_f32_16x16x32_bf16 v[124:127], v[160:163], v[176:179], v[124:127]
	v_mfma_f32_16x16x32_bf16 v[120:123], v[164:167], v[176:179], v[120:123]
	v_mfma_f32_16x16x32_bf16 v[116:119], v[160:163], v[184:187], v[116:119]
	v_mfma_f32_16x16x32_bf16 v[112:115], v[164:167], v[184:187], v[112:115]
	v_mfma_f32_16x16x32_bf16 v[108:111], v[160:163], v[192:195], v[108:111]
	v_mfma_f32_16x16x32_bf16 v[104:107], v[164:167], v[192:195], v[104:107]
	v_mfma_f32_16x16x32_bf16 v[100:103], v[160:163], v[200:203], v[100:103]
	v_mfma_f32_16x16x32_bf16 v[96:99], v[164:167], v[200:203], v[96:99]
	v_mfma_f32_16x16x32_bf16 v[124:127], v[168:171], v[180:183], v[124:127]
	v_mfma_f32_16x16x32_bf16 v[120:123], v[172:175], v[180:183], v[120:123]
	v_mfma_f32_16x16x32_bf16 v[116:119], v[168:171], v[188:191], v[116:119]
	v_mfma_f32_16x16x32_bf16 v[112:115], v[172:175], v[188:191], v[112:115]
	v_mfma_f32_16x16x32_bf16 v[108:111], v[168:171], v[196:199], v[108:111]
	v_mfma_f32_16x16x32_bf16 v[104:107], v[172:175], v[196:199], v[104:107]
	v_mfma_f32_16x16x32_bf16 v[100:103], v[168:171], v[204:207], v[100:103]
	v_mfma_f32_16x16x32_bf16 v[96:99], v[172:175], v[204:207], v[96:99]
	s_setprio 0
	s_waitcnt lgkmcnt(0)
	s_setprio 1
	s_waitcnt lgkmcnt(0)
	v_mfma_f32_16x16x32_bf16 v[92:95], v[208:211], v[176:179], v[92:95]
	v_mfma_f32_16x16x32_bf16 v[88:91], v[212:215], v[176:179], v[88:91]
	v_mfma_f32_16x16x32_bf16 v[84:87], v[208:211], v[184:187], v[84:87]
	v_mfma_f32_16x16x32_bf16 v[80:83], v[212:215], v[184:187], v[80:83]
	v_mfma_f32_16x16x32_bf16 v[76:79], v[208:211], v[192:195], v[76:79]
	v_mfma_f32_16x16x32_bf16 v[72:75], v[212:215], v[192:195], v[72:75]
	v_mfma_f32_16x16x32_bf16 v[68:71], v[208:211], v[200:203], v[68:71]
	v_mfma_f32_16x16x32_bf16 v[64:67], v[212:215], v[200:203], v[64:67]
	v_mfma_f32_16x16x32_bf16 v[92:95], v[216:219], v[180:183], v[92:95]
	v_mfma_f32_16x16x32_bf16 v[88:91], v[220:223], v[180:183], v[88:91]
	v_mfma_f32_16x16x32_bf16 v[84:87], v[216:219], v[188:191], v[84:87]
	v_mfma_f32_16x16x32_bf16 v[80:83], v[220:223], v[188:191], v[80:83]
	v_mfma_f32_16x16x32_bf16 v[76:79], v[216:219], v[196:199], v[76:79]
	v_mfma_f32_16x16x32_bf16 v[72:75], v[220:223], v[196:199], v[72:75]
	v_mfma_f32_16x16x32_bf16 v[68:71], v[216:219], v[204:207], v[68:71]
	v_mfma_f32_16x16x32_bf16 v[64:67], v[220:223], v[204:207], v[64:67]
	s_setprio 0
	s_barrier
; #define STAGE(P, BASE, br, kt) do { const char* _gb = (const char*)(BASE) + ((size_t)(br) * K + (size_t)(kt) * BK) * 2; \
;     __builtin_amdgcn_global_load_lds((const unsigned*)(_gb + loff0), (unsigned*)((char*)(P) + tid * 16), 16, 0, 0); \
;     __builtin_amdgcn_global_load_lds((const unsigned*)(_gb + (size_t)K * 128 + loff0), (unsigned*)((char*)(P) + tid * 16 + 8192), 16, 0, 0); } while (0)
; #define LDA(dst, b, h) for (int m = 0; m < 4; ++m) { \
;     dst[m][0] = *reinterpret_cast<const bf16x8*>((char*)SA(b, h) + aoff0 + m * 2048); \
;     dst[m][1] = *reinterpret_cast<const bf16x8*>((char*)SA(b, h) + aoff1 + m * 2048); }
; #define LDB(dst, b, h) for (int n = 0; n < 2; ++n) { \
;     dst[n][0] = *reinterpret_cast<const bf16x8*>((char*)SB(b, h) + boff0 + n * 256); \
;     dst[n][1] = *reinterpret_cast<const bf16x8*>((char*)SB(b, h) + boff1 + n * 256); }
; #define MMA(ai, bj, At, Btf) do { __builtin_amdgcn_s_setprio(1); \
;     for (int m = 0; m < 4; ++m) for (int n = 0; n < 2; ++n) for (int k = 0; k < 2; ++k) \
;       acc[ai][bj][m][n] = __builtin_amdgcn_mfma_f32_16x16x32_bf16(Btf[n][k], At[m][k], acc[ai][bj][m][n], 0, 0, 0); \
;     __builtin_amdgcn_s_setprio(0); } while (0)
; #define WAIT_V(n) asm volatile("s_waitcnt vmcnt(" #n ")" ::: "memory")
; template <int EPI> ...
;     ...
;   for (int t = 0; t < nt - 2; t += 2) {
;     LDB(B0, 0, 0); SCHED; LDA(At, 0, 0); STAGE(SA(1, 1), A, brow + HALF, t + 1);
;     WAIT_L(8); BAR; WAIT_L(0); MMA(0, 0, At, B0); BAR; SCHED;
;     LDB(B1, 0, 1); STAGE(SB(0, 0), Bt, bcol, t + 2);
;     BAR; WAIT_L(0); MMA(0, 1, At, B1); BAR;
;     LDA(At, 0, 1); STAGE(SA(0, 0), A, brow, t + 2);
;     BAR; WAIT_L(0); MMA(1, 0, At, B0); BAR; SCHED;
;     STAGE(SB(0, 1), Bt, bcol + HALF, t + 2);
;     WAIT_V(6); BAR; MMA(1, 1, At, B1); BAR;
;     LDB(B0, 1, 0); SCHED; LDA(At, 1, 0); STAGE(SA(0, 1), A, brow + HALF, t + 2);
;     WAIT_L(8); BAR; WAIT_L(0); MMA(0, 0, At, B0); BAR; SCHED;
;     LDB(B1, 1, 1); STAGE(SB(1, 0), Bt, bcol, t + 3);
;     BAR; WAIT_L(0); MMA(0, 1, At, B1); BAR;
;     LDA(At, 1, 1); STAGE(SA(1, 0), A, brow, t + 3);
;     BAR; WAIT_L(0); MMA(1, 0, At, B0); BAR; SCHED;
;     STAGE(SB(1, 1), Bt, bcol + HALF, t + 3);
;     WAIT_V(6); BAR; MMA(1, 1, At, B1); BAR;
;   }
;   { LDB(B0, 0, 0); LDA(At, 0, 0); STAGE(SA(1, 1), A, brow + HALF, nt - 1);
;     BAR; WAIT_L(0); MMA(0, 0, At, B0); BAR;
	v_readfirstlane_b32 s68, v143
	v_lshl_add_u64 v[228:229], v[226:227], 0, s[46:47]
	s_mov_b32 m0, s68
	v_readfirstlane_b32 s68, v144
	global_load_lds_dwordx4 v[228:229], off
	v_lshl_add_u64 v[228:229], v[226:227], 0, s[48:49]
	s_mov_b32 m0, s68
	s_nop 0
	global_load_lds_dwordx4 v[228:229], off
	v_readfirstlane_b32 s68, v145
	v_lshl_add_u64 v[228:229], v[224:225], 0, s[50:51]
	s_mov_b32 m0, s68
	v_readfirstlane_b32 s68, v146
	ds_read_b128 v[176:179], v149 offset:49152
	ds_read_b128 v[180:183], v149 offset:50176
	ds_read_b128 v[184:187], v149 offset:51200
	ds_read_b128 v[188:191], v149 offset:52224
	ds_read_b128 v[192:195], v149 offset:53248
	ds_read_b128 v[196:199], v149 offset:54272
	ds_read_b128 v[200:203], v149 offset:55296
	ds_read_b128 v[204:207], v149 offset:56320
	global_load_lds_dwordx4 v[228:229], off
	v_lshl_add_u64 v[224:225], v[224:225], 0, s[52:53]
	s_mov_b32 m0, s68
	s_nop 0
	global_load_lds_dwordx4 v[224:225], off
	v_readfirstlane_b32 s68, v147
	v_lshl_add_u64 v[246:247], v[226:227], 0, s[54:55]
	s_mov_b32 m0, s68
	v_readfirstlane_b32 s68, v148
	global_load_lds_dwordx4 v[246:247], off
	s_waitcnt vmcnt(5)
	s_barrier
	s_waitcnt lgkmcnt(0)
	s_setprio 1
	s_waitcnt lgkmcnt(0)
	v_mfma_f32_16x16x32_bf16 v[60:63], v[160:163], v[176:179], v[60:63]
	v_mfma_f32_16x16x32_bf16 v[56:59], v[164:167], v[176:179], v[56:59]
	v_mfma_f32_16x16x32_bf16 v[52:55], v[160:163], v[184:187], v[52:55]
	v_mfma_f32_16x16x32_bf16 v[48:51], v[164:167], v[184:187], v[48:51]
	v_mfma_f32_16x16x32_bf16 v[44:47], v[160:163], v[192:195], v[44:47]
	v_mfma_f32_16x16x32_bf16 v[40:43], v[164:167], v[192:195], v[40:43]
	v_mfma_f32_16x16x32_bf16 v[36:39], v[160:163], v[200:203], v[36:39]
	v_mfma_f32_16x16x32_bf16 v[32:35], v[164:167], v[200:203], v[32:35]
	v_mfma_f32_16x16x32_bf16 v[60:63], v[168:171], v[180:183], v[60:63]
	v_mfma_f32_16x16x32_bf16 v[56:59], v[172:175], v[180:183], v[56:59]
	v_mfma_f32_16x16x32_bf16 v[52:55], v[168:171], v[188:191], v[52:55]
	v_mfma_f32_16x16x32_bf16 v[48:51], v[172:175], v[188:191], v[48:51]
	v_mfma_f32_16x16x32_bf16 v[44:47], v[168:171], v[196:199], v[44:47]
	v_mfma_f32_16x16x32_bf16 v[40:43], v[172:175], v[196:199], v[40:43]
	v_mfma_f32_16x16x32_bf16 v[36:39], v[168:171], v[204:207], v[36:39]
	v_mfma_f32_16x16x32_bf16 v[32:35], v[172:175], v[204:207], v[32:35]
	s_setprio 0
	s_setprio 1
	v_mfma_f32_16x16x32_bf16 v[28:31], v[208:211], v[176:179], v[28:31]
	v_mfma_f32_16x16x32_bf16 v[24:27], v[212:215], v[176:179], v[24:27]
	v_mfma_f32_16x16x32_bf16 v[20:23], v[208:211], v[184:187], v[20:23]
	v_mfma_f32_16x16x32_bf16 v[16:19], v[212:215], v[184:187], v[16:19]
	v_mfma_f32_16x16x32_bf16 v[12:15], v[208:211], v[192:195], v[12:15]
	v_mfma_f32_16x16x32_bf16 v[8:11], v[212:215], v[192:195], v[8:11]
	v_mfma_f32_16x16x32_bf16 v[4:7], v[208:211], v[200:203], v[4:7]
	v_mfma_f32_16x16x32_bf16 v[0:3], v[212:215], v[200:203], v[0:3]
	v_mfma_f32_16x16x32_bf16 v[28:31], v[216:219], v[180:183], v[28:31]
	v_mfma_f32_16x16x32_bf16 v[24:27], v[220:223], v[180:183], v[24:27]
	v_mfma_f32_16x16x32_bf16 v[20:23], v[216:219], v[188:191], v[20:23]
	v_mfma_f32_16x16x32_bf16 v[16:19], v[220:223], v[188:191], v[16:19]
	v_mfma_f32_16x16x32_bf16 v[12:15], v[216:219], v[196:199], v[12:15]
	v_mfma_f32_16x16x32_bf16 v[8:11], v[220:223], v[196:199], v[8:11]
	v_mfma_f32_16x16x32_bf16 v[4:7], v[216:219], v[204:207], v[4:7]
	v_mfma_f32_16x16x32_bf16 v[0:3], v[220:223], v[204:207], v[0:3]
	s_setprio 0
	s_add_i32 s59, s59, 2
	s_add_u32 s64, s64, 0x100
	s_addc_u32 s65, s65, 0
	s_add_u32 s66, s66, 0x100
	s_addc_u32 s67, s67, 0
	s_cmp_lt_u32 s59, 28
	s_barrier
	s_cbranch_scc1 .LBB0_1018
	v_readfirstlane_b32 s68, v148
	v_lshl_add_u64 v[246:247], v[226:227], 0, s[56:57]
	s_mov_b32 m0, s68
	s_nop 0
	global_load_lds_dwordx4 v[246:247], off
	s_add_u32 s62, s72, s62
	s_addc_u32 s63, s73, s63
	v_readfirstlane_b32 s59, v150
	v_lshl_add_u64 v[208:209], s[62:63], 0, v[128:129]
	s_mov_b32 m0, s59
	v_readfirstlane_b32 s59, v151
	ds_read_b128 v[160:163], v152
	ds_read_b128 v[164:167], v152 offset:256
	ds_read_b128 v[168:171], v153
	ds_read_b128 v[172:175], v153 offset:256
	ds_read_b128 v[176:179], v149
	ds_read_b128 v[180:183], v149 offset:1024
	ds_read_b128 v[184:187], v149 offset:2048
	ds_read_b128 v[188:191], v149 offset:3072
	ds_read_b128 v[192:195], v149 offset:4096
	ds_read_b128 v[196:199], v149 offset:5120
	ds_read_b128 v[200:203], v149 offset:6144
	ds_read_b128 v[204:207], v149 offset:7168
	global_load_lds_dwordx4 v[208:209], off
	v_lshl_add_u64 v[208:209], v[208:209], 0, s[8:9]
	s_mov_b32 m0, s59
	s_nop 0
	global_load_lds_dwordx4 v[208:209], off
	s_barrier
	s_waitcnt lgkmcnt(0)
	s_setprio 1
	s_waitcnt lgkmcnt(0)
	v_mfma_f32_16x16x32_bf16 v[124:127], v[160:163], v[176:179], v[124:127]
	v_mfma_f32_16x16x32_bf16 v[116:119], v[160:163], v[184:187], v[116:119]
	v_mfma_f32_16x16x32_bf16 v[108:111], v[160:163], v[192:195], v[108:111]
	v_mfma_f32_16x16x32_bf16 v[100:103], v[160:163], v[200:203], v[100:103]
	v_mfma_f32_16x16x32_bf16 v[96:99], v[164:167], v[200:203], v[96:99]
	v_mfma_f32_16x16x32_bf16 v[124:127], v[168:171], v[180:183], v[124:127]
	v_mfma_f32_16x16x32_bf16 v[120:123], v[164:167], v[176:179], v[120:123]
	v_mfma_f32_16x16x32_bf16 v[116:119], v[168:171], v[188:191], v[116:119]
	v_mfma_f32_16x16x32_bf16 v[112:115], v[164:167], v[184:187], v[112:115]
	v_mfma_f32_16x16x32_bf16 v[108:111], v[168:171], v[196:199], v[108:111]
	v_mfma_f32_16x16x32_bf16 v[104:107], v[164:167], v[192:195], v[104:107]
	v_mfma_f32_16x16x32_bf16 v[100:103], v[168:171], v[204:207], v[100:103]
	v_mfma_f32_16x16x32_bf16 v[96:99], v[172:175], v[204:207], v[96:99]
	v_mfma_f32_16x16x32_bf16 v[208:211], v[172:175], v[180:183], v[120:123]
	v_mfma_f32_16x16x32_bf16 v[212:215], v[172:175], v[188:191], v[112:115]
	v_mfma_f32_16x16x32_bf16 v[216:219], v[172:175], v[196:199], v[104:107]
	s_setprio 0
	s_barrier
; #define LDA(dst, b, h) for (int m = 0; m < 4; ++m) { \
;     dst[m][0] = *reinterpret_cast<const bf16x8*>((char*)SA(b, h) + aoff0 + m * 2048); \
;     dst[m][1] = *reinterpret_cast<const bf16x8*>((char*)SA(b, h) + aoff1 + m * 2048); }
; #define LDB(dst, b, h) for (int n = 0; n < 2; ++n) { \
;     dst[n][0] = *reinterpret_cast<const bf16x8*>((char*)SB(b, h) + boff0 + n * 256); \
;     dst[n][1] = *reinterpret_cast<const bf16x8*>((char*)SB(b, h) + boff1 + n * 256); }
; #define MMA(ai, bj, At, Btf) do { __builtin_amdgcn_s_setprio(1); \
;     for (int m = 0; m < 4; ++m) for (int n = 0; n < 2; ++n) for (int k = 0; k < 2; ++k) \
;       acc[ai][bj][m][n] = __builtin_amdgcn_mfma_f32_16x16x32_bf16(Btf[n][k], At[m][k], acc[ai][bj][m][n], 0, 0, 0); \
;     __builtin_amdgcn_s_setprio(0); } while (0)
; #define WAIT_V(n) asm volatile("s_waitcnt vmcnt(" #n ")" ::: "memory")
; #define WAIT_L(n) asm volatile("s_waitcnt lgkmcnt(" #n ")" ::: "memory")
; #define BAR __builtin_amdgcn_s_barrier()
; template <int EPI> ...
;     ...
;     LDB(B1, 0, 1); BAR; WAIT_L(0); MMA(0, 1, At, B1); BAR;
;     LDA(At, 0, 1); WAIT_V(4); BAR; WAIT_L(0); MMA(1, 0, At, B0); MMA(1, 1, At, B1); BAR; }
;   { LDB(B0, 1, 0); LDA(At, 1, 0); WAIT_V(2); BAR; WAIT_L(0); MMA(0, 0, At, B0); BAR;
	s_nop 0
	ds_read_b128 v[104:107], v154
	ds_read_b128 v[112:115], v154 offset:256
	ds_read_b128 v[120:123], v155
	ds_read_b128 v[220:223], v155 offset:256
	s_barrier
	s_waitcnt lgkmcnt(0)
	s_setprio 1
	s_waitcnt lgkmcnt(0)
	v_mfma_f32_16x16x32_bf16 v[84:87], v[104:107], v[184:187], v[84:87]
	v_mfma_f32_16x16x32_bf16 v[76:79], v[104:107], v[192:195], v[76:79]
	v_mfma_f32_16x16x32_bf16 v[72:75], v[112:115], v[192:195], v[72:75]
	v_mfma_f32_16x16x32_bf16 v[92:95], v[104:107], v[176:179], v[92:95]
	v_mfma_f32_16x16x32_bf16 v[88:91], v[112:115], v[176:179], v[88:91]
	v_mfma_f32_16x16x32_bf16 v[84:87], v[120:123], v[188:191], v[84:87]
	v_mfma_f32_16x16x32_bf16 v[80:83], v[112:115], v[184:187], v[80:83]
	v_mfma_f32_16x16x32_bf16 v[76:79], v[120:123], v[196:199], v[76:79]
	v_mfma_f32_16x16x32_bf16 v[72:75], v[220:223], v[196:199], v[72:75]
	v_mfma_f32_16x16x32_bf16 v[68:71], v[104:107], v[200:203], v[68:71]
	v_mfma_f32_16x16x32_bf16 v[64:67], v[112:115], v[200:203], v[64:67]
	v_mfma_f32_16x16x32_bf16 v[224:227], v[120:123], v[180:183], v[92:95]
	v_mfma_f32_16x16x32_bf16 v[176:179], v[220:223], v[180:183], v[88:91]
	v_mfma_f32_16x16x32_bf16 v[180:183], v[220:223], v[188:191], v[80:83]
	v_mfma_f32_16x16x32_bf16 v[184:187], v[120:123], v[204:207], v[68:71]
	v_mfma_f32_16x16x32_bf16 v[188:191], v[220:223], v[204:207], v[64:67]
	s_setprio 0
	s_barrier
	s_nop 0
	ds_read_b128 v[64:67], v149 offset:16384
	ds_read_b128 v[68:71], v149 offset:17408
	ds_read_b128 v[80:83], v149 offset:18432
	ds_read_b128 v[88:91], v149 offset:19456
	ds_read_b128 v[92:95], v149 offset:20480
	ds_read_b128 v[192:195], v149 offset:21504
	ds_read_b128 v[196:199], v149 offset:22528
	ds_read_b128 v[200:203], v149 offset:23552
	s_waitcnt vmcnt(4)
	s_barrier
	s_waitcnt lgkmcnt(0)
	s_setprio 1
	s_waitcnt lgkmcnt(0)
	v_mfma_f32_16x16x32_bf16 v[52:55], v[160:163], v[80:83], v[52:55]
	v_mfma_f32_16x16x32_bf16 v[44:47], v[160:163], v[92:95], v[44:47]
	v_mfma_f32_16x16x32_bf16 v[36:39], v[160:163], v[196:199], v[36:39]
	v_mfma_f32_16x16x32_bf16 v[60:63], v[160:163], v[64:67], v[60:63]
	v_mfma_f32_16x16x32_bf16 v[56:59], v[164:167], v[64:67], v[56:59]
	v_mfma_f32_16x16x32_bf16 v[52:55], v[168:171], v[88:91], v[52:55]
	v_mfma_f32_16x16x32_bf16 v[48:51], v[164:167], v[80:83], v[48:51]
	v_mfma_f32_16x16x32_bf16 v[44:47], v[168:171], v[192:195], v[44:47]
	v_mfma_f32_16x16x32_bf16 v[40:43], v[164:167], v[92:95], v[40:43]
	v_mfma_f32_16x16x32_bf16 v[36:39], v[168:171], v[200:203], v[36:39]
	v_mfma_f32_16x16x32_bf16 v[32:35], v[164:167], v[196:199], v[32:35]
	v_mfma_f32_16x16x32_bf16 v[204:207], v[168:171], v[68:71], v[60:63]
	v_mfma_f32_16x16x32_bf16 v[228:231], v[172:175], v[68:71], v[56:59]
	v_mfma_f32_16x16x32_bf16 v[232:235], v[172:175], v[88:91], v[48:51]
	v_mfma_f32_16x16x32_bf16 v[236:239], v[172:175], v[192:195], v[40:43]
	v_mfma_f32_16x16x32_bf16 v[160:163], v[172:175], v[200:203], v[32:35]
	s_setprio 0
	s_setprio 1
	v_mfma_f32_16x16x32_bf16 v[28:31], v[104:107], v[64:67], v[28:31]
	v_mfma_f32_16x16x32_bf16 v[20:23], v[104:107], v[80:83], v[20:23]
	v_mfma_f32_16x16x32_bf16 v[12:15], v[104:107], v[92:95], v[12:15]
	v_mfma_f32_16x16x32_bf16 v[4:7], v[104:107], v[196:199], v[4:7]
	v_mfma_f32_16x16x32_bf16 v[28:31], v[120:123], v[68:71], v[28:31]
	v_mfma_f32_16x16x32_bf16 v[24:27], v[112:115], v[64:67], v[24:27]
	v_mfma_f32_16x16x32_bf16 v[20:23], v[120:123], v[88:91], v[20:23]
	v_mfma_f32_16x16x32_bf16 v[16:19], v[112:115], v[80:83], v[16:19]
	v_mfma_f32_16x16x32_bf16 v[12:15], v[120:123], v[192:195], v[12:15]
	v_mfma_f32_16x16x32_bf16 v[8:11], v[112:115], v[92:95], v[8:11]
	v_mfma_f32_16x16x32_bf16 v[4:7], v[120:123], v[200:203], v[4:7]
	v_mfma_f32_16x16x32_bf16 v[0:3], v[112:115], v[196:199], v[0:3]
	v_mfma_f32_16x16x32_bf16 v[164:167], v[220:223], v[68:71], v[24:27]
	v_mfma_f32_16x16x32_bf16 v[168:171], v[220:223], v[88:91], v[16:19]
	v_mfma_f32_16x16x32_bf16 v[172:175], v[220:223], v[192:195], v[8:11]
	v_mfma_f32_16x16x32_bf16 v[192:195], v[220:223], v[200:203], v[0:3]
	s_setprio 0
	s_barrier
	s_nop 1
	ds_read_b128 v[0:3], v156
	ds_read_b128 v[8:11], v156 offset:256
	ds_read_b128 v[16:19], v157
	ds_read_b128 v[24:27], v157 offset:256
	ds_read_b128 v[32:35], v149 offset:32768
	ds_read_b128 v[40:43], v149 offset:33792
	ds_read_b128 v[48:51], v149 offset:34816
	ds_read_b128 v[56:59], v149 offset:35840
	ds_read_b128 v[60:63], v149 offset:36864
	ds_read_b128 v[68:71], v149 offset:37888
	ds_read_b128 v[196:199], v149 offset:38912
	ds_read_b128 v[200:203], v149 offset:39936
	s_waitcnt vmcnt(2)
	s_barrier
; #define LDA(dst, b, h) for (int m = 0; m < 4; ++m) { \
;     dst[m][0] = *reinterpret_cast<const bf16x8*>((char*)SA(b, h) + aoff0 + m * 2048); \
;     dst[m][1] = *reinterpret_cast<const bf16x8*>((char*)SA(b, h) + aoff1 + m * 2048); }
; #define LDB(dst, b, h) for (int n = 0; n < 2; ++n) { \
;     dst[n][0] = *reinterpret_cast<const bf16x8*>((char*)SB(b, h) + boff0 + n * 256); \
;     dst[n][1] = *reinterpret_cast<const bf16x8*>((char*)SB(b, h) + boff1 + n * 256); }
; #define MMA(ai, bj, At, Btf) do { __builtin_amdgcn_s_setprio(1); \
;     for (int m = 0; m < 4; ++m) for (int n = 0; n < 2; ++n) for (int k = 0; k < 2; ++k) \
;       acc[ai][bj][m][n] = __builtin_amdgcn_mfma_f32_16x16x32_bf16(Btf[n][k], At[m][k], acc[ai][bj][m][n], 0, 0, 0); \
;     __builtin_amdgcn_s_setprio(0); } while (0)
; #define WAIT_V(n) asm volatile("s_waitcnt vmcnt(" #n ")" ::: "memory")
; #define WAIT_L(n) asm volatile("s_waitcnt lgkmcnt(" #n ")" ::: "memory")
; #define BAR __builtin_amdgcn_s_barrier()
; template <int EPI> ...
;     ...
;   { LDB(B0, 1, 0); LDA(At, 1, 0); WAIT_V(2); BAR; WAIT_L(0); MMA(0, 0, At, B0); BAR;
;     LDB(B1, 1, 1); WAIT_V(0); BAR; WAIT_L(0); MMA(0, 1, At, B1); BAR;
;     LDA(At, 1, 1); BAR; WAIT_L(0); MMA(1, 0, At, B0); MMA(1, 1, At, B1); BAR; }
;   if (wr == 0) BAR;
	s_waitcnt lgkmcnt(0)
	s_setprio 1
	s_waitcnt lgkmcnt(0)
	v_mfma_f32_16x16x32_bf16 v[64:67], v[0:3], v[32:35], v[124:127]
	v_mfma_f32_16x16x32_bf16 v[120:123], v[16:19], v[40:43], v[64:67]
	v_mfma_f32_16x16x32_bf16 v[64:67], v[8:11], v[32:35], v[208:211]
	v_mfma_f32_16x16x32_bf16 v[124:127], v[24:27], v[40:43], v[64:67]
	v_mfma_f32_16x16x32_bf16 v[64:67], v[0:3], v[48:51], v[116:119]
	v_mfma_f32_16x16x32_bf16 v[112:115], v[16:19], v[56:59], v[64:67]
	v_mfma_f32_16x16x32_bf16 v[64:67], v[8:11], v[48:51], v[212:215]
	v_mfma_f32_16x16x32_bf16 v[116:119], v[24:27], v[56:59], v[64:67]
	v_mfma_f32_16x16x32_bf16 v[64:67], v[0:3], v[60:63], v[108:111]
	v_mfma_f32_16x16x32_bf16 v[104:107], v[16:19], v[68:71], v[64:67]
	v_mfma_f32_16x16x32_bf16 v[64:67], v[8:11], v[60:63], v[216:219]
	v_mfma_f32_16x16x32_bf16 v[108:111], v[24:27], v[68:71], v[64:67]
	v_mfma_f32_16x16x32_bf16 v[64:67], v[0:3], v[196:199], v[100:103]
	v_mfma_f32_16x16x32_bf16 v[88:91], v[16:19], v[200:203], v[64:67]
	v_mfma_f32_16x16x32_bf16 v[64:67], v[8:11], v[196:199], v[96:99]
	v_mfma_f32_16x16x32_bf16 v[92:95], v[24:27], v[200:203], v[64:67]
	s_setprio 0
	s_barrier
	ds_read_b128 v[208:211], v158
	ds_read_b128 v[212:215], v158 offset:256
	ds_read_b128 v[216:219], v159
	ds_read_b128 v[220:223], v159 offset:256
	s_waitcnt vmcnt(0)
	s_barrier
	s_waitcnt lgkmcnt(0)
	s_setprio 1
	s_waitcnt lgkmcnt(0)
	v_mfma_f32_16x16x32_bf16 v[64:67], v[208:211], v[32:35], v[224:227]
	v_mfma_f32_16x16x32_bf16 v[32:35], v[212:215], v[32:35], v[176:179]
	v_mfma_f32_16x16x32_bf16 v[100:103], v[220:223], v[40:43], v[32:35]
	v_mfma_f32_16x16x32_bf16 v[32:35], v[208:211], v[48:51], v[84:87]
	v_mfma_f32_16x16x32_bf16 v[80:83], v[216:219], v[56:59], v[32:35]
	v_mfma_f32_16x16x32_bf16 v[32:35], v[212:215], v[48:51], v[180:183]
	v_mfma_f32_16x16x32_bf16 v[84:87], v[220:223], v[56:59], v[32:35]
	v_mfma_f32_16x16x32_bf16 v[32:35], v[208:211], v[60:63], v[76:79]
	v_mfma_f32_16x16x32_bf16 v[96:99], v[216:219], v[40:43], v[64:67]
	v_mfma_f32_16x16x32_bf16 v[64:67], v[216:219], v[68:71], v[32:35]
	v_mfma_f32_16x16x32_bf16 v[32:35], v[212:215], v[60:63], v[72:75]
	v_mfma_f32_16x16x32_bf16 v[68:71], v[220:223], v[68:71], v[32:35]
	v_mfma_f32_16x16x32_bf16 v[32:35], v[208:211], v[196:199], v[184:187]
	v_mfma_f32_16x16x32_bf16 v[56:59], v[216:219], v[200:203], v[32:35]
	v_mfma_f32_16x16x32_bf16 v[32:35], v[212:215], v[196:199], v[188:191]
	v_mfma_f32_16x16x32_bf16 v[60:63], v[220:223], v[200:203], v[32:35]
	s_setprio 0
	s_barrier
	ds_read_b128 v[176:179], v149 offset:49152
	ds_read_b128 v[180:183], v149 offset:50176
	ds_read_b128 v[184:187], v149 offset:51200
	ds_read_b128 v[188:191], v149 offset:52224
	ds_read_b128 v[196:199], v149 offset:53248
	ds_read_b128 v[200:203], v149 offset:54272
	ds_read_b128 v[224:227], v149 offset:55296
	ds_read_b128 v[240:243], v149 offset:56320
	s_barrier
	s_waitcnt lgkmcnt(0)
	s_setprio 1
	s_waitcnt lgkmcnt(0)
	v_mfma_f32_16x16x32_bf16 v[32:35], v[0:3], v[176:179], v[204:207]
	v_mfma_f32_16x16x32_bf16 v[72:75], v[16:19], v[180:183], v[32:35]
	v_mfma_f32_16x16x32_bf16 v[32:35], v[8:11], v[176:179], v[228:231]
	v_mfma_f32_16x16x32_bf16 v[76:79], v[24:27], v[180:183], v[32:35]
	v_mfma_f32_16x16x32_bf16 v[32:35], v[0:3], v[184:187], v[52:55]
	v_mfma_f32_16x16x32_bf16 v[48:51], v[16:19], v[188:191], v[32:35]
	v_mfma_f32_16x16x32_bf16 v[32:35], v[8:11], v[184:187], v[232:235]
	v_mfma_f32_16x16x32_bf16 v[52:55], v[24:27], v[188:191], v[32:35]
	v_mfma_f32_16x16x32_bf16 v[32:35], v[0:3], v[196:199], v[44:47]
	v_mfma_f32_16x16x32_bf16 v[40:43], v[16:19], v[200:203], v[32:35]
	v_mfma_f32_16x16x32_bf16 v[32:35], v[8:11], v[196:199], v[236:239]
	v_mfma_f32_16x16x32_bf16 v[0:3], v[0:3], v[224:227], v[36:39]
	v_mfma_f32_16x16x32_bf16 v[44:47], v[24:27], v[200:203], v[32:35]
	v_mfma_f32_16x16x32_bf16 v[32:35], v[16:19], v[240:243], v[0:3]
	v_mfma_f32_16x16x32_bf16 v[0:3], v[8:11], v[224:227], v[160:163]
	v_mfma_f32_16x16x32_bf16 v[36:39], v[24:27], v[240:243], v[0:3]
	s_setprio 0
	s_setprio 1
	v_mfma_f32_16x16x32_bf16 v[0:3], v[208:211], v[176:179], v[28:31]
	v_mfma_f32_16x16x32_bf16 v[24:27], v[216:219], v[180:183], v[0:3]
	v_mfma_f32_16x16x32_bf16 v[0:3], v[212:215], v[176:179], v[164:167]
	v_mfma_f32_16x16x32_bf16 v[28:31], v[220:223], v[180:183], v[0:3]
	v_mfma_f32_16x16x32_bf16 v[0:3], v[208:211], v[184:187], v[20:23]
	v_mfma_f32_16x16x32_bf16 v[16:19], v[216:219], v[188:191], v[0:3]
	v_mfma_f32_16x16x32_bf16 v[0:3], v[212:215], v[184:187], v[168:171]
	v_mfma_f32_16x16x32_bf16 v[20:23], v[220:223], v[188:191], v[0:3]
	v_mfma_f32_16x16x32_bf16 v[0:3], v[208:211], v[196:199], v[12:15]
	v_mfma_f32_16x16x32_bf16 v[8:11], v[216:219], v[200:203], v[0:3]
	v_mfma_f32_16x16x32_bf16 v[0:3], v[212:215], v[196:199], v[172:175]
	v_mfma_f32_16x16x32_bf16 v[12:15], v[220:223], v[200:203], v[0:3]
	v_mfma_f32_16x16x32_bf16 v[0:3], v[208:211], v[224:227], v[4:7]
	v_mfma_f32_16x16x32_bf16 v[4:7], v[212:215], v[224:227], v[192:195]
	v_mfma_f32_16x16x32_bf16 v[0:3], v[216:219], v[240:243], v[0:3]
	v_mfma_f32_16x16x32_bf16 v[4:7], v[220:223], v[240:243], v[4:7]
	s_setprio 0
	s_barrier
	s_and_saveexec_b64 s[62:63], s[2:3]
	s_cbranch_execz .LBB0_1012
	s_barrier
	s_branch .LBB0_1012

; #define STAGE(P, BASE, br, kt) do { const char* _gb = (const char*)(BASE) + ((size_t)(br) * K + (size_t)(kt) * BK) * 2; \
;     __builtin_amdgcn_global_load_lds((const unsigned*)(_gb + loff0), (unsigned*)((char*)(P) + tid * 16), 16, 0, 0); \
;     __builtin_amdgcn_global_load_lds((const unsigned*)(_gb + (size_t)K * 128 + loff0), (unsigned*)((char*)(P) + tid * 16 + 8192), 16, 0, 0); } while (0)
; #define LDA(dst, b, h) for (int m = 0; m < 4; ++m) { \
;     dst[m][0] = *reinterpret_cast<const bf16x8*>((char*)SA(b, h) + aoff0 + m * 2048); \
;     dst[m][1] = *reinterpret_cast<const bf16x8*>((char*)SA(b, h) + aoff1 + m * 2048); }
; #define LDB(dst, b, h) for (int n = 0; n < 2; ++n) { \
;     dst[n][0] = *reinterpret_cast<const bf16x8*>((char*)SB(b, h) + boff0 + n * 256); \
;     dst[n][1] = *reinterpret_cast<const bf16x8*>((char*)SB(b, h) + boff1 + n * 256); }
; #define MMA(ai, bj, At, Btf) do { __builtin_amdgcn_s_setprio(1); \
;     for (int m = 0; m < 4; ++m) for (int n = 0; n < 2; ++n) for (int k = 0; k < 2; ++k) \
;       acc[ai][bj][m][n] = __builtin_amdgcn_mfma_f32_16x16x32_bf16(Btf[n][k], At[m][k], acc[ai][bj][m][n], 0, 0, 0); \
;     __builtin_amdgcn_s_setprio(0); } while (0)
; #define WAIT_V(n) asm volatile("s_waitcnt vmcnt(" #n ")" ::: "memory")
; #define WAIT_L(n) asm volatile("s_waitcnt lgkmcnt(" #n ")" ::: "memory")
; #define BAR __builtin_amdgcn_s_barrier()
; template <int EPI> ...
;     ...
;   for (int t = 0; t < nt - 2; t += 2) {
;     LDB(B0, 0, 0); SCHED; LDA(At, 0, 0); STAGE(SA(1, 1), A, brow + HALF, t + 1);
;     WAIT_L(8); BAR; WAIT_L(0); MMA(0, 0, At, B0); BAR; SCHED;
;     LDB(B1, 0, 1); STAGE(SB(0, 0), Bt, bcol, t + 2);
;     BAR; WAIT_L(0); MMA(0, 1, At, B1); BAR;
;     LDA(At, 0, 1); STAGE(SA(0, 0), A, brow, t + 2);
;     BAR; WAIT_L(0); MMA(1, 0, At, B0); BAR; SCHED;
;     STAGE(SB(0, 1), Bt, bcol + HALF, t + 2);
;     WAIT_V(6); BAR; MMA(1, 1, At, B1); BAR;
;     LDB(B0, 1, 0); SCHED; LDA(At, 1, 0); STAGE(SA(0, 1), A, brow + HALF, t + 2);
;     WAIT_L(8); BAR; WAIT_L(0); MMA(0, 0, At, B0); BAR; SCHED;
;     LDB(B1, 1, 1); STAGE(SB(1, 0), Bt, bcol, t + 3);
;     BAR; WAIT_L(0); MMA(0, 1, At, B1); BAR;
;     LDA(At, 1, 1); STAGE(SA(1, 0), A, brow, t + 3);
;     BAR; WAIT_L(0); MMA(1, 0, At, B0); BAR; SCHED;
;     STAGE(SB(1, 1), Bt, bcol + HALF, t + 3);
;     WAIT_V(6); BAR; MMA(1, 1, At, B1); BAR;
;   }
.LBB0_1105:
	ds_read_b128 v[162:165], v153
	ds_read_b128 v[166:169], v153 offset:256
	ds_read_b128 v[170:173], v154
	ds_read_b128 v[174:177], v154 offset:256
	v_lshl_add_u64 v[226:227], s[66:67], 0, v[130:131]
	v_readfirstlane_b32 s70, v151
	v_lshl_add_u64 v[210:211], v[226:227], 0, s[18:19]
	s_mov_b32 m0, s70
	v_readfirstlane_b32 s70, v152
	ds_read_b128 v[178:181], v150
	ds_read_b128 v[182:185], v150 offset:1024
	ds_read_b128 v[186:189], v150 offset:2048
	ds_read_b128 v[190:193], v150 offset:3072
	ds_read_b128 v[194:197], v150 offset:4096
	ds_read_b128 v[198:201], v150 offset:5120
	ds_read_b128 v[202:205], v150 offset:6144
	ds_read_b128 v[206:209], v150 offset:7168
	global_load_lds_dwordx4 v[210:211], off
	v_lshl_add_u64 v[210:211], v[226:227], 0, s[20:21]
	s_mov_b32 m0, s70
	s_nop 0
	global_load_lds_dwordx4 v[210:211], off
	s_waitcnt lgkmcnt(8)
	v_readfirstlane_b32 s70, v149
	v_lshl_add_u64 v[246:247], v[228:229], 0, s[58:59]
	s_mov_b32 m0, s70
	s_nop 0
	global_load_lds_dwordx4 v[246:247], off
	ds_read_b128 v[210:213], v155
	ds_read_b128 v[214:217], v155 offset:256
	ds_read_b128 v[218:221], v156
	ds_read_b128 v[222:225], v156 offset:256
	s_barrier
	s_waitcnt lgkmcnt(0)
	s_setprio 1
	s_waitcnt lgkmcnt(0)
	v_mfma_f32_16x16x32_bf16 v[124:127], v[162:165], v[178:181], v[124:127]
	v_mfma_f32_16x16x32_bf16 v[120:123], v[166:169], v[178:181], v[120:123]
	v_mfma_f32_16x16x32_bf16 v[116:119], v[162:165], v[186:189], v[116:119]
	v_mfma_f32_16x16x32_bf16 v[112:115], v[166:169], v[186:189], v[112:115]
	v_mfma_f32_16x16x32_bf16 v[108:111], v[162:165], v[194:197], v[108:111]
	v_mfma_f32_16x16x32_bf16 v[104:107], v[166:169], v[194:197], v[104:107]
	v_mfma_f32_16x16x32_bf16 v[100:103], v[162:165], v[202:205], v[100:103]
	v_mfma_f32_16x16x32_bf16 v[96:99], v[166:169], v[202:205], v[96:99]
	v_mfma_f32_16x16x32_bf16 v[124:127], v[170:173], v[182:185], v[124:127]
	v_mfma_f32_16x16x32_bf16 v[120:123], v[174:177], v[182:185], v[120:123]
	v_mfma_f32_16x16x32_bf16 v[116:119], v[170:173], v[190:193], v[116:119]
	v_mfma_f32_16x16x32_bf16 v[112:115], v[174:177], v[190:193], v[112:115]
	v_mfma_f32_16x16x32_bf16 v[108:111], v[170:173], v[198:201], v[108:111]
	v_mfma_f32_16x16x32_bf16 v[104:107], v[174:177], v[198:201], v[104:107]
	v_mfma_f32_16x16x32_bf16 v[100:103], v[170:173], v[206:209], v[100:103]
	v_mfma_f32_16x16x32_bf16 v[96:99], v[174:177], v[206:209], v[96:99]
	s_setprio 0
	s_waitcnt lgkmcnt(0)
	s_setprio 1
	s_waitcnt lgkmcnt(0)
	v_mfma_f32_16x16x32_bf16 v[92:95], v[210:213], v[178:181], v[92:95]
	v_mfma_f32_16x16x32_bf16 v[88:91], v[214:217], v[178:181], v[88:91]
	v_mfma_f32_16x16x32_bf16 v[84:87], v[210:213], v[186:189], v[84:87]
	v_mfma_f32_16x16x32_bf16 v[80:83], v[214:217], v[186:189], v[80:83]
	v_mfma_f32_16x16x32_bf16 v[76:79], v[210:213], v[194:197], v[76:79]
	v_mfma_f32_16x16x32_bf16 v[72:75], v[214:217], v[194:197], v[72:75]
	v_mfma_f32_16x16x32_bf16 v[68:71], v[210:213], v[202:205], v[68:71]
	v_mfma_f32_16x16x32_bf16 v[64:67], v[214:217], v[202:205], v[64:67]
	v_mfma_f32_16x16x32_bf16 v[92:95], v[218:221], v[182:185], v[92:95]
	v_mfma_f32_16x16x32_bf16 v[88:91], v[222:225], v[182:185], v[88:91]
	v_mfma_f32_16x16x32_bf16 v[84:87], v[218:221], v[190:193], v[84:87]
	v_mfma_f32_16x16x32_bf16 v[80:83], v[222:225], v[190:193], v[80:83]
	v_mfma_f32_16x16x32_bf16 v[76:79], v[218:221], v[198:201], v[76:79]
	v_mfma_f32_16x16x32_bf16 v[72:75], v[222:225], v[198:201], v[72:75]
	v_mfma_f32_16x16x32_bf16 v[68:71], v[218:221], v[206:209], v[68:71]
	v_mfma_f32_16x16x32_bf16 v[64:67], v[222:225], v[206:209], v[64:67]
	s_setprio 0
	s_barrier
	v_lshl_add_u64 v[228:229], s[68:69], 0, v[130:131]
	v_readfirstlane_b32 s70, v136
	v_lshl_add_u64 v[230:231], v[228:229], 0, s[22:23]
	s_mov_b32 m0, s70
	v_readfirstlane_b32 s70, v137
	global_load_lds_dwordx4 v[230:231], off
	v_lshl_add_u64 v[230:231], v[228:229], 0, s[24:25]
	s_mov_b32 m0, s70
	s_nop 0
	global_load_lds_dwordx4 v[230:231], off
	v_readfirstlane_b32 s70, v138
	v_lshl_add_u64 v[230:231], v[226:227], 0, s[26:27]
	s_mov_b32 m0, s70
	v_readfirstlane_b32 s70, v139
	ds_read_b128 v[178:181], v150 offset:16384
	ds_read_b128 v[182:185], v150 offset:17408
	ds_read_b128 v[186:189], v150 offset:18432
	ds_read_b128 v[190:193], v150 offset:19456
	ds_read_b128 v[194:197], v150 offset:20480
	ds_read_b128 v[198:201], v150 offset:21504
	ds_read_b128 v[202:205], v150 offset:22528
	ds_read_b128 v[206:209], v150 offset:23552
	global_load_lds_dwordx4 v[230:231], off
	v_lshl_add_u64 v[230:231], v[226:227], 0, s[28:29]
	s_mov_b32 m0, s70
	s_nop 0
	global_load_lds_dwordx4 v[230:231], off
	v_readfirstlane_b32 s70, v140
	v_lshl_add_u64 v[246:247], v[228:229], 0, s[30:31]
	s_mov_b32 m0, s70
	v_readfirstlane_b32 s70, v141
	global_load_lds_dwordx4 v[246:247], off
	s_waitcnt vmcnt(5)
	s_barrier
; #define STAGE(P, BASE, br, kt) do { const char* _gb = (const char*)(BASE) + ((size_t)(br) * K + (size_t)(kt) * BK) * 2; \
;     __builtin_amdgcn_global_load_lds((const unsigned*)(_gb + loff0), (unsigned*)((char*)(P) + tid * 16), 16, 0, 0); \
;     __builtin_amdgcn_global_load_lds((const unsigned*)(_gb + (size_t)K * 128 + loff0), (unsigned*)((char*)(P) + tid * 16 + 8192), 16, 0, 0); } while (0)
; #define LDA(dst, b, h) for (int m = 0; m < 4; ++m) { \
;     dst[m][0] = *reinterpret_cast<const bf16x8*>((char*)SA(b, h) + aoff0 + m * 2048); \
;     dst[m][1] = *reinterpret_cast<const bf16x8*>((char*)SA(b, h) + aoff1 + m * 2048); }
; #define LDB(dst, b, h) for (int n = 0; n < 2; ++n) { \
;     dst[n][0] = *reinterpret_cast<const bf16x8*>((char*)SB(b, h) + boff0 + n * 256); \
;     dst[n][1] = *reinterpret_cast<const bf16x8*>((char*)SB(b, h) + boff1 + n * 256); }
; #define MMA(ai, bj, At, Btf) do { __builtin_amdgcn_s_setprio(1); \
;     for (int m = 0; m < 4; ++m) for (int n = 0; n < 2; ++n) for (int k = 0; k < 2; ++k) \
;       acc[ai][bj][m][n] = __builtin_amdgcn_mfma_f32_16x16x32_bf16(Btf[n][k], At[m][k], acc[ai][bj][m][n], 0, 0, 0); \
;     __builtin_amdgcn_s_setprio(0); } while (0)
; #define WAIT_V(n) asm volatile("s_waitcnt vmcnt(" #n ")" ::: "memory")
; #define WAIT_L(n) asm volatile("s_waitcnt lgkmcnt(" #n ")" ::: "memory")
; #define BAR __builtin_amdgcn_s_barrier()
; template <int EPI> ...
;     ...
;   for (int t = 0; t < nt - 2; t += 2) {
;     LDB(B0, 0, 0); SCHED; LDA(At, 0, 0); STAGE(SA(1, 1), A, brow + HALF, t + 1);
;     WAIT_L(8); BAR; WAIT_L(0); MMA(0, 0, At, B0); BAR; SCHED;
;     LDB(B1, 0, 1); STAGE(SB(0, 0), Bt, bcol, t + 2);
;     BAR; WAIT_L(0); MMA(0, 1, At, B1); BAR;
;     LDA(At, 0, 1); STAGE(SA(0, 0), A, brow, t + 2);
;     BAR; WAIT_L(0); MMA(1, 0, At, B0); BAR; SCHED;
;     STAGE(SB(0, 1), Bt, bcol + HALF, t + 2);
;     WAIT_V(6); BAR; MMA(1, 1, At, B1); BAR;
;     LDB(B0, 1, 0); SCHED; LDA(At, 1, 0); STAGE(SA(0, 1), A, brow + HALF, t + 2);
;     WAIT_L(8); BAR; WAIT_L(0); MMA(0, 0, At, B0); BAR; SCHED;
;     LDB(B1, 1, 1); STAGE(SB(1, 0), Bt, bcol, t + 3);
;     BAR; WAIT_L(0); MMA(0, 1, At, B1); BAR;
;     LDA(At, 1, 1); STAGE(SA(1, 0), A, brow, t + 3);
;     BAR; WAIT_L(0); MMA(1, 0, At, B0); BAR; SCHED;
;     STAGE(SB(1, 1), Bt, bcol + HALF, t + 3);
;     WAIT_V(6); BAR; MMA(1, 1, At, B1); BAR;
;   }
	s_waitcnt lgkmcnt(0)
	s_setprio 1
	s_waitcnt lgkmcnt(0)
	v_mfma_f32_16x16x32_bf16 v[60:63], v[162:165], v[178:181], v[60:63]
	v_mfma_f32_16x16x32_bf16 v[56:59], v[166:169], v[178:181], v[56:59]
	v_mfma_f32_16x16x32_bf16 v[52:55], v[162:165], v[186:189], v[52:55]
	v_mfma_f32_16x16x32_bf16 v[48:51], v[166:169], v[186:189], v[48:51]
	v_mfma_f32_16x16x32_bf16 v[44:47], v[162:165], v[194:197], v[44:47]
	v_mfma_f32_16x16x32_bf16 v[40:43], v[166:169], v[194:197], v[40:43]
	v_mfma_f32_16x16x32_bf16 v[36:39], v[162:165], v[202:205], v[36:39]
	v_mfma_f32_16x16x32_bf16 v[32:35], v[166:169], v[202:205], v[32:35]
	v_mfma_f32_16x16x32_bf16 v[60:63], v[170:173], v[182:185], v[60:63]
	v_mfma_f32_16x16x32_bf16 v[56:59], v[174:177], v[182:185], v[56:59]
	v_mfma_f32_16x16x32_bf16 v[52:55], v[170:173], v[190:193], v[52:55]
	v_mfma_f32_16x16x32_bf16 v[48:51], v[174:177], v[190:193], v[48:51]
	v_mfma_f32_16x16x32_bf16 v[44:47], v[170:173], v[198:201], v[44:47]
	v_mfma_f32_16x16x32_bf16 v[40:43], v[174:177], v[198:201], v[40:43]
	v_mfma_f32_16x16x32_bf16 v[36:39], v[170:173], v[206:209], v[36:39]
	v_mfma_f32_16x16x32_bf16 v[32:35], v[174:177], v[206:209], v[32:35]
	s_setprio 0
	s_setprio 1
	v_mfma_f32_16x16x32_bf16 v[28:31], v[210:213], v[178:181], v[28:31]
	v_mfma_f32_16x16x32_bf16 v[24:27], v[214:217], v[178:181], v[24:27]
	v_mfma_f32_16x16x32_bf16 v[20:23], v[210:213], v[186:189], v[20:23]
	v_mfma_f32_16x16x32_bf16 v[16:19], v[214:217], v[186:189], v[16:19]
	v_mfma_f32_16x16x32_bf16 v[12:15], v[210:213], v[194:197], v[12:15]
	v_mfma_f32_16x16x32_bf16 v[8:11], v[214:217], v[194:197], v[8:11]
	v_mfma_f32_16x16x32_bf16 v[4:7], v[210:213], v[202:205], v[4:7]
	v_mfma_f32_16x16x32_bf16 v[0:3], v[214:217], v[202:205], v[0:3]
	v_mfma_f32_16x16x32_bf16 v[28:31], v[218:221], v[182:185], v[28:31]
	v_mfma_f32_16x16x32_bf16 v[24:27], v[222:225], v[182:185], v[24:27]
	v_mfma_f32_16x16x32_bf16 v[20:23], v[218:221], v[190:193], v[20:23]
	v_mfma_f32_16x16x32_bf16 v[16:19], v[222:225], v[190:193], v[16:19]
	v_mfma_f32_16x16x32_bf16 v[12:15], v[218:221], v[198:201], v[12:15]
	v_mfma_f32_16x16x32_bf16 v[8:11], v[222:225], v[198:201], v[8:11]
	v_mfma_f32_16x16x32_bf16 v[4:7], v[218:221], v[206:209], v[4:7]
	v_mfma_f32_16x16x32_bf16 v[0:3], v[222:225], v[206:209], v[0:3]
	s_setprio 0
	s_barrier
	ds_read_b128 v[162:165], v157
	ds_read_b128 v[166:169], v157 offset:256
	ds_read_b128 v[170:173], v158
	ds_read_b128 v[174:177], v158 offset:256
	v_readfirstlane_b32 s70, v142
	v_lshl_add_u64 v[210:211], v[226:227], 0, s[38:39]
	s_mov_b32 m0, s70
	v_readfirstlane_b32 s70, v143
	ds_read_b128 v[178:181], v150 offset:32768
	ds_read_b128 v[182:185], v150 offset:33792
	ds_read_b128 v[186:189], v150 offset:34816
	ds_read_b128 v[190:193], v150 offset:35840
	ds_read_b128 v[194:197], v150 offset:36864
	ds_read_b128 v[198:201], v150 offset:37888
	ds_read_b128 v[202:205], v150 offset:38912
	ds_read_b128 v[206:209], v150 offset:39936
	global_load_lds_dwordx4 v[210:211], off
	v_lshl_add_u64 v[210:211], v[226:227], 0, s[46:47]
	s_mov_b32 m0, s70
	s_nop 0
	global_load_lds_dwordx4 v[210:211], off
	s_waitcnt lgkmcnt(8)
	v_readfirstlane_b32 s70, v141
	v_lshl_add_u64 v[246:247], v[228:229], 0, s[36:37]
	s_mov_b32 m0, s70
	s_nop 0
	global_load_lds_dwordx4 v[246:247], off
	ds_read_b128 v[210:213], v159
	ds_read_b128 v[214:217], v159 offset:256
	ds_read_b128 v[218:221], v160
	ds_read_b128 v[222:225], v160 offset:256
	s_barrier
	s_waitcnt lgkmcnt(0)
	s_setprio 1
	s_waitcnt lgkmcnt(0)
	v_mfma_f32_16x16x32_bf16 v[124:127], v[162:165], v[178:181], v[124:127]
	v_mfma_f32_16x16x32_bf16 v[120:123], v[166:169], v[178:181], v[120:123]
	v_mfma_f32_16x16x32_bf16 v[116:119], v[162:165], v[186:189], v[116:119]
	v_mfma_f32_16x16x32_bf16 v[112:115], v[166:169], v[186:189], v[112:115]
	v_mfma_f32_16x16x32_bf16 v[108:111], v[162:165], v[194:197], v[108:111]
	v_mfma_f32_16x16x32_bf16 v[104:107], v[166:169], v[194:197], v[104:107]
	v_mfma_f32_16x16x32_bf16 v[100:103], v[162:165], v[202:205], v[100:103]
	v_mfma_f32_16x16x32_bf16 v[96:99], v[166:169], v[202:205], v[96:99]
	v_mfma_f32_16x16x32_bf16 v[124:127], v[170:173], v[182:185], v[124:127]
	v_mfma_f32_16x16x32_bf16 v[120:123], v[174:177], v[182:185], v[120:123]
	v_mfma_f32_16x16x32_bf16 v[116:119], v[170:173], v[190:193], v[116:119]
	v_mfma_f32_16x16x32_bf16 v[112:115], v[174:177], v[190:193], v[112:115]
	v_mfma_f32_16x16x32_bf16 v[108:111], v[170:173], v[198:201], v[108:111]
	v_mfma_f32_16x16x32_bf16 v[104:107], v[174:177], v[198:201], v[104:107]
	v_mfma_f32_16x16x32_bf16 v[100:103], v[170:173], v[206:209], v[100:103]
	v_mfma_f32_16x16x32_bf16 v[96:99], v[174:177], v[206:209], v[96:99]
	s_setprio 0
	s_waitcnt lgkmcnt(0)
	s_setprio 1
	s_waitcnt lgkmcnt(0)
	v_mfma_f32_16x16x32_bf16 v[92:95], v[210:213], v[178:181], v[92:95]
	v_mfma_f32_16x16x32_bf16 v[88:91], v[214:217], v[178:181], v[88:91]
	v_mfma_f32_16x16x32_bf16 v[84:87], v[210:213], v[186:189], v[84:87]
	v_mfma_f32_16x16x32_bf16 v[80:83], v[214:217], v[186:189], v[80:83]
	v_mfma_f32_16x16x32_bf16 v[76:79], v[210:213], v[194:197], v[76:79]
	v_mfma_f32_16x16x32_bf16 v[72:75], v[214:217], v[194:197], v[72:75]
	v_mfma_f32_16x16x32_bf16 v[68:71], v[210:213], v[202:205], v[68:71]
	v_mfma_f32_16x16x32_bf16 v[64:67], v[214:217], v[202:205], v[64:67]
	v_mfma_f32_16x16x32_bf16 v[92:95], v[218:221], v[182:185], v[92:95]
	v_mfma_f32_16x16x32_bf16 v[88:91], v[222:225], v[182:185], v[88:91]
	v_mfma_f32_16x16x32_bf16 v[84:87], v[218:221], v[190:193], v[84:87]
	v_mfma_f32_16x16x32_bf16 v[80:83], v[222:225], v[190:193], v[80:83]
	v_mfma_f32_16x16x32_bf16 v[76:79], v[218:221], v[198:201], v[76:79]
	v_mfma_f32_16x16x32_bf16 v[72:75], v[222:225], v[198:201], v[72:75]
	v_mfma_f32_16x16x32_bf16 v[68:71], v[218:221], v[206:209], v[68:71]
	v_mfma_f32_16x16x32_bf16 v[64:67], v[222:225], v[206:209], v[64:67]
	s_setprio 0
	s_barrier
; #define STAGE(P, BASE, br, kt) do { const char* _gb = (const char*)(BASE) + ((size_t)(br) * K + (size_t)(kt) * BK) * 2; \
;     __builtin_amdgcn_global_load_lds((const unsigned*)(_gb + loff0), (unsigned*)((char*)(P) + tid * 16), 16, 0, 0); \
;     __builtin_amdgcn_global_load_lds((const unsigned*)(_gb + (size_t)K * 128 + loff0), (unsigned*)((char*)(P) + tid * 16 + 8192), 16, 0, 0); } while (0)
; #define LDA(dst, b, h) for (int m = 0; m < 4; ++m) { \
;     dst[m][0] = *reinterpret_cast<const bf16x8*>((char*)SA(b, h) + aoff0 + m * 2048); \
;     dst[m][1] = *reinterpret_cast<const bf16x8*>((char*)SA(b, h) + aoff1 + m * 2048); }
; #define LDB(dst, b, h) for (int n = 0; n < 2; ++n) { \
;     dst[n][0] = *reinterpret_cast<const bf16x8*>((char*)SB(b, h) + boff0 + n * 256); \
;     dst[n][1] = *reinterpret_cast<const bf16x8*>((char*)SB(b, h) + boff1 + n * 256); }
; #define MMA(ai, bj, At, Btf) do { __builtin_amdgcn_s_setprio(1); \
;     for (int m = 0; m < 4; ++m) for (int n = 0; n < 2; ++n) for (int k = 0; k < 2; ++k) \
;       acc[ai][bj][m][n] = __builtin_amdgcn_mfma_f32_16x16x32_bf16(Btf[n][k], At[m][k], acc[ai][bj][m][n], 0, 0, 0); \
;     __builtin_amdgcn_s_setprio(0); } while (0)
; #define WAIT_V(n) asm volatile("s_waitcnt vmcnt(" #n ")" ::: "memory")
; template <int EPI> ...
;     ...
;   for (int t = 0; t < nt - 2; t += 2) {
;     LDB(B0, 0, 0); SCHED; LDA(At, 0, 0); STAGE(SA(1, 1), A, brow + HALF, t + 1);
;     WAIT_L(8); BAR; WAIT_L(0); MMA(0, 0, At, B0); BAR; SCHED;
;     LDB(B1, 0, 1); STAGE(SB(0, 0), Bt, bcol, t + 2);
;     BAR; WAIT_L(0); MMA(0, 1, At, B1); BAR;
;     LDA(At, 0, 1); STAGE(SA(0, 0), A, brow, t + 2);
;     BAR; WAIT_L(0); MMA(1, 0, At, B0); BAR; SCHED;
;     STAGE(SB(0, 1), Bt, bcol + HALF, t + 2);
;     WAIT_V(6); BAR; MMA(1, 1, At, B1); BAR;
;     LDB(B0, 1, 0); SCHED; LDA(At, 1, 0); STAGE(SA(0, 1), A, brow + HALF, t + 2);
;     WAIT_L(8); BAR; WAIT_L(0); MMA(0, 0, At, B0); BAR; SCHED;
;     LDB(B1, 1, 1); STAGE(SB(1, 0), Bt, bcol, t + 3);
;     BAR; WAIT_L(0); MMA(0, 1, At, B1); BAR;
;     LDA(At, 1, 1); STAGE(SA(1, 0), A, brow, t + 3);
;     BAR; WAIT_L(0); MMA(1, 0, At, B0); BAR; SCHED;
;     STAGE(SB(1, 1), Bt, bcol + HALF, t + 3);
;     WAIT_V(6); BAR; MMA(1, 1, At, B1); BAR;
;   }
;   { LDB(B0, 0, 0); LDA(At, 0, 0); STAGE(SA(1, 1), A, brow + HALF, nt - 1);
;     BAR; WAIT_L(0); MMA(0, 0, At, B0); BAR;
	v_readfirstlane_b32 s70, v144
	v_lshl_add_u64 v[230:231], v[228:229], 0, s[48:49]
	s_mov_b32 m0, s70
	v_readfirstlane_b32 s70, v145
	global_load_lds_dwordx4 v[230:231], off
	v_lshl_add_u64 v[230:231], v[228:229], 0, s[50:51]
	s_mov_b32 m0, s70
	s_nop 0
	global_load_lds_dwordx4 v[230:231], off
	v_readfirstlane_b32 s70, v146
	v_lshl_add_u64 v[230:231], v[226:227], 0, s[52:53]
	s_mov_b32 m0, s70
	v_readfirstlane_b32 s70, v147
	ds_read_b128 v[178:181], v150 offset:49152
	ds_read_b128 v[182:185], v150 offset:50176
	ds_read_b128 v[186:189], v150 offset:51200
	ds_read_b128 v[190:193], v150 offset:52224
	ds_read_b128 v[194:197], v150 offset:53248
	ds_read_b128 v[198:201], v150 offset:54272
	ds_read_b128 v[202:205], v150 offset:55296
	ds_read_b128 v[206:209], v150 offset:56320
	global_load_lds_dwordx4 v[230:231], off
	v_lshl_add_u64 v[226:227], v[226:227], 0, s[54:55]
	s_mov_b32 m0, s70
	s_nop 0
	global_load_lds_dwordx4 v[226:227], off
	v_readfirstlane_b32 s70, v148
	v_lshl_add_u64 v[246:247], v[228:229], 0, s[56:57]
	s_mov_b32 m0, s70
	v_readfirstlane_b32 s70, v149
	global_load_lds_dwordx4 v[246:247], off
	s_waitcnt vmcnt(5)
	s_barrier
	s_waitcnt lgkmcnt(0)
	s_setprio 1
	s_waitcnt lgkmcnt(0)
	v_mfma_f32_16x16x32_bf16 v[60:63], v[162:165], v[178:181], v[60:63]
	v_mfma_f32_16x16x32_bf16 v[56:59], v[166:169], v[178:181], v[56:59]
	v_mfma_f32_16x16x32_bf16 v[52:55], v[162:165], v[186:189], v[52:55]
	v_mfma_f32_16x16x32_bf16 v[48:51], v[166:169], v[186:189], v[48:51]
	v_mfma_f32_16x16x32_bf16 v[44:47], v[162:165], v[194:197], v[44:47]
	v_mfma_f32_16x16x32_bf16 v[40:43], v[166:169], v[194:197], v[40:43]
	v_mfma_f32_16x16x32_bf16 v[36:39], v[162:165], v[202:205], v[36:39]
	v_mfma_f32_16x16x32_bf16 v[32:35], v[166:169], v[202:205], v[32:35]
	v_mfma_f32_16x16x32_bf16 v[60:63], v[170:173], v[182:185], v[60:63]
	v_mfma_f32_16x16x32_bf16 v[56:59], v[174:177], v[182:185], v[56:59]
	v_mfma_f32_16x16x32_bf16 v[52:55], v[170:173], v[190:193], v[52:55]
	v_mfma_f32_16x16x32_bf16 v[48:51], v[174:177], v[190:193], v[48:51]
	v_mfma_f32_16x16x32_bf16 v[44:47], v[170:173], v[198:201], v[44:47]
	v_mfma_f32_16x16x32_bf16 v[40:43], v[174:177], v[198:201], v[40:43]
	v_mfma_f32_16x16x32_bf16 v[36:39], v[170:173], v[206:209], v[36:39]
	v_mfma_f32_16x16x32_bf16 v[32:35], v[174:177], v[206:209], v[32:35]
	s_setprio 0
	s_setprio 1
	v_mfma_f32_16x16x32_bf16 v[28:31], v[210:213], v[178:181], v[28:31]
	v_mfma_f32_16x16x32_bf16 v[24:27], v[214:217], v[178:181], v[24:27]
	v_mfma_f32_16x16x32_bf16 v[20:23], v[210:213], v[186:189], v[20:23]
	v_mfma_f32_16x16x32_bf16 v[16:19], v[214:217], v[186:189], v[16:19]
	v_mfma_f32_16x16x32_bf16 v[12:15], v[210:213], v[194:197], v[12:15]
	v_mfma_f32_16x16x32_bf16 v[8:11], v[214:217], v[194:197], v[8:11]
	v_mfma_f32_16x16x32_bf16 v[4:7], v[210:213], v[202:205], v[4:7]
	v_mfma_f32_16x16x32_bf16 v[0:3], v[214:217], v[202:205], v[0:3]
	v_mfma_f32_16x16x32_bf16 v[28:31], v[218:221], v[182:185], v[28:31]
	v_mfma_f32_16x16x32_bf16 v[24:27], v[222:225], v[182:185], v[24:27]
	v_mfma_f32_16x16x32_bf16 v[20:23], v[218:221], v[190:193], v[20:23]
	v_mfma_f32_16x16x32_bf16 v[16:19], v[222:225], v[190:193], v[16:19]
	v_mfma_f32_16x16x32_bf16 v[12:15], v[218:221], v[198:201], v[12:15]
	v_mfma_f32_16x16x32_bf16 v[8:11], v[222:225], v[198:201], v[8:11]
	v_mfma_f32_16x16x32_bf16 v[4:7], v[218:221], v[206:209], v[4:7]
	v_mfma_f32_16x16x32_bf16 v[0:3], v[222:225], v[206:209], v[0:3]
	s_setprio 0
	s_add_i32 s65, s65, 2
	s_add_u32 s66, s66, 0x100
	s_addc_u32 s67, s67, 0
	s_add_u32 s68, s68, 0x100
	s_addc_u32 s69, s69, 0
	s_cmp_lt_u32 s65, 28
	s_barrier
	s_cbranch_scc1 .LBB0_1105
	v_readfirstlane_b32 s70, v149
	v_lshl_add_u64 v[246:247], v[228:229], 0, s[58:59]
	s_mov_b32 m0, s70
	s_nop 0
	global_load_lds_dwordx4 v[246:247], off
	v_readfirstlane_b32 s65, v151
	v_lshl_add_u64 v[210:211], v[132:133], 0, s[60:61]
	s_mov_b32 m0, s65
	v_readfirstlane_b32 s65, v152
	ds_read_b128 v[162:165], v153
	ds_read_b128 v[166:169], v153 offset:256
	ds_read_b128 v[170:173], v154
	ds_read_b128 v[174:177], v154 offset:256
	ds_read_b128 v[178:181], v150
	ds_read_b128 v[182:185], v150 offset:1024
	ds_read_b128 v[186:189], v150 offset:2048
	ds_read_b128 v[190:193], v150 offset:3072
	ds_read_b128 v[194:197], v150 offset:4096
	ds_read_b128 v[198:201], v150 offset:5120
	ds_read_b128 v[202:205], v150 offset:6144
	ds_read_b128 v[206:209], v150 offset:7168
	global_load_lds_dwordx4 v[210:211], off
	v_lshl_add_u64 v[132:133], v[132:133], 0, s[62:63]
	s_mov_b32 m0, s65
	s_nop 0
	global_load_lds_dwordx4 v[132:133], off
	s_barrier
	s_waitcnt lgkmcnt(0)
	s_setprio 1
	s_waitcnt lgkmcnt(0)
	v_mfma_f32_16x16x32_bf16 v[124:127], v[162:165], v[178:181], v[124:127]
	v_mfma_f32_16x16x32_bf16 v[116:119], v[162:165], v[186:189], v[116:119]
	v_mfma_f32_16x16x32_bf16 v[108:111], v[162:165], v[194:197], v[108:111]
	v_mfma_f32_16x16x32_bf16 v[100:103], v[162:165], v[202:205], v[100:103]
	v_mfma_f32_16x16x32_bf16 v[124:127], v[170:173], v[182:185], v[124:127]
	v_mfma_f32_16x16x32_bf16 v[120:123], v[166:169], v[178:181], v[120:123]
	v_mfma_f32_16x16x32_bf16 v[116:119], v[170:173], v[190:193], v[116:119]
	v_mfma_f32_16x16x32_bf16 v[112:115], v[166:169], v[186:189], v[112:115]
	v_mfma_f32_16x16x32_bf16 v[108:111], v[170:173], v[198:201], v[108:111]
	v_mfma_f32_16x16x32_bf16 v[104:107], v[166:169], v[194:197], v[104:107]
	v_mfma_f32_16x16x32_bf16 v[100:103], v[170:173], v[206:209], v[100:103]
	v_mfma_f32_16x16x32_bf16 v[96:99], v[166:169], v[202:205], v[96:99]
	v_mfma_f32_16x16x32_bf16 v[210:213], v[174:177], v[182:185], v[120:123]
	v_mfma_f32_16x16x32_bf16 v[214:217], v[174:177], v[190:193], v[112:115]
	v_mfma_f32_16x16x32_bf16 v[218:221], v[174:177], v[198:201], v[104:107]
	v_mfma_f32_16x16x32_bf16 v[222:225], v[174:177], v[206:209], v[96:99]
	s_setprio 0
	s_barrier
; #define LDA(dst, b, h) for (int m = 0; m < 4; ++m) { \
;     dst[m][0] = *reinterpret_cast<const bf16x8*>((char*)SA(b, h) + aoff0 + m * 2048); \
;     dst[m][1] = *reinterpret_cast<const bf16x8*>((char*)SA(b, h) + aoff1 + m * 2048); }
; #define LDB(dst, b, h) for (int n = 0; n < 2; ++n) { \
;     dst[n][0] = *reinterpret_cast<const bf16x8*>((char*)SB(b, h) + boff0 + n * 256); \
;     dst[n][1] = *reinterpret_cast<const bf16x8*>((char*)SB(b, h) + boff1 + n * 256); }
; #define MMA(ai, bj, At, Btf) do { __builtin_amdgcn_s_setprio(1); \
;     for (int m = 0; m < 4; ++m) for (int n = 0; n < 2; ++n) for (int k = 0; k < 2; ++k) \
;       acc[ai][bj][m][n] = __builtin_amdgcn_mfma_f32_16x16x32_bf16(Btf[n][k], At[m][k], acc[ai][bj][m][n], 0, 0, 0); \
;     __builtin_amdgcn_s_setprio(0); } while (0)
; #define WAIT_V(n) asm volatile("s_waitcnt vmcnt(" #n ")" ::: "memory")
; #define WAIT_L(n) asm volatile("s_waitcnt lgkmcnt(" #n ")" ::: "memory")
; #define BAR __builtin_amdgcn_s_barrier()
; template <int EPI> ...
;     ...
;     LDB(B1, 0, 1); BAR; WAIT_L(0); MMA(0, 1, At, B1); BAR;
;     LDA(At, 0, 1); WAIT_V(4); BAR; WAIT_L(0); MMA(1, 0, At, B0); MMA(1, 1, At, B1); BAR; }
;   { LDB(B0, 1, 0); LDA(At, 1, 0); WAIT_V(2); BAR; WAIT_L(0); MMA(0, 0, At, B0); BAR;
	s_nop 1
	ds_read_b128 v[96:99], v155
	ds_read_b128 v[104:107], v155 offset:256
	ds_read_b128 v[112:115], v156
	ds_read_b128 v[120:123], v156 offset:256
	s_barrier
	s_waitcnt lgkmcnt(0)
	s_setprio 1
	s_waitcnt lgkmcnt(0)
	v_mfma_f32_16x16x32_bf16 v[92:95], v[96:99], v[178:181], v[92:95]
	v_mfma_f32_16x16x32_bf16 v[84:87], v[96:99], v[186:189], v[84:87]
	v_mfma_f32_16x16x32_bf16 v[76:79], v[96:99], v[194:197], v[76:79]
	v_mfma_f32_16x16x32_bf16 v[68:71], v[96:99], v[202:205], v[68:71]
	v_mfma_f32_16x16x32_bf16 v[92:95], v[112:115], v[182:185], v[92:95]
	v_mfma_f32_16x16x32_bf16 v[88:91], v[104:107], v[178:181], v[88:91]
	v_mfma_f32_16x16x32_bf16 v[84:87], v[112:115], v[190:193], v[84:87]
	v_mfma_f32_16x16x32_bf16 v[80:83], v[104:107], v[186:189], v[80:83]
	v_mfma_f32_16x16x32_bf16 v[76:79], v[112:115], v[198:201], v[76:79]
	v_mfma_f32_16x16x32_bf16 v[72:75], v[104:107], v[194:197], v[72:75]
	v_mfma_f32_16x16x32_bf16 v[68:71], v[112:115], v[206:209], v[68:71]
	v_mfma_f32_16x16x32_bf16 v[64:67], v[104:107], v[202:205], v[64:67]
	v_mfma_f32_16x16x32_bf16 v[178:181], v[120:123], v[182:185], v[88:91]
	v_mfma_f32_16x16x32_bf16 v[182:185], v[120:123], v[190:193], v[80:83]
	v_mfma_f32_16x16x32_bf16 v[186:189], v[120:123], v[198:201], v[72:75]
	v_mfma_f32_16x16x32_bf16 v[190:193], v[120:123], v[206:209], v[64:67]
	s_setprio 0
	s_barrier
	s_nop 1
	ds_read_b128 v[64:67], v150 offset:16384
	ds_read_b128 v[72:75], v150 offset:17408
	ds_read_b128 v[80:83], v150 offset:18432
	ds_read_b128 v[88:91], v150 offset:19456
	ds_read_b128 v[194:197], v150 offset:20480
	ds_read_b128 v[198:201], v150 offset:21504
	ds_read_b128 v[202:205], v150 offset:22528
	ds_read_b128 v[206:209], v150 offset:23552
	s_waitcnt vmcnt(4)
	s_barrier
	s_waitcnt lgkmcnt(0)
	s_setprio 1
	s_waitcnt lgkmcnt(0)
	v_mfma_f32_16x16x32_bf16 v[60:63], v[162:165], v[64:67], v[60:63]
	v_mfma_f32_16x16x32_bf16 v[56:59], v[166:169], v[64:67], v[56:59]
	v_mfma_f32_16x16x32_bf16 v[52:55], v[162:165], v[80:83], v[52:55]
	v_mfma_f32_16x16x32_bf16 v[40:43], v[166:169], v[194:197], v[40:43]
	v_mfma_f32_16x16x32_bf16 v[36:39], v[162:165], v[202:205], v[36:39]
	v_mfma_f32_16x16x32_bf16 v[60:63], v[170:173], v[72:75], v[60:63]
	v_mfma_f32_16x16x32_bf16 v[56:59], v[174:177], v[72:75], v[56:59]
	v_mfma_f32_16x16x32_bf16 v[52:55], v[170:173], v[88:91], v[52:55]
	v_mfma_f32_16x16x32_bf16 v[48:51], v[166:169], v[80:83], v[48:51]
	v_mfma_f32_16x16x32_bf16 v[44:47], v[162:165], v[194:197], v[44:47]
	v_mfma_f32_16x16x32_bf16 v[40:43], v[174:177], v[198:201], v[40:43]
	v_mfma_f32_16x16x32_bf16 v[36:39], v[170:173], v[206:209], v[36:39]
	v_mfma_f32_16x16x32_bf16 v[32:35], v[166:169], v[202:205], v[32:35]
	v_mfma_f32_16x16x32_bf16 v[226:229], v[174:177], v[88:91], v[48:51]
	v_mfma_f32_16x16x32_bf16 v[230:233], v[170:173], v[198:201], v[44:47]
	v_mfma_f32_16x16x32_bf16 v[162:165], v[174:177], v[206:209], v[32:35]
	s_setprio 0
	s_setprio 1
	v_mfma_f32_16x16x32_bf16 v[24:27], v[104:107], v[64:67], v[24:27]
	v_mfma_f32_16x16x32_bf16 v[20:23], v[96:99], v[80:83], v[20:23]
	v_mfma_f32_16x16x32_bf16 v[8:11], v[104:107], v[194:197], v[8:11]
	v_mfma_f32_16x16x32_bf16 v[4:7], v[96:99], v[202:205], v[4:7]
	v_mfma_f32_16x16x32_bf16 v[28:31], v[96:99], v[64:67], v[28:31]
	v_mfma_f32_16x16x32_bf16 v[24:27], v[120:123], v[72:75], v[24:27]
	v_mfma_f32_16x16x32_bf16 v[20:23], v[112:115], v[88:91], v[20:23]
	v_mfma_f32_16x16x32_bf16 v[16:19], v[104:107], v[80:83], v[16:19]
	v_mfma_f32_16x16x32_bf16 v[12:15], v[96:99], v[194:197], v[12:15]
	v_mfma_f32_16x16x32_bf16 v[8:11], v[120:123], v[198:201], v[8:11]
	v_mfma_f32_16x16x32_bf16 v[4:7], v[112:115], v[206:209], v[4:7]
	v_mfma_f32_16x16x32_bf16 v[0:3], v[104:107], v[202:205], v[0:3]
	v_mfma_f32_16x16x32_bf16 v[166:169], v[112:115], v[72:75], v[28:31]
	v_mfma_f32_16x16x32_bf16 v[170:173], v[120:123], v[88:91], v[16:19]
	v_mfma_f32_16x16x32_bf16 v[174:177], v[112:115], v[198:201], v[12:15]
	v_mfma_f32_16x16x32_bf16 v[194:197], v[120:123], v[206:209], v[0:3]
	s_setprio 0
	s_barrier
	s_nop 1
	ds_read_b128 v[0:3], v157
	ds_read_b128 v[198:201], v157 offset:256
	ds_read_b128 v[12:15], v158
	ds_read_b128 v[202:205], v158 offset:256
	ds_read_b128 v[16:19], v150 offset:32768
	ds_read_b128 v[28:31], v150 offset:33792
	ds_read_b128 v[32:35], v150 offset:34816
	ds_read_b128 v[44:47], v150 offset:35840
	ds_read_b128 v[48:51], v150 offset:36864
	ds_read_b128 v[206:209], v150 offset:37888
	ds_read_b128 v[234:237], v150 offset:38912
	ds_read_b128 v[238:241], v150 offset:39936
	s_waitcnt vmcnt(2)
	s_barrier
; #define LDA(dst, b, h) for (int m = 0; m < 4; ++m) { \
;     dst[m][0] = *reinterpret_cast<const bf16x8*>((char*)SA(b, h) + aoff0 + m * 2048); \
;     dst[m][1] = *reinterpret_cast<const bf16x8*>((char*)SA(b, h) + aoff1 + m * 2048); }
; #define LDB(dst, b, h) for (int n = 0; n < 2; ++n) { \
;     dst[n][0] = *reinterpret_cast<const bf16x8*>((char*)SB(b, h) + boff0 + n * 256); \
;     dst[n][1] = *reinterpret_cast<const bf16x8*>((char*)SB(b, h) + boff1 + n * 256); }
; #define MMA(ai, bj, At, Btf) do { __builtin_amdgcn_s_setprio(1); \
;     for (int m = 0; m < 4; ++m) for (int n = 0; n < 2; ++n) for (int k = 0; k < 2; ++k) \
;       acc[ai][bj][m][n] = __builtin_amdgcn_mfma_f32_16x16x32_bf16(Btf[n][k], At[m][k], acc[ai][bj][m][n], 0, 0, 0); \
;     __builtin_amdgcn_s_setprio(0); } while (0)
; #define WAIT_V(n) asm volatile("s_waitcnt vmcnt(" #n ")" ::: "memory")
; #define WAIT_L(n) asm volatile("s_waitcnt lgkmcnt(" #n ")" ::: "memory")
; #define BAR __builtin_amdgcn_s_barrier()
; template <int EPI> ...
;     ...
;   { LDB(B0, 1, 0); LDA(At, 1, 0); WAIT_V(2); BAR; WAIT_L(0); MMA(0, 0, At, B0); BAR;
;     LDB(B1, 1, 1); WAIT_V(0); BAR; WAIT_L(0); MMA(0, 1, At, B1); BAR;
;     LDA(At, 1, 1); BAR; WAIT_L(0); MMA(1, 0, At, B0); MMA(1, 1, At, B1); BAR; }
;   if (wr == 0) BAR;
	s_waitcnt lgkmcnt(0)
	s_setprio 1
	s_waitcnt lgkmcnt(0)
	v_mfma_f32_16x16x32_bf16 v[64:67], v[0:3], v[16:19], v[124:127]
	v_mfma_f32_16x16x32_bf16 v[120:123], v[12:15], v[28:31], v[64:67]
	v_mfma_f32_16x16x32_bf16 v[64:67], v[198:201], v[16:19], v[210:213]
	v_mfma_f32_16x16x32_bf16 v[112:115], v[202:205], v[28:31], v[64:67]
	v_mfma_f32_16x16x32_bf16 v[64:67], v[0:3], v[32:35], v[116:119]
	v_mfma_f32_16x16x32_bf16 v[104:107], v[12:15], v[44:47], v[64:67]
	v_mfma_f32_16x16x32_bf16 v[64:67], v[198:201], v[32:35], v[214:217]
	v_mfma_f32_16x16x32_bf16 v[96:99], v[202:205], v[44:47], v[64:67]
	v_mfma_f32_16x16x32_bf16 v[64:67], v[0:3], v[48:51], v[108:111]
	v_mfma_f32_16x16x32_bf16 v[88:91], v[12:15], v[206:209], v[64:67]
	v_mfma_f32_16x16x32_bf16 v[64:67], v[198:201], v[48:51], v[218:221]
	v_mfma_f32_16x16x32_bf16 v[80:83], v[202:205], v[206:209], v[64:67]
	v_mfma_f32_16x16x32_bf16 v[64:67], v[0:3], v[234:237], v[100:103]
	v_mfma_f32_16x16x32_bf16 v[72:75], v[12:15], v[238:241], v[64:67]
	v_mfma_f32_16x16x32_bf16 v[64:67], v[198:201], v[234:237], v[222:225]
	v_mfma_f32_16x16x32_bf16 v[64:67], v[202:205], v[238:241], v[64:67]
	s_setprio 0
	s_barrier
	ds_read_b128 v[210:213], v159
	ds_read_b128 v[214:217], v159 offset:256
	ds_read_b128 v[218:221], v160
	ds_read_b128 v[222:225], v160 offset:256
	s_waitcnt vmcnt(0)
	s_barrier
	s_waitcnt lgkmcnt(0)
	s_setprio 1
	s_waitcnt lgkmcnt(0)
	v_mfma_f32_16x16x32_bf16 v[92:95], v[210:213], v[16:19], v[92:95]
	v_mfma_f32_16x16x32_bf16 v[16:19], v[214:217], v[16:19], v[178:181]
	v_mfma_f32_16x16x32_bf16 v[116:119], v[222:225], v[28:31], v[16:19]
	v_mfma_f32_16x16x32_bf16 v[16:19], v[210:213], v[32:35], v[84:87]
	v_mfma_f32_16x16x32_bf16 v[108:111], v[218:221], v[44:47], v[16:19]
	v_mfma_f32_16x16x32_bf16 v[16:19], v[214:217], v[32:35], v[182:185]
	v_mfma_f32_16x16x32_bf16 v[100:103], v[222:225], v[44:47], v[16:19]
	v_mfma_f32_16x16x32_bf16 v[16:19], v[210:213], v[48:51], v[76:79]
	v_mfma_f32_16x16x32_bf16 v[124:127], v[218:221], v[28:31], v[92:95]
	v_mfma_f32_16x16x32_bf16 v[92:95], v[218:221], v[206:209], v[16:19]
	v_mfma_f32_16x16x32_bf16 v[16:19], v[214:217], v[48:51], v[186:189]
	v_mfma_f32_16x16x32_bf16 v[84:87], v[222:225], v[206:209], v[16:19]
	v_mfma_f32_16x16x32_bf16 v[16:19], v[210:213], v[234:237], v[68:71]
	v_mfma_f32_16x16x32_bf16 v[76:79], v[218:221], v[238:241], v[16:19]
	v_mfma_f32_16x16x32_bf16 v[16:19], v[214:217], v[234:237], v[190:193]
	v_mfma_f32_16x16x32_bf16 v[68:71], v[222:225], v[238:241], v[16:19]
	s_setprio 0
	s_barrier
	ds_read_b128 v[178:181], v150 offset:49152
	ds_read_b128 v[182:185], v150 offset:50176
	ds_read_b128 v[186:189], v150 offset:51200
	ds_read_b128 v[190:193], v150 offset:52224
	ds_read_b128 v[206:209], v150 offset:53248
	ds_read_b128 v[234:237], v150 offset:54272
	ds_read_b128 v[238:241], v150 offset:55296
	ds_read_b128 v[242:245], v150 offset:56320
	s_barrier
	s_waitcnt lgkmcnt(0)
	s_setprio 1
	s_waitcnt lgkmcnt(0)
	v_mfma_f32_16x16x32_bf16 v[16:19], v[0:3], v[178:181], v[60:63]
	v_mfma_f32_16x16x32_bf16 v[60:63], v[12:15], v[182:185], v[16:19]
	v_mfma_f32_16x16x32_bf16 v[16:19], v[198:201], v[178:181], v[56:59]
	v_mfma_f32_16x16x32_bf16 v[48:51], v[202:205], v[182:185], v[16:19]
	v_mfma_f32_16x16x32_bf16 v[16:19], v[0:3], v[186:189], v[52:55]
	v_mfma_f32_16x16x32_bf16 v[44:47], v[12:15], v[190:193], v[16:19]
	v_mfma_f32_16x16x32_bf16 v[16:19], v[198:201], v[186:189], v[226:229]
	v_mfma_f32_16x16x32_bf16 v[32:35], v[202:205], v[190:193], v[16:19]
	v_mfma_f32_16x16x32_bf16 v[16:19], v[0:3], v[206:209], v[230:233]
	v_mfma_f32_16x16x32_bf16 v[0:3], v[0:3], v[238:241], v[36:39]
	v_mfma_f32_16x16x32_bf16 v[28:31], v[12:15], v[234:237], v[16:19]
	v_mfma_f32_16x16x32_bf16 v[16:19], v[198:201], v[206:209], v[40:43]
	v_mfma_f32_16x16x32_bf16 v[12:15], v[12:15], v[242:245], v[0:3]
	v_mfma_f32_16x16x32_bf16 v[0:3], v[198:201], v[238:241], v[162:165]
	v_mfma_f32_16x16x32_bf16 v[16:19], v[202:205], v[234:237], v[16:19]
	v_mfma_f32_16x16x32_bf16 v[0:3], v[202:205], v[242:245], v[0:3]
	s_setprio 0
	s_setprio 1
	v_mfma_f32_16x16x32_bf16 v[20:23], v[210:213], v[186:189], v[20:23]
	v_mfma_f32_16x16x32_bf16 v[36:39], v[210:213], v[178:181], v[166:169]
	v_mfma_f32_16x16x32_bf16 v[40:43], v[218:221], v[190:193], v[20:23]
	v_mfma_f32_16x16x32_bf16 v[20:23], v[214:217], v[186:189], v[170:173]
	v_mfma_f32_16x16x32_bf16 v[56:59], v[218:221], v[182:185], v[36:39]
	v_mfma_f32_16x16x32_bf16 v[24:27], v[214:217], v[178:181], v[24:27]
	v_mfma_f32_16x16x32_bf16 v[36:39], v[222:225], v[190:193], v[20:23]
	v_mfma_f32_16x16x32_bf16 v[20:23], v[210:213], v[206:209], v[174:177]
	v_mfma_f32_16x16x32_bf16 v[8:11], v[214:217], v[206:209], v[8:11]
	v_mfma_f32_16x16x32_bf16 v[4:7], v[210:213], v[238:241], v[4:7]
	v_mfma_f32_16x16x32_bf16 v[52:55], v[222:225], v[182:185], v[24:27]
	v_mfma_f32_16x16x32_bf16 v[24:27], v[218:221], v[234:237], v[20:23]
	v_mfma_f32_16x16x32_bf16 v[20:23], v[222:225], v[234:237], v[8:11]
	v_mfma_f32_16x16x32_bf16 v[8:11], v[218:221], v[242:245], v[4:7]
	v_mfma_f32_16x16x32_bf16 v[4:7], v[214:217], v[238:241], v[194:197]
	v_mfma_f32_16x16x32_bf16 v[4:7], v[222:225], v[242:245], v[4:7]
	s_setprio 0
	s_barrier
	s_and_saveexec_b64 s[66:67], s[2:3]
	s_cbranch_execz .LBB0_1099
	s_barrier
	s_branch .LBB0_1099

; #define STAGE(P, BASE, br, kt) do { const char* _gb = (const char*)(BASE) + ((size_t)(br) * K + (size_t)(kt) * BK) * 2; \
;     __builtin_amdgcn_global_load_lds((const unsigned*)(_gb + loff0), (unsigned*)((char*)(P) + tid * 16), 16, 0, 0); \
;     __builtin_amdgcn_global_load_lds((const unsigned*)(_gb + (size_t)K * 128 + loff0), (unsigned*)((char*)(P) + tid * 16 + 8192), 16, 0, 0); } while (0)
; #define LDA(dst, b, h) for (int m = 0; m < 4; ++m) { \
;     dst[m][0] = *reinterpret_cast<const bf16x8*>((char*)SA(b, h) + aoff0 + m * 2048); \
;     dst[m][1] = *reinterpret_cast<const bf16x8*>((char*)SA(b, h) + aoff1 + m * 2048); }
; #define LDB(dst, b, h) for (int n = 0; n < 2; ++n) { \
;     dst[n][0] = *reinterpret_cast<const bf16x8*>((char*)SB(b, h) + boff0 + n * 256); \
;     dst[n][1] = *reinterpret_cast<const bf16x8*>((char*)SB(b, h) + boff1 + n * 256); }
; #define MMA(ai, bj, At, Btf) do { __builtin_amdgcn_s_setprio(1); \
;     for (int m = 0; m < 4; ++m) for (int n = 0; n < 2; ++n) for (int k = 0; k < 2; ++k) \
;       acc[ai][bj][m][n] = __builtin_amdgcn_mfma_f32_16x16x32_bf16(Btf[n][k], At[m][k], acc[ai][bj][m][n], 0, 0, 0); \
;     __builtin_amdgcn_s_setprio(0); } while (0)
; #define WAIT_V(n) asm volatile("s_waitcnt vmcnt(" #n ")" ::: "memory")
; #define WAIT_L(n) asm volatile("s_waitcnt lgkmcnt(" #n ")" ::: "memory")
; #define BAR __builtin_amdgcn_s_barrier()
; template <int EPI> ...
;     ...
;   for (int t = 0; t < nt - 2; t += 2) {
;     LDB(B0, 0, 0); SCHED; LDA(At, 0, 0); STAGE(SA(1, 1), A, brow + HALF, t + 1);
;     WAIT_L(8); BAR; WAIT_L(0); MMA(0, 0, At, B0); BAR; SCHED;
;     LDB(B1, 0, 1); STAGE(SB(0, 0), Bt, bcol, t + 2);
;     BAR; WAIT_L(0); MMA(0, 1, At, B1); BAR;
;     LDA(At, 0, 1); STAGE(SA(0, 0), A, brow, t + 2);
;     BAR; WAIT_L(0); MMA(1, 0, At, B0); BAR; SCHED;
;     STAGE(SB(0, 1), Bt, bcol + HALF, t + 2);
;     WAIT_V(6); BAR; MMA(1, 1, At, B1); BAR;
;     LDB(B0, 1, 0); SCHED; LDA(At, 1, 0); STAGE(SA(0, 1), A, brow + HALF, t + 2);
;     WAIT_L(8); BAR; WAIT_L(0); MMA(0, 0, At, B0); BAR; SCHED;
;     LDB(B1, 1, 1); STAGE(SB(1, 0), Bt, bcol, t + 3);
;     BAR; WAIT_L(0); MMA(0, 1, At, B1); BAR;
;     LDA(At, 1, 1); STAGE(SA(1, 0), A, brow, t + 3);
;     BAR; WAIT_L(0); MMA(1, 0, At, B0); BAR; SCHED;
;     STAGE(SB(1, 1), Bt, bcol + HALF, t + 3);
;     WAIT_V(6); BAR; MMA(1, 1, At, B1); BAR;
;   }
.LBB0_1152:
	ds_read_b128 v[160:163], v152
	ds_read_b128 v[164:167], v152 offset:256
	ds_read_b128 v[168:171], v153
	ds_read_b128 v[172:175], v153 offset:256
	v_lshl_add_u64 v[224:225], s[62:63], 0, v[132:133]
	v_readfirstlane_b32 s75, v150
	v_lshl_add_u64 v[208:209], v[224:225], 0, s[16:17]
	s_mov_b32 m0, s75
	v_readfirstlane_b32 s75, v151
	ds_read_b128 v[176:179], v149
	ds_read_b128 v[180:183], v149 offset:1024
	ds_read_b128 v[184:187], v149 offset:2048
	ds_read_b128 v[188:191], v149 offset:3072
	ds_read_b128 v[192:195], v149 offset:4096
	ds_read_b128 v[196:199], v149 offset:5120
	ds_read_b128 v[200:203], v149 offset:6144
	ds_read_b128 v[204:207], v149 offset:7168
	global_load_lds_dwordx4 v[208:209], off
	v_lshl_add_u64 v[208:209], v[224:225], 0, s[18:19]
	s_mov_b32 m0, s75
	s_nop 0
	global_load_lds_dwordx4 v[208:209], off
	s_waitcnt lgkmcnt(8)
	v_readfirstlane_b32 s75, v148
	v_lshl_add_u64 v[246:247], v[228:229], 0, s[56:57]
	s_mov_b32 m0, s75
	s_nop 0
	global_load_lds_dwordx4 v[246:247], off
	ds_read_b128 v[208:211], v154
	ds_read_b128 v[212:215], v154 offset:256
	ds_read_b128 v[216:219], v155
	ds_read_b128 v[220:223], v155 offset:256
	s_barrier
	s_waitcnt lgkmcnt(0)
	s_setprio 1
	s_waitcnt lgkmcnt(0)
	v_mfma_f32_16x16x32_bf16 v[124:127], v[160:163], v[176:179], v[124:127]
	v_mfma_f32_16x16x32_bf16 v[120:123], v[164:167], v[176:179], v[120:123]
	v_mfma_f32_16x16x32_bf16 v[116:119], v[160:163], v[184:187], v[116:119]
	v_mfma_f32_16x16x32_bf16 v[112:115], v[164:167], v[184:187], v[112:115]
	v_mfma_f32_16x16x32_bf16 v[108:111], v[160:163], v[192:195], v[108:111]
	v_mfma_f32_16x16x32_bf16 v[104:107], v[164:167], v[192:195], v[104:107]
	v_mfma_f32_16x16x32_bf16 v[100:103], v[160:163], v[200:203], v[100:103]
	v_mfma_f32_16x16x32_bf16 v[96:99], v[164:167], v[200:203], v[96:99]
	v_mfma_f32_16x16x32_bf16 v[124:127], v[168:171], v[180:183], v[124:127]
	v_mfma_f32_16x16x32_bf16 v[120:123], v[172:175], v[180:183], v[120:123]
	v_mfma_f32_16x16x32_bf16 v[116:119], v[168:171], v[188:191], v[116:119]
	v_mfma_f32_16x16x32_bf16 v[112:115], v[172:175], v[188:191], v[112:115]
	v_mfma_f32_16x16x32_bf16 v[108:111], v[168:171], v[196:199], v[108:111]
	v_mfma_f32_16x16x32_bf16 v[104:107], v[172:175], v[196:199], v[104:107]
	v_mfma_f32_16x16x32_bf16 v[100:103], v[168:171], v[204:207], v[100:103]
	v_mfma_f32_16x16x32_bf16 v[96:99], v[172:175], v[204:207], v[96:99]
	s_setprio 0
	s_waitcnt lgkmcnt(0)
	s_setprio 1
	s_waitcnt lgkmcnt(0)
	v_mfma_f32_16x16x32_bf16 v[92:95], v[208:211], v[176:179], v[92:95]
	v_mfma_f32_16x16x32_bf16 v[88:91], v[212:215], v[176:179], v[88:91]
	v_mfma_f32_16x16x32_bf16 v[84:87], v[208:211], v[184:187], v[84:87]
	v_mfma_f32_16x16x32_bf16 v[80:83], v[212:215], v[184:187], v[80:83]
	v_mfma_f32_16x16x32_bf16 v[76:79], v[208:211], v[192:195], v[76:79]
	v_mfma_f32_16x16x32_bf16 v[72:75], v[212:215], v[192:195], v[72:75]
	v_mfma_f32_16x16x32_bf16 v[68:71], v[208:211], v[200:203], v[68:71]
	v_mfma_f32_16x16x32_bf16 v[64:67], v[212:215], v[200:203], v[64:67]
	v_mfma_f32_16x16x32_bf16 v[92:95], v[216:219], v[180:183], v[92:95]
	v_mfma_f32_16x16x32_bf16 v[88:91], v[220:223], v[180:183], v[88:91]
	v_mfma_f32_16x16x32_bf16 v[84:87], v[216:219], v[188:191], v[84:87]
	v_mfma_f32_16x16x32_bf16 v[80:83], v[220:223], v[188:191], v[80:83]
	v_mfma_f32_16x16x32_bf16 v[76:79], v[216:219], v[196:199], v[76:79]
	v_mfma_f32_16x16x32_bf16 v[72:75], v[220:223], v[196:199], v[72:75]
	v_mfma_f32_16x16x32_bf16 v[68:71], v[216:219], v[204:207], v[68:71]
	v_mfma_f32_16x16x32_bf16 v[64:67], v[220:223], v[204:207], v[64:67]
	s_setprio 0
	s_barrier
	v_lshl_add_u64 v[226:227], s[64:65], 0, v[132:133]
	v_readfirstlane_b32 s75, v135
	v_lshl_add_u64 v[228:229], v[226:227], 0, s[20:21]
	s_mov_b32 m0, s75
	v_readfirstlane_b32 s75, v136
	global_load_lds_dwordx4 v[228:229], off
	v_lshl_add_u64 v[228:229], v[226:227], 0, s[22:23]
	s_mov_b32 m0, s75
	s_nop 0
	global_load_lds_dwordx4 v[228:229], off
	v_readfirstlane_b32 s75, v137
	v_lshl_add_u64 v[228:229], v[224:225], 0, s[24:25]
	s_mov_b32 m0, s75
	v_readfirstlane_b32 s75, v138
	ds_read_b128 v[176:179], v149 offset:16384
	ds_read_b128 v[180:183], v149 offset:17408
	ds_read_b128 v[184:187], v149 offset:18432
	ds_read_b128 v[188:191], v149 offset:19456
	ds_read_b128 v[192:195], v149 offset:20480
	ds_read_b128 v[196:199], v149 offset:21504
	ds_read_b128 v[200:203], v149 offset:22528
	ds_read_b128 v[204:207], v149 offset:23552
	global_load_lds_dwordx4 v[228:229], off
	v_lshl_add_u64 v[228:229], v[224:225], 0, s[26:27]
	s_mov_b32 m0, s75
	s_nop 0
	global_load_lds_dwordx4 v[228:229], off
	v_lshl_add_u64 v[228:229], s[60:61], 0, v[132:133]
	v_readfirstlane_b32 s75, v139
	v_lshl_add_u64 v[246:247], v[228:229], 0, s[28:29]
	s_mov_b32 m0, s75
	v_readfirstlane_b32 s75, v140
	global_load_lds_dwordx4 v[246:247], off
	s_waitcnt vmcnt(5)
	s_barrier
; #define STAGE(P, BASE, br, kt) do { const char* _gb = (const char*)(BASE) + ((size_t)(br) * K + (size_t)(kt) * BK) * 2; \
;     __builtin_amdgcn_global_load_lds((const unsigned*)(_gb + loff0), (unsigned*)((char*)(P) + tid * 16), 16, 0, 0); \
;     __builtin_amdgcn_global_load_lds((const unsigned*)(_gb + (size_t)K * 128 + loff0), (unsigned*)((char*)(P) + tid * 16 + 8192), 16, 0, 0); } while (0)
; #define LDA(dst, b, h) for (int m = 0; m < 4; ++m) { \
;     dst[m][0] = *reinterpret_cast<const bf16x8*>((char*)SA(b, h) + aoff0 + m * 2048); \
;     dst[m][1] = *reinterpret_cast<const bf16x8*>((char*)SA(b, h) + aoff1 + m * 2048); }
; #define LDB(dst, b, h) for (int n = 0; n < 2; ++n) { \
;     dst[n][0] = *reinterpret_cast<const bf16x8*>((char*)SB(b, h) + boff0 + n * 256); \
;     dst[n][1] = *reinterpret_cast<const bf16x8*>((char*)SB(b, h) + boff1 + n * 256); }
; #define MMA(ai, bj, At, Btf) do { __builtin_amdgcn_s_setprio(1); \
;     for (int m = 0; m < 4; ++m) for (int n = 0; n < 2; ++n) for (int k = 0; k < 2; ++k) \
;       acc[ai][bj][m][n] = __builtin_amdgcn_mfma_f32_16x16x32_bf16(Btf[n][k], At[m][k], acc[ai][bj][m][n], 0, 0, 0); \
;     __builtin_amdgcn_s_setprio(0); } while (0)
; #define WAIT_V(n) asm volatile("s_waitcnt vmcnt(" #n ")" ::: "memory")
; #define WAIT_L(n) asm volatile("s_waitcnt lgkmcnt(" #n ")" ::: "memory")
; #define BAR __builtin_amdgcn_s_barrier()
; template <int EPI> ...
;     ...
;   for (int t = 0; t < nt - 2; t += 2) {
;     LDB(B0, 0, 0); SCHED; LDA(At, 0, 0); STAGE(SA(1, 1), A, brow + HALF, t + 1);
;     WAIT_L(8); BAR; WAIT_L(0); MMA(0, 0, At, B0); BAR; SCHED;
;     LDB(B1, 0, 1); STAGE(SB(0, 0), Bt, bcol, t + 2);
;     BAR; WAIT_L(0); MMA(0, 1, At, B1); BAR;
;     LDA(At, 0, 1); STAGE(SA(0, 0), A, brow, t + 2);
;     BAR; WAIT_L(0); MMA(1, 0, At, B0); BAR; SCHED;
;     STAGE(SB(0, 1), Bt, bcol + HALF, t + 2);
;     WAIT_V(6); BAR; MMA(1, 1, At, B1); BAR;
;     LDB(B0, 1, 0); SCHED; LDA(At, 1, 0); STAGE(SA(0, 1), A, brow + HALF, t + 2);
;     WAIT_L(8); BAR; WAIT_L(0); MMA(0, 0, At, B0); BAR; SCHED;
;     LDB(B1, 1, 1); STAGE(SB(1, 0), Bt, bcol, t + 3);
;     BAR; WAIT_L(0); MMA(0, 1, At, B1); BAR;
;     LDA(At, 1, 1); STAGE(SA(1, 0), A, brow, t + 3);
;     BAR; WAIT_L(0); MMA(1, 0, At, B0); BAR; SCHED;
;     STAGE(SB(1, 1), Bt, bcol + HALF, t + 3);
;     WAIT_V(6); BAR; MMA(1, 1, At, B1); BAR;
;   }
	s_waitcnt lgkmcnt(0)
	s_setprio 1
	s_waitcnt lgkmcnt(0)
	v_mfma_f32_16x16x32_bf16 v[60:63], v[160:163], v[176:179], v[60:63]
	v_mfma_f32_16x16x32_bf16 v[56:59], v[164:167], v[176:179], v[56:59]
	v_mfma_f32_16x16x32_bf16 v[52:55], v[160:163], v[184:187], v[52:55]
	v_mfma_f32_16x16x32_bf16 v[48:51], v[164:167], v[184:187], v[48:51]
	v_mfma_f32_16x16x32_bf16 v[44:47], v[160:163], v[192:195], v[44:47]
	v_mfma_f32_16x16x32_bf16 v[40:43], v[164:167], v[192:195], v[40:43]
	v_mfma_f32_16x16x32_bf16 v[36:39], v[160:163], v[200:203], v[36:39]
	v_mfma_f32_16x16x32_bf16 v[32:35], v[164:167], v[200:203], v[32:35]
	v_mfma_f32_16x16x32_bf16 v[60:63], v[168:171], v[180:183], v[60:63]
	v_mfma_f32_16x16x32_bf16 v[56:59], v[172:175], v[180:183], v[56:59]
	v_mfma_f32_16x16x32_bf16 v[52:55], v[168:171], v[188:191], v[52:55]
	v_mfma_f32_16x16x32_bf16 v[48:51], v[172:175], v[188:191], v[48:51]
	v_mfma_f32_16x16x32_bf16 v[44:47], v[168:171], v[196:199], v[44:47]
	v_mfma_f32_16x16x32_bf16 v[40:43], v[172:175], v[196:199], v[40:43]
	v_mfma_f32_16x16x32_bf16 v[36:39], v[168:171], v[204:207], v[36:39]
	v_mfma_f32_16x16x32_bf16 v[32:35], v[172:175], v[204:207], v[32:35]
	s_setprio 0
	s_setprio 1
	v_mfma_f32_16x16x32_bf16 v[28:31], v[208:211], v[176:179], v[28:31]
	v_mfma_f32_16x16x32_bf16 v[24:27], v[212:215], v[176:179], v[24:27]
	v_mfma_f32_16x16x32_bf16 v[20:23], v[208:211], v[184:187], v[20:23]
	v_mfma_f32_16x16x32_bf16 v[16:19], v[212:215], v[184:187], v[16:19]
	v_mfma_f32_16x16x32_bf16 v[12:15], v[208:211], v[192:195], v[12:15]
	v_mfma_f32_16x16x32_bf16 v[8:11], v[212:215], v[192:195], v[8:11]
	v_mfma_f32_16x16x32_bf16 v[4:7], v[208:211], v[200:203], v[4:7]
	v_mfma_f32_16x16x32_bf16 v[0:3], v[212:215], v[200:203], v[0:3]
	v_mfma_f32_16x16x32_bf16 v[28:31], v[216:219], v[180:183], v[28:31]
	v_mfma_f32_16x16x32_bf16 v[24:27], v[220:223], v[180:183], v[24:27]
	v_mfma_f32_16x16x32_bf16 v[20:23], v[216:219], v[188:191], v[20:23]
	v_mfma_f32_16x16x32_bf16 v[16:19], v[220:223], v[188:191], v[16:19]
	v_mfma_f32_16x16x32_bf16 v[12:15], v[216:219], v[196:199], v[12:15]
	v_mfma_f32_16x16x32_bf16 v[8:11], v[220:223], v[196:199], v[8:11]
	v_mfma_f32_16x16x32_bf16 v[4:7], v[216:219], v[204:207], v[4:7]
	v_mfma_f32_16x16x32_bf16 v[0:3], v[220:223], v[204:207], v[0:3]
	s_setprio 0
	s_barrier
	ds_read_b128 v[160:163], v156
	ds_read_b128 v[164:167], v156 offset:256
	ds_read_b128 v[168:171], v157
	ds_read_b128 v[172:175], v157 offset:256
	v_readfirstlane_b32 s75, v141
	v_lshl_add_u64 v[208:209], v[224:225], 0, s[36:37]
	s_mov_b32 m0, s75
	v_readfirstlane_b32 s75, v142
	ds_read_b128 v[176:179], v149 offset:32768
	ds_read_b128 v[180:183], v149 offset:33792
	ds_read_b128 v[184:187], v149 offset:34816
	ds_read_b128 v[188:191], v149 offset:35840
	ds_read_b128 v[192:195], v149 offset:36864
	ds_read_b128 v[196:199], v149 offset:37888
	ds_read_b128 v[200:203], v149 offset:38912
	ds_read_b128 v[204:207], v149 offset:39936
	global_load_lds_dwordx4 v[208:209], off
	v_lshl_add_u64 v[208:209], v[224:225], 0, s[38:39]
	s_mov_b32 m0, s75
	s_nop 0
	global_load_lds_dwordx4 v[208:209], off
	s_waitcnt lgkmcnt(8)
	v_readfirstlane_b32 s75, v140
	v_lshl_add_u64 v[246:247], v[228:229], 0, s[30:31]
	s_mov_b32 m0, s75
	s_nop 0
	global_load_lds_dwordx4 v[246:247], off
	ds_read_b128 v[208:211], v158
	ds_read_b128 v[212:215], v158 offset:256
	ds_read_b128 v[216:219], v159
	ds_read_b128 v[220:223], v159 offset:256
	s_barrier
	s_waitcnt lgkmcnt(0)
	s_setprio 1
	s_waitcnt lgkmcnt(0)
	v_mfma_f32_16x16x32_bf16 v[124:127], v[160:163], v[176:179], v[124:127]
	v_mfma_f32_16x16x32_bf16 v[120:123], v[164:167], v[176:179], v[120:123]
	v_mfma_f32_16x16x32_bf16 v[116:119], v[160:163], v[184:187], v[116:119]
	v_mfma_f32_16x16x32_bf16 v[112:115], v[164:167], v[184:187], v[112:115]
	v_mfma_f32_16x16x32_bf16 v[108:111], v[160:163], v[192:195], v[108:111]
	v_mfma_f32_16x16x32_bf16 v[104:107], v[164:167], v[192:195], v[104:107]
	v_mfma_f32_16x16x32_bf16 v[100:103], v[160:163], v[200:203], v[100:103]
	v_mfma_f32_16x16x32_bf16 v[96:99], v[164:167], v[200:203], v[96:99]
	v_mfma_f32_16x16x32_bf16 v[124:127], v[168:171], v[180:183], v[124:127]
	v_mfma_f32_16x16x32_bf16 v[120:123], v[172:175], v[180:183], v[120:123]
	v_mfma_f32_16x16x32_bf16 v[116:119], v[168:171], v[188:191], v[116:119]
	v_mfma_f32_16x16x32_bf16 v[112:115], v[172:175], v[188:191], v[112:115]
	v_mfma_f32_16x16x32_bf16 v[108:111], v[168:171], v[196:199], v[108:111]
	v_mfma_f32_16x16x32_bf16 v[104:107], v[172:175], v[196:199], v[104:107]
	v_mfma_f32_16x16x32_bf16 v[100:103], v[168:171], v[204:207], v[100:103]
	v_mfma_f32_16x16x32_bf16 v[96:99], v[172:175], v[204:207], v[96:99]
	s_setprio 0
	s_waitcnt lgkmcnt(0)
	s_setprio 1
	s_waitcnt lgkmcnt(0)
	v_mfma_f32_16x16x32_bf16 v[92:95], v[208:211], v[176:179], v[92:95]
	v_mfma_f32_16x16x32_bf16 v[88:91], v[212:215], v[176:179], v[88:91]
	v_mfma_f32_16x16x32_bf16 v[84:87], v[208:211], v[184:187], v[84:87]
	v_mfma_f32_16x16x32_bf16 v[80:83], v[212:215], v[184:187], v[80:83]
	v_mfma_f32_16x16x32_bf16 v[76:79], v[208:211], v[192:195], v[76:79]
	v_mfma_f32_16x16x32_bf16 v[72:75], v[212:215], v[192:195], v[72:75]
	v_mfma_f32_16x16x32_bf16 v[68:71], v[208:211], v[200:203], v[68:71]
	v_mfma_f32_16x16x32_bf16 v[64:67], v[212:215], v[200:203], v[64:67]
	v_mfma_f32_16x16x32_bf16 v[92:95], v[216:219], v[180:183], v[92:95]
	v_mfma_f32_16x16x32_bf16 v[88:91], v[220:223], v[180:183], v[88:91]
	v_mfma_f32_16x16x32_bf16 v[84:87], v[216:219], v[188:191], v[84:87]
	v_mfma_f32_16x16x32_bf16 v[80:83], v[220:223], v[188:191], v[80:83]
	v_mfma_f32_16x16x32_bf16 v[76:79], v[216:219], v[196:199], v[76:79]
	v_mfma_f32_16x16x32_bf16 v[72:75], v[220:223], v[196:199], v[72:75]
	v_mfma_f32_16x16x32_bf16 v[68:71], v[216:219], v[204:207], v[68:71]
	v_mfma_f32_16x16x32_bf16 v[64:67], v[220:223], v[204:207], v[64:67]
	s_setprio 0
	s_barrier
; #define STAGE(P, BASE, br, kt) do { const char* _gb = (const char*)(BASE) + ((size_t)(br) * K + (size_t)(kt) * BK) * 2; \
;     __builtin_amdgcn_global_load_lds((const unsigned*)(_gb + loff0), (unsigned*)((char*)(P) + tid * 16), 16, 0, 0); \
;     __builtin_amdgcn_global_load_lds((const unsigned*)(_gb + (size_t)K * 128 + loff0), (unsigned*)((char*)(P) + tid * 16 + 8192), 16, 0, 0); } while (0)
; #define LDA(dst, b, h) for (int m = 0; m < 4; ++m) { \
;     dst[m][0] = *reinterpret_cast<const bf16x8*>((char*)SA(b, h) + aoff0 + m * 2048); \
;     dst[m][1] = *reinterpret_cast<const bf16x8*>((char*)SA(b, h) + aoff1 + m * 2048); }
; #define LDB(dst, b, h) for (int n = 0; n < 2; ++n) { \
;     dst[n][0] = *reinterpret_cast<const bf16x8*>((char*)SB(b, h) + boff0 + n * 256); \
;     dst[n][1] = *reinterpret_cast<const bf16x8*>((char*)SB(b, h) + boff1 + n * 256); }
; #define MMA(ai, bj, At, Btf) do { __builtin_amdgcn_s_setprio(1); \
;     for (int m = 0; m < 4; ++m) for (int n = 0; n < 2; ++n) for (int k = 0; k < 2; ++k) \
;       acc[ai][bj][m][n] = __builtin_amdgcn_mfma_f32_16x16x32_bf16(Btf[n][k], At[m][k], acc[ai][bj][m][n], 0, 0, 0); \
;     __builtin_amdgcn_s_setprio(0); } while (0)
; #define WAIT_V(n) asm volatile("s_waitcnt vmcnt(" #n ")" ::: "memory")
; template <int EPI> ...
;     ...
;   for (int t = 0; t < nt - 2; t += 2) {
;     LDB(B0, 0, 0); SCHED; LDA(At, 0, 0); STAGE(SA(1, 1), A, brow + HALF, t + 1);
;     WAIT_L(8); BAR; WAIT_L(0); MMA(0, 0, At, B0); BAR; SCHED;
;     LDB(B1, 0, 1); STAGE(SB(0, 0), Bt, bcol, t + 2);
;     BAR; WAIT_L(0); MMA(0, 1, At, B1); BAR;
;     LDA(At, 0, 1); STAGE(SA(0, 0), A, brow, t + 2);
;     BAR; WAIT_L(0); MMA(1, 0, At, B0); BAR; SCHED;
;     STAGE(SB(0, 1), Bt, bcol + HALF, t + 2);
;     WAIT_V(6); BAR; MMA(1, 1, At, B1); BAR;
;     LDB(B0, 1, 0); SCHED; LDA(At, 1, 0); STAGE(SA(0, 1), A, brow + HALF, t + 2);
;     WAIT_L(8); BAR; WAIT_L(0); MMA(0, 0, At, B0); BAR; SCHED;
;     LDB(B1, 1, 1); STAGE(SB(1, 0), Bt, bcol, t + 3);
;     BAR; WAIT_L(0); MMA(0, 1, At, B1); BAR;
;     LDA(At, 1, 1); STAGE(SA(1, 0), A, brow, t + 3);
;     BAR; WAIT_L(0); MMA(1, 0, At, B0); BAR; SCHED;
;     STAGE(SB(1, 1), Bt, bcol + HALF, t + 3);
;     WAIT_V(6); BAR; MMA(1, 1, At, B1); BAR;
;   }
;   { LDB(B0, 0, 0); LDA(At, 0, 0); STAGE(SA(1, 1), A, brow + HALF, nt - 1);
;     BAR; WAIT_L(0); MMA(0, 0, At, B0); BAR;
	v_readfirstlane_b32 s75, v143
	v_lshl_add_u64 v[230:231], v[226:227], 0, s[46:47]
	s_mov_b32 m0, s75
	v_readfirstlane_b32 s75, v144
	global_load_lds_dwordx4 v[230:231], off
	v_lshl_add_u64 v[226:227], v[226:227], 0, s[48:49]
	s_mov_b32 m0, s75
	s_nop 0
	global_load_lds_dwordx4 v[226:227], off
	v_readfirstlane_b32 s75, v145
	v_lshl_add_u64 v[226:227], v[224:225], 0, s[50:51]
	s_mov_b32 m0, s75
	v_readfirstlane_b32 s75, v146
	ds_read_b128 v[176:179], v149 offset:49152
	ds_read_b128 v[180:183], v149 offset:50176
	ds_read_b128 v[184:187], v149 offset:51200
	ds_read_b128 v[188:191], v149 offset:52224
	ds_read_b128 v[192:195], v149 offset:53248
	ds_read_b128 v[196:199], v149 offset:54272
	ds_read_b128 v[200:203], v149 offset:55296
	ds_read_b128 v[204:207], v149 offset:56320
	global_load_lds_dwordx4 v[226:227], off
	v_lshl_add_u64 v[224:225], v[224:225], 0, s[52:53]
	s_mov_b32 m0, s75
	s_nop 0
	global_load_lds_dwordx4 v[224:225], off
	v_readfirstlane_b32 s75, v147
	v_lshl_add_u64 v[246:247], v[228:229], 0, s[54:55]
	s_mov_b32 m0, s75
	v_readfirstlane_b32 s75, v148
	global_load_lds_dwordx4 v[246:247], off
	s_waitcnt vmcnt(5)
	s_barrier
	s_waitcnt lgkmcnt(0)
	s_setprio 1
	s_waitcnt lgkmcnt(0)
	v_mfma_f32_16x16x32_bf16 v[60:63], v[160:163], v[176:179], v[60:63]
	v_mfma_f32_16x16x32_bf16 v[56:59], v[164:167], v[176:179], v[56:59]
	v_mfma_f32_16x16x32_bf16 v[52:55], v[160:163], v[184:187], v[52:55]
	v_mfma_f32_16x16x32_bf16 v[48:51], v[164:167], v[184:187], v[48:51]
	v_mfma_f32_16x16x32_bf16 v[44:47], v[160:163], v[192:195], v[44:47]
	v_mfma_f32_16x16x32_bf16 v[40:43], v[164:167], v[192:195], v[40:43]
	v_mfma_f32_16x16x32_bf16 v[36:39], v[160:163], v[200:203], v[36:39]
	v_mfma_f32_16x16x32_bf16 v[32:35], v[164:167], v[200:203], v[32:35]
	v_mfma_f32_16x16x32_bf16 v[60:63], v[168:171], v[180:183], v[60:63]
	v_mfma_f32_16x16x32_bf16 v[56:59], v[172:175], v[180:183], v[56:59]
	v_mfma_f32_16x16x32_bf16 v[52:55], v[168:171], v[188:191], v[52:55]
	v_mfma_f32_16x16x32_bf16 v[48:51], v[172:175], v[188:191], v[48:51]
	v_mfma_f32_16x16x32_bf16 v[44:47], v[168:171], v[196:199], v[44:47]
	v_mfma_f32_16x16x32_bf16 v[40:43], v[172:175], v[196:199], v[40:43]
	v_mfma_f32_16x16x32_bf16 v[36:39], v[168:171], v[204:207], v[36:39]
	v_mfma_f32_16x16x32_bf16 v[32:35], v[172:175], v[204:207], v[32:35]
	s_setprio 0
	s_setprio 1
	v_mfma_f32_16x16x32_bf16 v[28:31], v[208:211], v[176:179], v[28:31]
	v_mfma_f32_16x16x32_bf16 v[24:27], v[212:215], v[176:179], v[24:27]
	v_mfma_f32_16x16x32_bf16 v[20:23], v[208:211], v[184:187], v[20:23]
	v_mfma_f32_16x16x32_bf16 v[16:19], v[212:215], v[184:187], v[16:19]
	v_mfma_f32_16x16x32_bf16 v[12:15], v[208:211], v[192:195], v[12:15]
	v_mfma_f32_16x16x32_bf16 v[8:11], v[212:215], v[192:195], v[8:11]
	v_mfma_f32_16x16x32_bf16 v[4:7], v[208:211], v[200:203], v[4:7]
	v_mfma_f32_16x16x32_bf16 v[0:3], v[212:215], v[200:203], v[0:3]
	v_mfma_f32_16x16x32_bf16 v[28:31], v[216:219], v[180:183], v[28:31]
	v_mfma_f32_16x16x32_bf16 v[24:27], v[220:223], v[180:183], v[24:27]
	v_mfma_f32_16x16x32_bf16 v[20:23], v[216:219], v[188:191], v[20:23]
	v_mfma_f32_16x16x32_bf16 v[16:19], v[220:223], v[188:191], v[16:19]
	v_mfma_f32_16x16x32_bf16 v[12:15], v[216:219], v[196:199], v[12:15]
	v_mfma_f32_16x16x32_bf16 v[8:11], v[220:223], v[196:199], v[8:11]
	v_mfma_f32_16x16x32_bf16 v[4:7], v[216:219], v[204:207], v[4:7]
	v_mfma_f32_16x16x32_bf16 v[0:3], v[220:223], v[204:207], v[0:3]
	s_setprio 0
	s_add_i32 s74, s74, 2
	s_add_u32 s60, s60, 0x100
	s_addc_u32 s61, s61, 0
	s_add_u32 s62, s62, 0x100
	s_addc_u32 s63, s63, 0
	s_add_u32 s64, s64, 0x100
	s_addc_u32 s65, s65, 0
	s_cmpk_lt_u32 s74, 0x54
	s_barrier
	s_cbranch_scc1 .LBB0_1152
	v_readfirstlane_b32 s75, v148
	v_lshl_add_u64 v[246:247], v[228:229], 0, s[56:57]
	s_mov_b32 m0, s75
	s_nop 0
	global_load_lds_dwordx4 v[246:247], off
	s_add_u32 s60, s68, s73
	s_addc_u32 s61, s69, s72
	v_lshl_add_u64 v[208:209], s[60:61], 0, v[128:129]
	v_readfirstlane_b32 s60, v150
	s_mov_b32 m0, s60
	v_readfirstlane_b32 s60, v151
	ds_read_b128 v[160:163], v152
	ds_read_b128 v[164:167], v152 offset:256
	ds_read_b128 v[168:171], v153
	ds_read_b128 v[172:175], v153 offset:256
	ds_read_b128 v[176:179], v149
	ds_read_b128 v[180:183], v149 offset:1024
	ds_read_b128 v[184:187], v149 offset:2048
	ds_read_b128 v[188:191], v149 offset:3072
	ds_read_b128 v[192:195], v149 offset:4096
	ds_read_b128 v[196:199], v149 offset:5120
	ds_read_b128 v[200:203], v149 offset:6144
	ds_read_b128 v[204:207], v149 offset:7168
	global_load_lds_dwordx4 v[208:209], off
	v_lshl_add_u64 v[208:209], v[208:209], 0, s[8:9]
	s_mov_b32 m0, s60
	s_nop 0
	global_load_lds_dwordx4 v[208:209], off
	s_barrier
	s_waitcnt lgkmcnt(0)
	s_setprio 1
	s_waitcnt lgkmcnt(0)
	v_mfma_f32_16x16x32_bf16 v[124:127], v[160:163], v[176:179], v[124:127]
	v_mfma_f32_16x16x32_bf16 v[116:119], v[160:163], v[184:187], v[116:119]
	v_mfma_f32_16x16x32_bf16 v[108:111], v[160:163], v[192:195], v[108:111]
	v_mfma_f32_16x16x32_bf16 v[100:103], v[160:163], v[200:203], v[100:103]
	v_mfma_f32_16x16x32_bf16 v[96:99], v[164:167], v[200:203], v[96:99]
	v_mfma_f32_16x16x32_bf16 v[124:127], v[168:171], v[180:183], v[124:127]
	v_mfma_f32_16x16x32_bf16 v[120:123], v[164:167], v[176:179], v[120:123]
	v_mfma_f32_16x16x32_bf16 v[116:119], v[168:171], v[188:191], v[116:119]
	v_mfma_f32_16x16x32_bf16 v[112:115], v[164:167], v[184:187], v[112:115]
	v_mfma_f32_16x16x32_bf16 v[108:111], v[168:171], v[196:199], v[108:111]
	v_mfma_f32_16x16x32_bf16 v[104:107], v[164:167], v[192:195], v[104:107]
	v_mfma_f32_16x16x32_bf16 v[100:103], v[168:171], v[204:207], v[100:103]
	v_mfma_f32_16x16x32_bf16 v[96:99], v[172:175], v[204:207], v[96:99]
	v_mfma_f32_16x16x32_bf16 v[208:211], v[172:175], v[180:183], v[120:123]
	v_mfma_f32_16x16x32_bf16 v[212:215], v[172:175], v[188:191], v[112:115]
	v_mfma_f32_16x16x32_bf16 v[216:219], v[172:175], v[196:199], v[104:107]
	s_setprio 0
	s_barrier
; #define LDA(dst, b, h) for (int m = 0; m < 4; ++m) { \
;     dst[m][0] = *reinterpret_cast<const bf16x8*>((char*)SA(b, h) + aoff0 + m * 2048); \
;     dst[m][1] = *reinterpret_cast<const bf16x8*>((char*)SA(b, h) + aoff1 + m * 2048); }
; #define LDB(dst, b, h) for (int n = 0; n < 2; ++n) { \
;     dst[n][0] = *reinterpret_cast<const bf16x8*>((char*)SB(b, h) + boff0 + n * 256); \
;     dst[n][1] = *reinterpret_cast<const bf16x8*>((char*)SB(b, h) + boff1 + n * 256); }
; #define MMA(ai, bj, At, Btf) do { __builtin_amdgcn_s_setprio(1); \
;     for (int m = 0; m < 4; ++m) for (int n = 0; n < 2; ++n) for (int k = 0; k < 2; ++k) \
;       acc[ai][bj][m][n] = __builtin_amdgcn_mfma_f32_16x16x32_bf16(Btf[n][k], At[m][k], acc[ai][bj][m][n], 0, 0, 0); \
;     __builtin_amdgcn_s_setprio(0); } while (0)
; #define WAIT_V(n) asm volatile("s_waitcnt vmcnt(" #n ")" ::: "memory")
; #define WAIT_L(n) asm volatile("s_waitcnt lgkmcnt(" #n ")" ::: "memory")
; #define BAR __builtin_amdgcn_s_barrier()
; template <int EPI> ...
;     ...
;     LDB(B1, 0, 1); BAR; WAIT_L(0); MMA(0, 1, At, B1); BAR;
;     LDA(At, 0, 1); WAIT_V(4); BAR; WAIT_L(0); MMA(1, 0, At, B0); MMA(1, 1, At, B1); BAR; }
;   { LDB(B0, 1, 0); LDA(At, 1, 0); WAIT_V(2); BAR; WAIT_L(0); MMA(0, 0, At, B0); BAR;
	s_nop 0
	ds_read_b128 v[104:107], v154
	ds_read_b128 v[112:115], v154 offset:256
	ds_read_b128 v[120:123], v155
	ds_read_b128 v[220:223], v155 offset:256
	s_barrier
	s_waitcnt lgkmcnt(0)
	s_setprio 1
	s_waitcnt lgkmcnt(0)
	v_mfma_f32_16x16x32_bf16 v[84:87], v[104:107], v[184:187], v[84:87]
	v_mfma_f32_16x16x32_bf16 v[76:79], v[104:107], v[192:195], v[76:79]
	v_mfma_f32_16x16x32_bf16 v[72:75], v[112:115], v[192:195], v[72:75]
	v_mfma_f32_16x16x32_bf16 v[92:95], v[104:107], v[176:179], v[92:95]
	v_mfma_f32_16x16x32_bf16 v[88:91], v[112:115], v[176:179], v[88:91]
	v_mfma_f32_16x16x32_bf16 v[84:87], v[120:123], v[188:191], v[84:87]
	v_mfma_f32_16x16x32_bf16 v[80:83], v[112:115], v[184:187], v[80:83]
	v_mfma_f32_16x16x32_bf16 v[76:79], v[120:123], v[196:199], v[76:79]
	v_mfma_f32_16x16x32_bf16 v[72:75], v[220:223], v[196:199], v[72:75]
	v_mfma_f32_16x16x32_bf16 v[68:71], v[104:107], v[200:203], v[68:71]
	v_mfma_f32_16x16x32_bf16 v[64:67], v[112:115], v[200:203], v[64:67]
	v_mfma_f32_16x16x32_bf16 v[224:227], v[120:123], v[180:183], v[92:95]
	v_mfma_f32_16x16x32_bf16 v[176:179], v[220:223], v[180:183], v[88:91]
	v_mfma_f32_16x16x32_bf16 v[180:183], v[220:223], v[188:191], v[80:83]
	v_mfma_f32_16x16x32_bf16 v[184:187], v[120:123], v[204:207], v[68:71]
	v_mfma_f32_16x16x32_bf16 v[188:191], v[220:223], v[204:207], v[64:67]
	s_setprio 0
	s_barrier
	s_nop 0
	ds_read_b128 v[64:67], v149 offset:16384
	ds_read_b128 v[68:71], v149 offset:17408
	ds_read_b128 v[80:83], v149 offset:18432
	ds_read_b128 v[88:91], v149 offset:19456
	ds_read_b128 v[92:95], v149 offset:20480
	ds_read_b128 v[192:195], v149 offset:21504
	ds_read_b128 v[196:199], v149 offset:22528
	ds_read_b128 v[200:203], v149 offset:23552
	s_waitcnt vmcnt(4)
	s_barrier
	s_waitcnt lgkmcnt(0)
	s_setprio 1
	s_waitcnt lgkmcnt(0)
	v_mfma_f32_16x16x32_bf16 v[52:55], v[160:163], v[80:83], v[52:55]
	v_mfma_f32_16x16x32_bf16 v[44:47], v[160:163], v[92:95], v[44:47]
	v_mfma_f32_16x16x32_bf16 v[36:39], v[160:163], v[196:199], v[36:39]
	v_mfma_f32_16x16x32_bf16 v[60:63], v[160:163], v[64:67], v[60:63]
	v_mfma_f32_16x16x32_bf16 v[56:59], v[164:167], v[64:67], v[56:59]
	v_mfma_f32_16x16x32_bf16 v[52:55], v[168:171], v[88:91], v[52:55]
	v_mfma_f32_16x16x32_bf16 v[48:51], v[164:167], v[80:83], v[48:51]
	v_mfma_f32_16x16x32_bf16 v[44:47], v[168:171], v[192:195], v[44:47]
	v_mfma_f32_16x16x32_bf16 v[40:43], v[164:167], v[92:95], v[40:43]
	v_mfma_f32_16x16x32_bf16 v[36:39], v[168:171], v[200:203], v[36:39]
	v_mfma_f32_16x16x32_bf16 v[32:35], v[164:167], v[196:199], v[32:35]
	v_mfma_f32_16x16x32_bf16 v[204:207], v[168:171], v[68:71], v[60:63]
	v_mfma_f32_16x16x32_bf16 v[228:231], v[172:175], v[68:71], v[56:59]
	v_mfma_f32_16x16x32_bf16 v[232:235], v[172:175], v[88:91], v[48:51]
	v_mfma_f32_16x16x32_bf16 v[236:239], v[172:175], v[192:195], v[40:43]
	v_mfma_f32_16x16x32_bf16 v[160:163], v[172:175], v[200:203], v[32:35]
	s_setprio 0
	s_setprio 1
	v_mfma_f32_16x16x32_bf16 v[28:31], v[104:107], v[64:67], v[28:31]
	v_mfma_f32_16x16x32_bf16 v[20:23], v[104:107], v[80:83], v[20:23]
	v_mfma_f32_16x16x32_bf16 v[12:15], v[104:107], v[92:95], v[12:15]
	v_mfma_f32_16x16x32_bf16 v[4:7], v[104:107], v[196:199], v[4:7]
	v_mfma_f32_16x16x32_bf16 v[28:31], v[120:123], v[68:71], v[28:31]
	v_mfma_f32_16x16x32_bf16 v[24:27], v[112:115], v[64:67], v[24:27]
	v_mfma_f32_16x16x32_bf16 v[20:23], v[120:123], v[88:91], v[20:23]
	v_mfma_f32_16x16x32_bf16 v[16:19], v[112:115], v[80:83], v[16:19]
	v_mfma_f32_16x16x32_bf16 v[12:15], v[120:123], v[192:195], v[12:15]
	v_mfma_f32_16x16x32_bf16 v[8:11], v[112:115], v[92:95], v[8:11]
	v_mfma_f32_16x16x32_bf16 v[4:7], v[120:123], v[200:203], v[4:7]
	v_mfma_f32_16x16x32_bf16 v[0:3], v[112:115], v[196:199], v[0:3]
	v_mfma_f32_16x16x32_bf16 v[164:167], v[220:223], v[68:71], v[24:27]
	v_mfma_f32_16x16x32_bf16 v[168:171], v[220:223], v[88:91], v[16:19]
	v_mfma_f32_16x16x32_bf16 v[172:175], v[220:223], v[192:195], v[8:11]
	v_mfma_f32_16x16x32_bf16 v[192:195], v[220:223], v[200:203], v[0:3]
	s_setprio 0
	s_barrier
	s_nop 1
	ds_read_b128 v[0:3], v156
	ds_read_b128 v[8:11], v156 offset:256
	ds_read_b128 v[16:19], v157
	ds_read_b128 v[24:27], v157 offset:256
	ds_read_b128 v[32:35], v149 offset:32768
	ds_read_b128 v[40:43], v149 offset:33792
	ds_read_b128 v[48:51], v149 offset:34816
	ds_read_b128 v[56:59], v149 offset:35840
	ds_read_b128 v[60:63], v149 offset:36864
	ds_read_b128 v[68:71], v149 offset:37888
	ds_read_b128 v[196:199], v149 offset:38912
	ds_read_b128 v[200:203], v149 offset:39936
	s_waitcnt vmcnt(2)
	s_barrier
; #define LDA(dst, b, h) for (int m = 0; m < 4; ++m) { \
;     dst[m][0] = *reinterpret_cast<const bf16x8*>((char*)SA(b, h) + aoff0 + m * 2048); \
;     dst[m][1] = *reinterpret_cast<const bf16x8*>((char*)SA(b, h) + aoff1 + m * 2048); }
; #define LDB(dst, b, h) for (int n = 0; n < 2; ++n) { \
;     dst[n][0] = *reinterpret_cast<const bf16x8*>((char*)SB(b, h) + boff0 + n * 256); \
;     dst[n][1] = *reinterpret_cast<const bf16x8*>((char*)SB(b, h) + boff1 + n * 256); }
; #define MMA(ai, bj, At, Btf) do { __builtin_amdgcn_s_setprio(1); \
;     for (int m = 0; m < 4; ++m) for (int n = 0; n < 2; ++n) for (int k = 0; k < 2; ++k) \
;       acc[ai][bj][m][n] = __builtin_amdgcn_mfma_f32_16x16x32_bf16(Btf[n][k], At[m][k], acc[ai][bj][m][n], 0, 0, 0); \
;     __builtin_amdgcn_s_setprio(0); } while (0)
; #define WAIT_V(n) asm volatile("s_waitcnt vmcnt(" #n ")" ::: "memory")
; #define WAIT_L(n) asm volatile("s_waitcnt lgkmcnt(" #n ")" ::: "memory")
; #define BAR __builtin_amdgcn_s_barrier()
; template <int EPI> ...
;     ...
;   { LDB(B0, 1, 0); LDA(At, 1, 0); WAIT_V(2); BAR; WAIT_L(0); MMA(0, 0, At, B0); BAR;
;     LDB(B1, 1, 1); WAIT_V(0); BAR; WAIT_L(0); MMA(0, 1, At, B1); BAR;
;     LDA(At, 1, 1); BAR; WAIT_L(0); MMA(1, 0, At, B0); MMA(1, 1, At, B1); BAR; }
;   if (wr == 0) BAR;
	s_waitcnt lgkmcnt(0)
	s_setprio 1
	s_waitcnt lgkmcnt(0)
	v_mfma_f32_16x16x32_bf16 v[64:67], v[0:3], v[32:35], v[124:127]
	v_mfma_f32_16x16x32_bf16 v[120:123], v[16:19], v[40:43], v[64:67]
	v_mfma_f32_16x16x32_bf16 v[64:67], v[8:11], v[32:35], v[208:211]
	v_mfma_f32_16x16x32_bf16 v[124:127], v[24:27], v[40:43], v[64:67]
	v_mfma_f32_16x16x32_bf16 v[64:67], v[0:3], v[48:51], v[116:119]
	v_mfma_f32_16x16x32_bf16 v[112:115], v[16:19], v[56:59], v[64:67]
	v_mfma_f32_16x16x32_bf16 v[64:67], v[8:11], v[48:51], v[212:215]
	v_mfma_f32_16x16x32_bf16 v[116:119], v[24:27], v[56:59], v[64:67]
	v_mfma_f32_16x16x32_bf16 v[64:67], v[0:3], v[60:63], v[108:111]
	v_mfma_f32_16x16x32_bf16 v[104:107], v[16:19], v[68:71], v[64:67]
	v_mfma_f32_16x16x32_bf16 v[64:67], v[8:11], v[60:63], v[216:219]
	v_mfma_f32_16x16x32_bf16 v[108:111], v[24:27], v[68:71], v[64:67]
	v_mfma_f32_16x16x32_bf16 v[64:67], v[0:3], v[196:199], v[100:103]
	v_mfma_f32_16x16x32_bf16 v[88:91], v[16:19], v[200:203], v[64:67]
	v_mfma_f32_16x16x32_bf16 v[64:67], v[8:11], v[196:199], v[96:99]
	v_mfma_f32_16x16x32_bf16 v[92:95], v[24:27], v[200:203], v[64:67]
	s_setprio 0
	s_barrier
	ds_read_b128 v[208:211], v158
	ds_read_b128 v[212:215], v158 offset:256
	ds_read_b128 v[216:219], v159
	ds_read_b128 v[220:223], v159 offset:256
	s_waitcnt vmcnt(0)
	s_barrier
	s_waitcnt lgkmcnt(0)
	s_setprio 1
	s_waitcnt lgkmcnt(0)
	v_mfma_f32_16x16x32_bf16 v[64:67], v[208:211], v[32:35], v[224:227]
	v_mfma_f32_16x16x32_bf16 v[32:35], v[212:215], v[32:35], v[176:179]
	v_mfma_f32_16x16x32_bf16 v[100:103], v[220:223], v[40:43], v[32:35]
	v_mfma_f32_16x16x32_bf16 v[32:35], v[208:211], v[48:51], v[84:87]
	v_mfma_f32_16x16x32_bf16 v[80:83], v[216:219], v[56:59], v[32:35]
	v_mfma_f32_16x16x32_bf16 v[32:35], v[212:215], v[48:51], v[180:183]
	v_mfma_f32_16x16x32_bf16 v[84:87], v[220:223], v[56:59], v[32:35]
	v_mfma_f32_16x16x32_bf16 v[32:35], v[208:211], v[60:63], v[76:79]
	v_mfma_f32_16x16x32_bf16 v[96:99], v[216:219], v[40:43], v[64:67]
	v_mfma_f32_16x16x32_bf16 v[64:67], v[216:219], v[68:71], v[32:35]
	v_mfma_f32_16x16x32_bf16 v[32:35], v[212:215], v[60:63], v[72:75]
	v_mfma_f32_16x16x32_bf16 v[68:71], v[220:223], v[68:71], v[32:35]
	v_mfma_f32_16x16x32_bf16 v[32:35], v[208:211], v[196:199], v[184:187]
	v_mfma_f32_16x16x32_bf16 v[56:59], v[216:219], v[200:203], v[32:35]
	v_mfma_f32_16x16x32_bf16 v[32:35], v[212:215], v[196:199], v[188:191]
	v_mfma_f32_16x16x32_bf16 v[60:63], v[220:223], v[200:203], v[32:35]
	s_setprio 0
	s_barrier
	ds_read_b128 v[176:179], v149 offset:49152
	ds_read_b128 v[180:183], v149 offset:50176
	ds_read_b128 v[184:187], v149 offset:51200
	ds_read_b128 v[188:191], v149 offset:52224
	ds_read_b128 v[196:199], v149 offset:53248
	ds_read_b128 v[200:203], v149 offset:54272
	ds_read_b128 v[224:227], v149 offset:55296
	ds_read_b128 v[240:243], v149 offset:56320
	s_barrier
	s_waitcnt lgkmcnt(0)
	s_setprio 1
	s_waitcnt lgkmcnt(0)
	v_mfma_f32_16x16x32_bf16 v[32:35], v[0:3], v[176:179], v[204:207]
	v_mfma_f32_16x16x32_bf16 v[72:75], v[16:19], v[180:183], v[32:35]
	v_mfma_f32_16x16x32_bf16 v[32:35], v[8:11], v[176:179], v[228:231]
	v_mfma_f32_16x16x32_bf16 v[76:79], v[24:27], v[180:183], v[32:35]
	v_mfma_f32_16x16x32_bf16 v[32:35], v[0:3], v[184:187], v[52:55]
	v_mfma_f32_16x16x32_bf16 v[48:51], v[16:19], v[188:191], v[32:35]
	v_mfma_f32_16x16x32_bf16 v[32:35], v[8:11], v[184:187], v[232:235]
	v_mfma_f32_16x16x32_bf16 v[52:55], v[24:27], v[188:191], v[32:35]
	v_mfma_f32_16x16x32_bf16 v[32:35], v[0:3], v[196:199], v[44:47]
	v_mfma_f32_16x16x32_bf16 v[40:43], v[16:19], v[200:203], v[32:35]
	v_mfma_f32_16x16x32_bf16 v[32:35], v[8:11], v[196:199], v[236:239]
	v_mfma_f32_16x16x32_bf16 v[0:3], v[0:3], v[224:227], v[36:39]
	v_mfma_f32_16x16x32_bf16 v[44:47], v[24:27], v[200:203], v[32:35]
	v_mfma_f32_16x16x32_bf16 v[32:35], v[16:19], v[240:243], v[0:3]
	v_mfma_f32_16x16x32_bf16 v[0:3], v[8:11], v[224:227], v[160:163]
	v_mfma_f32_16x16x32_bf16 v[36:39], v[24:27], v[240:243], v[0:3]
	s_setprio 0
	s_setprio 1
	v_mfma_f32_16x16x32_bf16 v[0:3], v[208:211], v[176:179], v[28:31]
	v_mfma_f32_16x16x32_bf16 v[24:27], v[216:219], v[180:183], v[0:3]
	v_mfma_f32_16x16x32_bf16 v[0:3], v[212:215], v[176:179], v[164:167]
	v_mfma_f32_16x16x32_bf16 v[28:31], v[220:223], v[180:183], v[0:3]
	v_mfma_f32_16x16x32_bf16 v[0:3], v[208:211], v[184:187], v[20:23]
	v_mfma_f32_16x16x32_bf16 v[16:19], v[216:219], v[188:191], v[0:3]
	v_mfma_f32_16x16x32_bf16 v[0:3], v[212:215], v[184:187], v[168:171]
	v_mfma_f32_16x16x32_bf16 v[20:23], v[220:223], v[188:191], v[0:3]
	v_mfma_f32_16x16x32_bf16 v[0:3], v[208:211], v[196:199], v[12:15]
	v_mfma_f32_16x16x32_bf16 v[8:11], v[216:219], v[200:203], v[0:3]
	v_mfma_f32_16x16x32_bf16 v[0:3], v[212:215], v[196:199], v[172:175]
	v_mfma_f32_16x16x32_bf16 v[12:15], v[220:223], v[200:203], v[0:3]
	v_mfma_f32_16x16x32_bf16 v[0:3], v[208:211], v[224:227], v[4:7]
	v_mfma_f32_16x16x32_bf16 v[4:7], v[212:215], v[224:227], v[192:195]
	v_mfma_f32_16x16x32_bf16 v[0:3], v[216:219], v[240:243], v[0:3]
	v_mfma_f32_16x16x32_bf16 v[4:7], v[220:223], v[240:243], v[4:7]
	s_setprio 0
	s_barrier
	s_and_saveexec_b64 s[60:61], s[2:3]
	s_cbranch_execz .LBB0_1146
	s_barrier
	s_branch .LBB0_1146
